# GEMM compute blocks: the two MFMAs of each accumulator (k=0, k=1) issued back to back (order n, m, k) instead of 8 apart
# speedup vs baseline: 1.0154x; 1.0154x over previous
; #define PG8_STAGE(bufoff, gbase, voff) do { _Pragma("unroll") for (int _i = 0; _i < 2; ++_i) \
;         __builtin_amdgcn_global_load_lds((const unsigned*)((const char*)(gbase) + (voff)[_i]), (PG8_LAS unsigned*)(lds + (bufoff) + ldsw + _i * 8192), 16, 0, 0); } while (0)
; #define PG8_LDA(dst, b, h) do { _Pragma("unroll") for (int m = 0; m < 4; ++m) _Pragma("unroll") for (int k = 0; k < 2; ++k) dst[m][k] = *(const PG8_LAS bf16x8*)(lds + PG8_SA(b, h) + aoffk[k] + m * 2048); } while (0)
; #define PG8_LDB(dst, b, h) do { _Pragma("unroll") for (int n = 0; n < 2; ++n) _Pragma("unroll") for (int k = 0; k < 2; ++k) dst[n][k] = *(const PG8_LAS bf16x8*)(lds + PG8_SB(b, h) + boffk[k] + n * 2048); } while (0)
; #define PG8_MMA(ai, bj, At, Bt) do { __builtin_amdgcn_s_setprio(1); _Pragma("unroll") for (int m = 0; m < 4; ++m) _Pragma("unroll") for (int n = 0; n < 2; ++n) _Pragma("unroll") for (int k = 0; k < 2; ++k) \
;         acc[ai][bj][m][n] = __builtin_amdgcn_mfma_f32_16x16x32_bf16(Bt[n][k], At[m][k], acc[ai][bj][m][n], 0, 0, 0); __builtin_amdgcn_s_setprio(0); } while (0)
; #define PG8_WAIT_V(n) asm volatile("s_waitcnt vmcnt(" #n ")" ::: "memory")
; #define PG8_WAIT_L(n) asm volatile("s_waitcnt lgkmcnt(" #n ")" ::: "memory")
; #define PG8_BAR __builtin_amdgcn_s_barrier()
; #define PG8_SCHED __builtin_amdgcn_sched_barrier(0)
; template <class Epi, class Sched, bool ALIGN_EPI = false, bool SP2 = false>
; __device__ __forceinline__ void gemm_phase(PG8_LAS unsigned char* lds, const Gemm g, const Sched& S, const Epi& E) {
;     ...
;             PG8_LDB(B0, 0, 0); PG8_LDB(B1, 0, 1); PG8_SCHED; PG8_LDA(At, 0, 0); PG8_STAGE(PG8_SA(1, 1), a1 + hstepA, voffA);
;             PG8_WAIT_V(8); PG8_WAIT_L(0); PG8_BAR; PG8_MMA(0, 0, At, B0); PG8_MMA(0, 1, At, B1); PG8_BAR; PG8_SCHED;
;             PG8_LDA(At, 0, 1); PG8_STAGE(PG8_SB(0, 0), b2, voffB); PG8_STAGE(PG8_SB(0, 1), b2 + hstepB, voffB); PG8_STAGE(PG8_SA(0, 0), a2, voffA);
.Lgemm_first_0:
	s_add_u32 s22, s20, 0xfff80080
	s_addc_u32 s23, s21, -1
	s_add_i32 s47, 0, 0x10000
	s_cmp_eq_u32 s46, 28
	s_cselect_b32 s25, s11, s23
	s_cselect_b32 s24, s33, s22
	s_cselect_b32 s23, s9, s45
	s_cselect_b32 s22, s43, s44
	s_add_i32 s50, 0, 0x14000
	v_add_u32_e32 v142, s47, v147
	v_add_u32_e32 v156, s47, v148
	v_add_u32_e32 v168, s50, v147
	v_add_u32_e32 v176, s50, v148
	ds_read_b128 v[142:145], v142
	ds_read_b128 v[156:159], v156
	ds_read_b128 v[160:163], v150
	ds_read_b128 v[164:167], v151
	ds_read_b128 v[172:175], v168
	ds_read_b128 v[176:179], v176
	ds_read_b128 v[180:183], v152
	ds_read_b128 v[184:187], v153
	v_lshl_add_u64 v[212:213], s[20:21], 0, v[138:139]
	s_add_i32 m0, s36, 0xc000
	ds_read_b128 v[188:191], v154
	ds_read_b128 v[192:195], v154 offset:1024
	ds_read_b128 v[196:199], v154 offset:2048
	ds_read_b128 v[200:203], v154 offset:3072
	ds_read_b128 v[204:207], v154 offset:4096
	ds_read_b128 v[208:211], v154 offset:5120
	ds_read_b128 v[226:229], v154 offset:6144
	ds_read_b128 v[230:233], v154 offset:7168
	global_load_lds_dwordx4 v[212:213], off
	v_lshl_add_u64 v[212:213], s[20:21], 0, v[140:141]
	s_add_i32 m0, s36, 0xe000
	s_nop 0
	global_load_lds_dwordx4 v[212:213], off
	s_waitcnt vmcnt(8)
	s_waitcnt lgkmcnt(0)
	s_barrier
	v_mfma_f32_16x16x32_bf16 v[128:131], v[142:145], v[188:191], 0
	v_mfma_f32_16x16x32_bf16 v[128:131], v[156:159], v[192:195], v[128:131]
	v_mfma_f32_16x16x32_bf16 v[112:115], v[142:145], v[196:199], 0
	v_mfma_f32_16x16x32_bf16 v[112:115], v[156:159], v[200:203], v[112:115]
	v_mfma_f32_16x16x32_bf16 v[96:99], v[142:145], v[204:207], 0
	v_mfma_f32_16x16x32_bf16 v[96:99], v[156:159], v[208:211], v[96:99]
	v_mfma_f32_16x16x32_bf16 v[80:83], v[142:145], v[226:229], 0
	v_mfma_f32_16x16x32_bf16 v[80:83], v[156:159], v[230:233], v[80:83]
	v_mfma_f32_16x16x32_bf16 v[120:123], v[160:163], v[188:191], 0
	v_mfma_f32_16x16x32_bf16 v[120:123], v[164:167], v[192:195], v[120:123]
	v_mfma_f32_16x16x32_bf16 v[104:107], v[160:163], v[196:199], 0
	v_mfma_f32_16x16x32_bf16 v[104:107], v[164:167], v[200:203], v[104:107]
	v_mfma_f32_16x16x32_bf16 v[88:91], v[160:163], v[204:207], 0
	v_mfma_f32_16x16x32_bf16 v[88:91], v[164:167], v[208:211], v[88:91]
	v_mfma_f32_16x16x32_bf16 v[72:75], v[160:163], v[226:229], 0
	v_mfma_f32_16x16x32_bf16 v[72:75], v[164:167], v[230:233], v[72:75]
	v_mfma_f32_16x16x32_bf16 v[124:127], v[172:175], v[188:191], 0
	v_mfma_f32_16x16x32_bf16 v[124:127], v[176:179], v[192:195], v[124:127]
	v_mfma_f32_16x16x32_bf16 v[108:111], v[172:175], v[196:199], 0
	v_mfma_f32_16x16x32_bf16 v[108:111], v[176:179], v[200:203], v[108:111]
	v_mfma_f32_16x16x32_bf16 v[92:95], v[172:175], v[204:207], 0
	v_mfma_f32_16x16x32_bf16 v[92:95], v[176:179], v[208:211], v[92:95]
	v_mfma_f32_16x16x32_bf16 v[76:79], v[172:175], v[226:229], 0
	v_mfma_f32_16x16x32_bf16 v[76:79], v[176:179], v[230:233], v[76:79]
	v_mfma_f32_16x16x32_bf16 v[116:119], v[180:183], v[188:191], 0
	v_mfma_f32_16x16x32_bf16 v[116:119], v[184:187], v[192:195], v[116:119]
	v_mfma_f32_16x16x32_bf16 v[100:103], v[180:183], v[196:199], 0
	v_mfma_f32_16x16x32_bf16 v[100:103], v[184:187], v[200:203], v[100:103]
	v_mfma_f32_16x16x32_bf16 v[84:87], v[180:183], v[204:207], 0
	v_mfma_f32_16x16x32_bf16 v[84:87], v[184:187], v[208:211], v[84:87]
	v_mfma_f32_16x16x32_bf16 v[68:71], v[180:183], v[226:229], 0
	v_mfma_f32_16x16x32_bf16 v[68:71], v[184:187], v[230:233], v[68:71]
	s_barrier
	s_add_i32 s47, s47, s34
	v_lshl_add_u64 v[212:213], s[22:23], 0, v[2:3]
	s_mov_b32 m0, s47
	ds_read_b128 v[188:191], v154 offset:16384
	ds_read_b128 v[192:195], v154 offset:17408
	ds_read_b128 v[196:199], v154 offset:18432
	ds_read_b128 v[200:203], v154 offset:19456
	ds_read_b128 v[204:207], v154 offset:20480
	ds_read_b128 v[208:211], v154 offset:21504
	ds_read_b128 v[226:229], v154 offset:22528
	ds_read_b128 v[230:233], v154 offset:23552
	global_load_lds_dwordx4 v[212:213], off
	s_add_i32 m0, s47, 0x2000
	s_add_u32 s48, s22, 0x80000
	v_lshl_add_u64 v[234:235], s[22:23], 0, v[132:133]
	s_addc_u32 s49, s23, 0
	s_add_i32 s47, s50, s34
	global_load_lds_dwordx4 v[234:235], off
	v_lshl_add_u64 v[236:237], s[48:49], 0, v[2:3]
	s_mov_b32 m0, s47
	v_lshl_add_u64 v[238:239], s[24:25], 0, v[134:135]
	global_load_lds_dwordx4 v[236:237], off
	v_lshl_add_u64 v[236:237], s[48:49], 0, v[132:133]
	s_add_i32 m0, s47, 0x2000
	s_nop 0
	global_load_lds_dwordx4 v[236:237], off
	v_lshl_add_u64 v[236:237], s[24:25], 0, v[136:137]
	s_mov_b32 m0, s36
	s_nop 0
	global_load_lds_dwordx4 v[236:237], off
	s_mov_b32 m0, s37
	s_nop 0
	global_load_lds_dwordx4 v[238:239], off
	s_waitcnt vmcnt(8)
	s_waitcnt lgkmcnt(0)
	s_barrier
; #define PG8_STAGE(bufoff, gbase, voff) do { _Pragma("unroll") for (int _i = 0; _i < 2; ++_i) \
;         __builtin_amdgcn_global_load_lds((const unsigned*)((const char*)(gbase) + (voff)[_i]), (PG8_LAS unsigned*)(lds + (bufoff) + ldsw + _i * 8192), 16, 0, 0); } while (0)
; #define PG8_LDA(dst, b, h) do { _Pragma("unroll") for (int m = 0; m < 4; ++m) _Pragma("unroll") for (int k = 0; k < 2; ++k) dst[m][k] = *(const PG8_LAS bf16x8*)(lds + PG8_SA(b, h) + aoffk[k] + m * 2048); } while (0)
; #define PG8_LDB(dst, b, h) do { _Pragma("unroll") for (int n = 0; n < 2; ++n) _Pragma("unroll") for (int k = 0; k < 2; ++k) dst[n][k] = *(const PG8_LAS bf16x8*)(lds + PG8_SB(b, h) + boffk[k] + n * 2048); } while (0)
; #define PG8_MMA(ai, bj, At, Bt) do { __builtin_amdgcn_s_setprio(1); _Pragma("unroll") for (int m = 0; m < 4; ++m) _Pragma("unroll") for (int n = 0; n < 2; ++n) _Pragma("unroll") for (int k = 0; k < 2; ++k) \
;         acc[ai][bj][m][n] = __builtin_amdgcn_mfma_f32_16x16x32_bf16(Bt[n][k], At[m][k], acc[ai][bj][m][n], 0, 0, 0); __builtin_amdgcn_s_setprio(0); } while (0)
; #define PG8_WAIT_V(n) asm volatile("s_waitcnt vmcnt(" #n ")" ::: "memory")
; #define PG8_WAIT_L(n) asm volatile("s_waitcnt lgkmcnt(" #n ")" ::: "memory")
; #define PG8_BAR __builtin_amdgcn_s_barrier()
; #define PG8_SCHED __builtin_amdgcn_sched_barrier(0)
; template <class Epi, class Sched, bool ALIGN_EPI = false, bool SP2 = false>
; __device__ __forceinline__ void gemm_phase(PG8_LAS unsigned char* lds, const Gemm g, const Sched& S, const Epi& E) {
;     ...
;             PG8_WAIT_V(8); PG8_WAIT_L(0); PG8_BAR; PG8_MMA(1, 0, At, B0); PG8_MMA(1, 1, At, B1); PG8_BAR; PG8_SCHED;
;             PG8_LDB(B0, 1, 0); PG8_LDB(B1, 1, 1); PG8_SCHED; PG8_LDA(At, 1, 0); PG8_STAGE(PG8_SA(0, 1), a2 + hstepA, voffA);
;             PG8_WAIT_V(8); PG8_WAIT_L(0); PG8_BAR; PG8_MMA(0, 0, At, B0); PG8_MMA(0, 1, At, B1); PG8_BAR; PG8_SCHED;
	v_mfma_f32_16x16x32_bf16 v[64:67], v[142:145], v[188:191], 0
	v_mfma_f32_16x16x32_bf16 v[64:67], v[156:159], v[192:195], v[64:67]
	v_mfma_f32_16x16x32_bf16 v[48:51], v[142:145], v[196:199], 0
	v_mfma_f32_16x16x32_bf16 v[48:51], v[156:159], v[200:203], v[48:51]
	v_mfma_f32_16x16x32_bf16 v[32:35], v[142:145], v[204:207], 0
	v_mfma_f32_16x16x32_bf16 v[32:35], v[156:159], v[208:211], v[32:35]
	v_mfma_f32_16x16x32_bf16 v[16:19], v[142:145], v[226:229], 0
	v_mfma_f32_16x16x32_bf16 v[16:19], v[156:159], v[230:233], v[16:19]
	v_mfma_f32_16x16x32_bf16 v[56:59], v[160:163], v[188:191], 0
	v_mfma_f32_16x16x32_bf16 v[56:59], v[164:167], v[192:195], v[56:59]
	v_mfma_f32_16x16x32_bf16 v[40:43], v[160:163], v[196:199], 0
	v_mfma_f32_16x16x32_bf16 v[40:43], v[164:167], v[200:203], v[40:43]
	v_mfma_f32_16x16x32_bf16 v[24:27], v[160:163], v[204:207], 0
	v_mfma_f32_16x16x32_bf16 v[24:27], v[164:167], v[208:211], v[24:27]
	v_mfma_f32_16x16x32_bf16 v[8:11], v[160:163], v[226:229], 0
	v_mfma_f32_16x16x32_bf16 v[8:11], v[164:167], v[230:233], v[8:11]
	v_mfma_f32_16x16x32_bf16 v[60:63], v[172:175], v[188:191], 0
	v_mfma_f32_16x16x32_bf16 v[60:63], v[176:179], v[192:195], v[60:63]
	v_mfma_f32_16x16x32_bf16 v[44:47], v[172:175], v[196:199], 0
	v_mfma_f32_16x16x32_bf16 v[44:47], v[176:179], v[200:203], v[44:47]
	v_mfma_f32_16x16x32_bf16 v[28:31], v[172:175], v[204:207], 0
	v_mfma_f32_16x16x32_bf16 v[28:31], v[176:179], v[208:211], v[28:31]
	v_mfma_f32_16x16x32_bf16 v[12:15], v[172:175], v[226:229], 0
	v_mfma_f32_16x16x32_bf16 v[12:15], v[176:179], v[230:233], v[12:15]
	v_mfma_f32_16x16x32_bf16 v[52:55], v[180:183], v[188:191], 0
	v_mfma_f32_16x16x32_bf16 v[52:55], v[184:187], v[192:195], v[52:55]
	v_mfma_f32_16x16x32_bf16 v[36:39], v[180:183], v[196:199], 0
	v_mfma_f32_16x16x32_bf16 v[36:39], v[184:187], v[200:203], v[36:39]
	v_mfma_f32_16x16x32_bf16 v[20:23], v[180:183], v[204:207], 0
	v_mfma_f32_16x16x32_bf16 v[20:23], v[184:187], v[208:211], v[20:23]
	v_mfma_f32_16x16x32_bf16 v[4:7], v[180:183], v[226:229], 0
	v_mfma_f32_16x16x32_bf16 v[4:7], v[184:187], v[230:233], v[4:7]
	s_barrier
	s_add_i32 s47, 0, 0x18000
	s_add_i32 s48, 0, 0x1c000
	v_add_u32_e32 v142, s47, v147
	v_add_u32_e32 v156, s47, v148
	v_add_u32_e32 v164, s52, v148
	v_add_u32_e32 v168, s48, v147
	v_add_u32_e32 v176, s48, v148
	ds_read_b128 v[142:145], v142
	ds_read_b128 v[156:159], v156
	ds_read_b128 v[160:163], v155
	ds_read_b128 v[164:167], v164
	ds_read_b128 v[172:175], v168
	ds_read_b128 v[176:179], v176
	v_add_u32_e32 v168, s53, v147
	v_add_u32_e32 v184, s53, v148
	ds_read_b128 v[180:183], v168
	ds_read_b128 v[184:187], v184
	s_add_u32 s24, s24, 0x80000
	s_addc_u32 s25, s25, 0
	s_mov_b32 m0, s38
	v_lshl_add_u64 v[240:241], s[24:25], 0, v[136:137]
	ds_read_b128 v[188:191], v154 offset:32768
	ds_read_b128 v[192:195], v154 offset:33792
	ds_read_b128 v[196:199], v154 offset:34816
	ds_read_b128 v[200:203], v154 offset:35840
	ds_read_b128 v[204:207], v154 offset:36864
	ds_read_b128 v[208:211], v154 offset:37888
	ds_read_b128 v[226:229], v154 offset:38912
	ds_read_b128 v[230:233], v154 offset:39936
	global_load_lds_dwordx4 v[240:241], off
	v_lshl_add_u64 v[240:241], s[24:25], 0, v[134:135]
	s_mov_b32 m0, s39
	s_nop 0
	global_load_lds_dwordx4 v[240:241], off
	s_waitcnt vmcnt(8)
	s_waitcnt lgkmcnt(0)
	s_barrier
	v_mfma_f32_16x16x32_bf16 v[128:131], v[142:145], v[188:191], v[128:131]
	v_mfma_f32_16x16x32_bf16 v[128:131], v[156:159], v[192:195], v[128:131]
	v_mfma_f32_16x16x32_bf16 v[112:115], v[142:145], v[196:199], v[112:115]
	v_mfma_f32_16x16x32_bf16 v[112:115], v[156:159], v[200:203], v[112:115]
	v_mfma_f32_16x16x32_bf16 v[96:99], v[142:145], v[204:207], v[96:99]
	v_mfma_f32_16x16x32_bf16 v[96:99], v[156:159], v[208:211], v[96:99]
	v_mfma_f32_16x16x32_bf16 v[80:83], v[142:145], v[226:229], v[80:83]
	v_mfma_f32_16x16x32_bf16 v[80:83], v[156:159], v[230:233], v[80:83]
	v_mfma_f32_16x16x32_bf16 v[120:123], v[160:163], v[188:191], v[120:123]
	v_mfma_f32_16x16x32_bf16 v[120:123], v[164:167], v[192:195], v[120:123]
	v_mfma_f32_16x16x32_bf16 v[104:107], v[160:163], v[196:199], v[104:107]
	v_mfma_f32_16x16x32_bf16 v[104:107], v[164:167], v[200:203], v[104:107]
	v_mfma_f32_16x16x32_bf16 v[88:91], v[160:163], v[204:207], v[88:91]
	v_mfma_f32_16x16x32_bf16 v[88:91], v[164:167], v[208:211], v[88:91]
	v_mfma_f32_16x16x32_bf16 v[72:75], v[160:163], v[226:229], v[72:75]
	v_mfma_f32_16x16x32_bf16 v[72:75], v[164:167], v[230:233], v[72:75]
	v_mfma_f32_16x16x32_bf16 v[124:127], v[172:175], v[188:191], v[124:127]
	v_mfma_f32_16x16x32_bf16 v[124:127], v[176:179], v[192:195], v[124:127]
	v_mfma_f32_16x16x32_bf16 v[108:111], v[172:175], v[196:199], v[108:111]
	v_mfma_f32_16x16x32_bf16 v[108:111], v[176:179], v[200:203], v[108:111]
	v_mfma_f32_16x16x32_bf16 v[92:95], v[172:175], v[204:207], v[92:95]
	v_mfma_f32_16x16x32_bf16 v[92:95], v[176:179], v[208:211], v[92:95]
	v_mfma_f32_16x16x32_bf16 v[76:79], v[172:175], v[226:229], v[76:79]
	v_mfma_f32_16x16x32_bf16 v[76:79], v[176:179], v[230:233], v[76:79]
	v_mfma_f32_16x16x32_bf16 v[116:119], v[180:183], v[188:191], v[116:119]
	v_mfma_f32_16x16x32_bf16 v[116:119], v[184:187], v[192:195], v[116:119]
	v_mfma_f32_16x16x32_bf16 v[100:103], v[180:183], v[196:199], v[100:103]
	v_mfma_f32_16x16x32_bf16 v[100:103], v[184:187], v[200:203], v[100:103]
	v_mfma_f32_16x16x32_bf16 v[84:87], v[180:183], v[204:207], v[84:87]
	v_mfma_f32_16x16x32_bf16 v[84:87], v[184:187], v[208:211], v[84:87]
	v_mfma_f32_16x16x32_bf16 v[68:71], v[180:183], v[226:229], v[68:71]
	v_mfma_f32_16x16x32_bf16 v[68:71], v[184:187], v[230:233], v[68:71]
	s_barrier
; #define PG8_STAGE(bufoff, gbase, voff) do { _Pragma("unroll") for (int _i = 0; _i < 2; ++_i) \
;         __builtin_amdgcn_global_load_lds((const unsigned*)((const char*)(gbase) + (voff)[_i]), (PG8_LAS unsigned*)(lds + (bufoff) + ldsw + _i * 8192), 16, 0, 0); } while (0)
; #define PG8_LDA(dst, b, h) do { _Pragma("unroll") for (int m = 0; m < 4; ++m) _Pragma("unroll") for (int k = 0; k < 2; ++k) dst[m][k] = *(const PG8_LAS bf16x8*)(lds + PG8_SA(b, h) + aoffk[k] + m * 2048); } while (0)
; #define PG8_MMA(ai, bj, At, Bt) do { __builtin_amdgcn_s_setprio(1); _Pragma("unroll") for (int m = 0; m < 4; ++m) _Pragma("unroll") for (int n = 0; n < 2; ++n) _Pragma("unroll") for (int k = 0; k < 2; ++k) \
;         acc[ai][bj][m][n] = __builtin_amdgcn_mfma_f32_16x16x32_bf16(Bt[n][k], At[m][k], acc[ai][bj][m][n], 0, 0, 0); __builtin_amdgcn_s_setprio(0); } while (0)
; #define PG8_WAIT_V(n) asm volatile("s_waitcnt vmcnt(" #n ")" ::: "memory")
; #define PG8_WAIT_L(n) asm volatile("s_waitcnt lgkmcnt(" #n ")" ::: "memory")
; #define PG8_BAR __builtin_amdgcn_s_barrier()
; #define PG8_SCHED __builtin_amdgcn_sched_barrier(0)
; template <class Epi, class Sched, bool ALIGN_EPI = false, bool SP2 = false>
; __device__ __forceinline__ void gemm_phase(PG8_LAS unsigned char* lds, const Gemm g, const Sched& S, const Epi& E) {
;     ...
;         for (int t = 0; t < nt; t += 2) {
;             const bool last = (t == nt - 2);
;             const char* a1 = cA + (size_t)(t + 1) * kstep;
;             const char* a2 = last ? nA : cA + (size_t)(t + 2) * kstep; const char* b2 = last ? nB : cB + (size_t)(t + 2) * kstep;
;             const char* a3 = a2 + kstep; const char* b3 = b2 + kstep;
;             if (last && has_next) S.a_ready(nxt);
;     ...
;             PG8_LDA(At, 1, 1); PG8_STAGE(PG8_SB(1, 0), b3, voffB); PG8_STAGE(PG8_SB(1, 1), b3 + hstepB, voffB); PG8_STAGE(PG8_SA(1, 0), a3, voffA);
;             PG8_WAIT_V(8); PG8_WAIT_L(0); PG8_BAR; PG8_MMA(1, 0, At, B0); PG8_MMA(1, 1, At, B1); PG8_BAR; PG8_SCHED;
	s_add_i32 s24, s47, s34
	v_lshl_add_u64 v[212:213], v[212:213], 0, s[56:57]
	s_mov_b32 m0, s24
	ds_read_b128 v[188:191], v154 offset:49152
	ds_read_b128 v[192:195], v154 offset:50176
	ds_read_b128 v[196:199], v154 offset:51200
	ds_read_b128 v[200:203], v154 offset:52224
	ds_read_b128 v[204:207], v154 offset:53248
	ds_read_b128 v[208:211], v154 offset:54272
	ds_read_b128 v[226:229], v154 offset:55296
	ds_read_b128 v[230:233], v154 offset:56320
	global_load_lds_dwordx4 v[212:213], off
	s_add_i32 m0, s24, 0x2000
	s_add_u32 s22, s22, 0x80080
	v_lshl_add_u64 v[212:213], v[234:235], 0, s[56:57]
	s_addc_u32 s23, s23, 0
	s_add_i32 s24, s48, s34
	global_load_lds_dwordx4 v[212:213], off
	v_lshl_add_u64 v[212:213], s[22:23], 0, v[2:3]
	s_mov_b32 m0, s24
	s_nop 0
	global_load_lds_dwordx4 v[212:213], off
	v_lshl_add_u64 v[212:213], s[22:23], 0, v[132:133]
	s_add_i32 m0, s24, 0x2000
	s_nop 0
	global_load_lds_dwordx4 v[212:213], off
	v_lshl_add_u64 v[212:213], v[236:237], 0, s[56:57]
	s_mov_b32 m0, s40
	s_nop 0
	global_load_lds_dwordx4 v[212:213], off
	v_lshl_add_u64 v[212:213], v[238:239], 0, s[56:57]
	s_mov_b32 m0, s41
	s_nop 0
	global_load_lds_dwordx4 v[212:213], off
	s_waitcnt vmcnt(8)
	s_waitcnt lgkmcnt(0)
	s_barrier
	v_mfma_f32_16x16x32_bf16 v[64:67], v[142:145], v[188:191], v[64:67]
	v_mfma_f32_16x16x32_bf16 v[64:67], v[156:159], v[192:195], v[64:67]
	v_mfma_f32_16x16x32_bf16 v[48:51], v[142:145], v[196:199], v[48:51]
	v_mfma_f32_16x16x32_bf16 v[48:51], v[156:159], v[200:203], v[48:51]
	v_mfma_f32_16x16x32_bf16 v[32:35], v[142:145], v[204:207], v[32:35]
	v_mfma_f32_16x16x32_bf16 v[32:35], v[156:159], v[208:211], v[32:35]
	v_mfma_f32_16x16x32_bf16 v[16:19], v[142:145], v[226:229], v[16:19]
	v_mfma_f32_16x16x32_bf16 v[16:19], v[156:159], v[230:233], v[16:19]
	v_mfma_f32_16x16x32_bf16 v[56:59], v[160:163], v[188:191], v[56:59]
	v_mfma_f32_16x16x32_bf16 v[56:59], v[164:167], v[192:195], v[56:59]
	v_mfma_f32_16x16x32_bf16 v[40:43], v[160:163], v[196:199], v[40:43]
	v_mfma_f32_16x16x32_bf16 v[40:43], v[164:167], v[200:203], v[40:43]
	v_mfma_f32_16x16x32_bf16 v[24:27], v[160:163], v[204:207], v[24:27]
	v_mfma_f32_16x16x32_bf16 v[24:27], v[164:167], v[208:211], v[24:27]
	v_mfma_f32_16x16x32_bf16 v[8:11], v[160:163], v[226:229], v[8:11]
	v_mfma_f32_16x16x32_bf16 v[8:11], v[164:167], v[230:233], v[8:11]
	v_mfma_f32_16x16x32_bf16 v[60:63], v[172:175], v[188:191], v[60:63]
	v_mfma_f32_16x16x32_bf16 v[60:63], v[176:179], v[192:195], v[60:63]
	v_mfma_f32_16x16x32_bf16 v[44:47], v[172:175], v[196:199], v[44:47]
	v_mfma_f32_16x16x32_bf16 v[44:47], v[176:179], v[200:203], v[44:47]
	v_mfma_f32_16x16x32_bf16 v[28:31], v[172:175], v[204:207], v[28:31]
	v_mfma_f32_16x16x32_bf16 v[28:31], v[176:179], v[208:211], v[28:31]
	v_mfma_f32_16x16x32_bf16 v[12:15], v[172:175], v[226:229], v[12:15]
	v_mfma_f32_16x16x32_bf16 v[12:15], v[176:179], v[230:233], v[12:15]
	v_mfma_f32_16x16x32_bf16 v[52:55], v[180:183], v[188:191], v[52:55]
	v_mfma_f32_16x16x32_bf16 v[52:55], v[184:187], v[192:195], v[52:55]
	v_mfma_f32_16x16x32_bf16 v[36:39], v[180:183], v[196:199], v[36:39]
	v_mfma_f32_16x16x32_bf16 v[36:39], v[184:187], v[200:203], v[36:39]
	v_mfma_f32_16x16x32_bf16 v[20:23], v[180:183], v[204:207], v[20:23]
	v_mfma_f32_16x16x32_bf16 v[20:23], v[184:187], v[208:211], v[20:23]
	v_mfma_f32_16x16x32_bf16 v[4:7], v[180:183], v[226:229], v[4:7]
	v_mfma_f32_16x16x32_bf16 v[4:7], v[184:187], v[230:233], v[4:7]
	s_barrier
	s_add_i32 s46, s46, 2
	s_add_u32 s20, s20, 0x100
	s_addc_u32 s21, s21, 0
	s_add_u32 s44, s44, 0x100
	s_addc_u32 s45, s45, 0
	s_cmp_gt_u32 s46, 29
	s_cbranch_scc0 .LBB0_296
	s_branch .Lgemm_after_0
.LBB0_296:
	s_add_u32 s22, s20, 0xfff80080
	s_addc_u32 s23, s21, -1
	s_add_i32 s47, 0, 0x10000
	s_cmp_eq_u32 s46, 28
	s_cselect_b32 s25, s11, s23
	s_cselect_b32 s24, s33, s22
	s_cselect_b32 s23, s9, s45
	s_cselect_b32 s22, s43, s44
	s_add_i32 s50, 0, 0x14000
	v_add_u32_e32 v142, s47, v147
	v_add_u32_e32 v156, s47, v148
	v_add_u32_e32 v168, s50, v147
	v_add_u32_e32 v176, s50, v148
	ds_read_b128 v[142:145], v142
	ds_read_b128 v[156:159], v156
	ds_read_b128 v[160:163], v150
	ds_read_b128 v[164:167], v151
	ds_read_b128 v[172:175], v168
	ds_read_b128 v[176:179], v176
	ds_read_b128 v[180:183], v152
	ds_read_b128 v[184:187], v153
	v_lshl_add_u64 v[212:213], s[20:21], 0, v[138:139]
	s_add_i32 m0, s36, 0xc000
	ds_read_b128 v[188:191], v154
	ds_read_b128 v[192:195], v154 offset:1024
	ds_read_b128 v[196:199], v154 offset:2048
	ds_read_b128 v[200:203], v154 offset:3072
	ds_read_b128 v[204:207], v154 offset:4096
	ds_read_b128 v[208:211], v154 offset:5120
	ds_read_b128 v[226:229], v154 offset:6144
	ds_read_b128 v[230:233], v154 offset:7168
	global_load_lds_dwordx4 v[212:213], off
	v_lshl_add_u64 v[212:213], s[20:21], 0, v[140:141]
	s_add_i32 m0, s36, 0xe000
	s_nop 0
	global_load_lds_dwordx4 v[212:213], off
	s_waitcnt vmcnt(8)
	s_waitcnt lgkmcnt(0)
	s_barrier
; #define PG8_STAGE(bufoff, gbase, voff) do { _Pragma("unroll") for (int _i = 0; _i < 2; ++_i) \
;         __builtin_amdgcn_global_load_lds((const unsigned*)((const char*)(gbase) + (voff)[_i]), (PG8_LAS unsigned*)(lds + (bufoff) + ldsw + _i * 8192), 16, 0, 0); } while (0)
; #define PG8_LDA(dst, b, h) do { _Pragma("unroll") for (int m = 0; m < 4; ++m) _Pragma("unroll") for (int k = 0; k < 2; ++k) dst[m][k] = *(const PG8_LAS bf16x8*)(lds + PG8_SA(b, h) + aoffk[k] + m * 2048); } while (0)
; #define PG8_MMA(ai, bj, At, Bt) do { __builtin_amdgcn_s_setprio(1); _Pragma("unroll") for (int m = 0; m < 4; ++m) _Pragma("unroll") for (int n = 0; n < 2; ++n) _Pragma("unroll") for (int k = 0; k < 2; ++k) \
;         acc[ai][bj][m][n] = __builtin_amdgcn_mfma_f32_16x16x32_bf16(Bt[n][k], At[m][k], acc[ai][bj][m][n], 0, 0, 0); __builtin_amdgcn_s_setprio(0); } while (0)
; #define PG8_WAIT_V(n) asm volatile("s_waitcnt vmcnt(" #n ")" ::: "memory")
; #define PG8_WAIT_L(n) asm volatile("s_waitcnt lgkmcnt(" #n ")" ::: "memory")
; #define PG8_BAR __builtin_amdgcn_s_barrier()
; #define PG8_SCHED __builtin_amdgcn_sched_barrier(0)
; template <class Epi, class Sched, bool ALIGN_EPI = false, bool SP2 = false>
; __device__ __forceinline__ void gemm_phase(PG8_LAS unsigned char* lds, const Gemm g, const Sched& S, const Epi& E) {
;     ...
;             PG8_WAIT_V(8); PG8_WAIT_L(0); PG8_BAR; PG8_MMA(0, 0, At, B0); PG8_MMA(0, 1, At, B1); PG8_BAR; PG8_SCHED;
;             PG8_LDA(At, 0, 1); PG8_STAGE(PG8_SB(0, 0), b2, voffB); PG8_STAGE(PG8_SB(0, 1), b2 + hstepB, voffB); PG8_STAGE(PG8_SA(0, 0), a2, voffA);
;             PG8_WAIT_V(8); PG8_WAIT_L(0); PG8_BAR; PG8_MMA(1, 0, At, B0); PG8_MMA(1, 1, At, B1); PG8_BAR; PG8_SCHED;
	v_mfma_f32_16x16x32_bf16 v[128:131], v[142:145], v[188:191], v[128:131]
	v_mfma_f32_16x16x32_bf16 v[128:131], v[156:159], v[192:195], v[128:131]
	v_mfma_f32_16x16x32_bf16 v[112:115], v[142:145], v[196:199], v[112:115]
	v_mfma_f32_16x16x32_bf16 v[112:115], v[156:159], v[200:203], v[112:115]
	v_mfma_f32_16x16x32_bf16 v[96:99], v[142:145], v[204:207], v[96:99]
	v_mfma_f32_16x16x32_bf16 v[96:99], v[156:159], v[208:211], v[96:99]
	v_mfma_f32_16x16x32_bf16 v[80:83], v[142:145], v[226:229], v[80:83]
	v_mfma_f32_16x16x32_bf16 v[80:83], v[156:159], v[230:233], v[80:83]
	v_mfma_f32_16x16x32_bf16 v[120:123], v[160:163], v[188:191], v[120:123]
	v_mfma_f32_16x16x32_bf16 v[120:123], v[164:167], v[192:195], v[120:123]
	v_mfma_f32_16x16x32_bf16 v[104:107], v[160:163], v[196:199], v[104:107]
	v_mfma_f32_16x16x32_bf16 v[104:107], v[164:167], v[200:203], v[104:107]
	v_mfma_f32_16x16x32_bf16 v[88:91], v[160:163], v[204:207], v[88:91]
	v_mfma_f32_16x16x32_bf16 v[88:91], v[164:167], v[208:211], v[88:91]
	v_mfma_f32_16x16x32_bf16 v[72:75], v[160:163], v[226:229], v[72:75]
	v_mfma_f32_16x16x32_bf16 v[72:75], v[164:167], v[230:233], v[72:75]
	v_mfma_f32_16x16x32_bf16 v[124:127], v[172:175], v[188:191], v[124:127]
	v_mfma_f32_16x16x32_bf16 v[124:127], v[176:179], v[192:195], v[124:127]
	v_mfma_f32_16x16x32_bf16 v[108:111], v[172:175], v[196:199], v[108:111]
	v_mfma_f32_16x16x32_bf16 v[108:111], v[176:179], v[200:203], v[108:111]
	v_mfma_f32_16x16x32_bf16 v[92:95], v[172:175], v[204:207], v[92:95]
	v_mfma_f32_16x16x32_bf16 v[92:95], v[176:179], v[208:211], v[92:95]
	v_mfma_f32_16x16x32_bf16 v[76:79], v[172:175], v[226:229], v[76:79]
	v_mfma_f32_16x16x32_bf16 v[76:79], v[176:179], v[230:233], v[76:79]
	v_mfma_f32_16x16x32_bf16 v[116:119], v[180:183], v[188:191], v[116:119]
	v_mfma_f32_16x16x32_bf16 v[116:119], v[184:187], v[192:195], v[116:119]
	v_mfma_f32_16x16x32_bf16 v[100:103], v[180:183], v[196:199], v[100:103]
	v_mfma_f32_16x16x32_bf16 v[100:103], v[184:187], v[200:203], v[100:103]
	v_mfma_f32_16x16x32_bf16 v[84:87], v[180:183], v[204:207], v[84:87]
	v_mfma_f32_16x16x32_bf16 v[84:87], v[184:187], v[208:211], v[84:87]
	v_mfma_f32_16x16x32_bf16 v[68:71], v[180:183], v[226:229], v[68:71]
	v_mfma_f32_16x16x32_bf16 v[68:71], v[184:187], v[230:233], v[68:71]
	s_barrier
	s_add_i32 s47, s47, s34
	v_lshl_add_u64 v[212:213], s[22:23], 0, v[2:3]
	s_mov_b32 m0, s47
	ds_read_b128 v[188:191], v154 offset:16384
	ds_read_b128 v[192:195], v154 offset:17408
	ds_read_b128 v[196:199], v154 offset:18432
	ds_read_b128 v[200:203], v154 offset:19456
	ds_read_b128 v[204:207], v154 offset:20480
	ds_read_b128 v[208:211], v154 offset:21504
	ds_read_b128 v[226:229], v154 offset:22528
	ds_read_b128 v[230:233], v154 offset:23552
	global_load_lds_dwordx4 v[212:213], off
	s_add_i32 m0, s47, 0x2000
	s_add_u32 s48, s22, 0x80000
	v_lshl_add_u64 v[234:235], s[22:23], 0, v[132:133]
	s_addc_u32 s49, s23, 0
	s_add_i32 s47, s50, s34
	global_load_lds_dwordx4 v[234:235], off
	v_lshl_add_u64 v[236:237], s[48:49], 0, v[2:3]
	s_mov_b32 m0, s47
	v_lshl_add_u64 v[238:239], s[24:25], 0, v[134:135]
	global_load_lds_dwordx4 v[236:237], off
	v_lshl_add_u64 v[236:237], s[48:49], 0, v[132:133]
	s_add_i32 m0, s47, 0x2000
	s_nop 0
	global_load_lds_dwordx4 v[236:237], off
	v_lshl_add_u64 v[236:237], s[24:25], 0, v[136:137]
	s_mov_b32 m0, s36
	s_nop 0
	global_load_lds_dwordx4 v[236:237], off
	s_mov_b32 m0, s37
	s_nop 0
	global_load_lds_dwordx4 v[238:239], off
	s_waitcnt vmcnt(8)
	s_waitcnt lgkmcnt(0)
	s_barrier
	v_mfma_f32_16x16x32_bf16 v[64:67], v[142:145], v[188:191], v[64:67]
	v_mfma_f32_16x16x32_bf16 v[64:67], v[156:159], v[192:195], v[64:67]
	v_mfma_f32_16x16x32_bf16 v[48:51], v[142:145], v[196:199], v[48:51]
	v_mfma_f32_16x16x32_bf16 v[48:51], v[156:159], v[200:203], v[48:51]
	v_mfma_f32_16x16x32_bf16 v[32:35], v[142:145], v[204:207], v[32:35]
	v_mfma_f32_16x16x32_bf16 v[32:35], v[156:159], v[208:211], v[32:35]
	v_mfma_f32_16x16x32_bf16 v[16:19], v[142:145], v[226:229], v[16:19]
	v_mfma_f32_16x16x32_bf16 v[16:19], v[156:159], v[230:233], v[16:19]
	v_mfma_f32_16x16x32_bf16 v[56:59], v[160:163], v[188:191], v[56:59]
	v_mfma_f32_16x16x32_bf16 v[56:59], v[164:167], v[192:195], v[56:59]
	v_mfma_f32_16x16x32_bf16 v[40:43], v[160:163], v[196:199], v[40:43]
	v_mfma_f32_16x16x32_bf16 v[40:43], v[164:167], v[200:203], v[40:43]
	v_mfma_f32_16x16x32_bf16 v[24:27], v[160:163], v[204:207], v[24:27]
	v_mfma_f32_16x16x32_bf16 v[24:27], v[164:167], v[208:211], v[24:27]
	v_mfma_f32_16x16x32_bf16 v[8:11], v[160:163], v[226:229], v[8:11]
	v_mfma_f32_16x16x32_bf16 v[8:11], v[164:167], v[230:233], v[8:11]
	v_mfma_f32_16x16x32_bf16 v[60:63], v[172:175], v[188:191], v[60:63]
	v_mfma_f32_16x16x32_bf16 v[60:63], v[176:179], v[192:195], v[60:63]
	v_mfma_f32_16x16x32_bf16 v[44:47], v[172:175], v[196:199], v[44:47]
	v_mfma_f32_16x16x32_bf16 v[44:47], v[176:179], v[200:203], v[44:47]
	v_mfma_f32_16x16x32_bf16 v[28:31], v[172:175], v[204:207], v[28:31]
	v_mfma_f32_16x16x32_bf16 v[28:31], v[176:179], v[208:211], v[28:31]
	v_mfma_f32_16x16x32_bf16 v[12:15], v[172:175], v[226:229], v[12:15]
	v_mfma_f32_16x16x32_bf16 v[12:15], v[176:179], v[230:233], v[12:15]
	v_mfma_f32_16x16x32_bf16 v[52:55], v[180:183], v[188:191], v[52:55]
	v_mfma_f32_16x16x32_bf16 v[52:55], v[184:187], v[192:195], v[52:55]
	v_mfma_f32_16x16x32_bf16 v[36:39], v[180:183], v[196:199], v[36:39]
	v_mfma_f32_16x16x32_bf16 v[36:39], v[184:187], v[200:203], v[36:39]
	v_mfma_f32_16x16x32_bf16 v[20:23], v[180:183], v[204:207], v[20:23]
	v_mfma_f32_16x16x32_bf16 v[20:23], v[184:187], v[208:211], v[20:23]
	v_mfma_f32_16x16x32_bf16 v[4:7], v[180:183], v[226:229], v[4:7]
	v_mfma_f32_16x16x32_bf16 v[4:7], v[184:187], v[230:233], v[4:7]
	s_barrier
; #define PG8_STAGE(bufoff, gbase, voff) do { _Pragma("unroll") for (int _i = 0; _i < 2; ++_i) \
;         __builtin_amdgcn_global_load_lds((const unsigned*)((const char*)(gbase) + (voff)[_i]), (PG8_LAS unsigned*)(lds + (bufoff) + ldsw + _i * 8192), 16, 0, 0); } while (0)
; #define PG8_LDA(dst, b, h) do { _Pragma("unroll") for (int m = 0; m < 4; ++m) _Pragma("unroll") for (int k = 0; k < 2; ++k) dst[m][k] = *(const PG8_LAS bf16x8*)(lds + PG8_SA(b, h) + aoffk[k] + m * 2048); } while (0)
; #define PG8_LDB(dst, b, h) do { _Pragma("unroll") for (int n = 0; n < 2; ++n) _Pragma("unroll") for (int k = 0; k < 2; ++k) dst[n][k] = *(const PG8_LAS bf16x8*)(lds + PG8_SB(b, h) + boffk[k] + n * 2048); } while (0)
; #define PG8_MMA(ai, bj, At, Bt) do { __builtin_amdgcn_s_setprio(1); _Pragma("unroll") for (int m = 0; m < 4; ++m) _Pragma("unroll") for (int n = 0; n < 2; ++n) _Pragma("unroll") for (int k = 0; k < 2; ++k) \
;         acc[ai][bj][m][n] = __builtin_amdgcn_mfma_f32_16x16x32_bf16(Bt[n][k], At[m][k], acc[ai][bj][m][n], 0, 0, 0); __builtin_amdgcn_s_setprio(0); } while (0)
; #define PG8_WAIT_V(n) asm volatile("s_waitcnt vmcnt(" #n ")" ::: "memory")
; #define PG8_WAIT_L(n) asm volatile("s_waitcnt lgkmcnt(" #n ")" ::: "memory")
; #define PG8_BAR __builtin_amdgcn_s_barrier()
; #define PG8_SCHED __builtin_amdgcn_sched_barrier(0)
; template <class Epi, class Sched, bool ALIGN_EPI = false, bool SP2 = false>
; __device__ __forceinline__ void gemm_phase(PG8_LAS unsigned char* lds, const Gemm g, const Sched& S, const Epi& E) {
;     ...
;             PG8_LDB(B0, 1, 0); PG8_LDB(B1, 1, 1); PG8_SCHED; PG8_LDA(At, 1, 0); PG8_STAGE(PG8_SA(0, 1), a2 + hstepA, voffA);
;             PG8_WAIT_V(8); PG8_WAIT_L(0); PG8_BAR; PG8_MMA(0, 0, At, B0); PG8_MMA(0, 1, At, B1); PG8_BAR; PG8_SCHED;
	s_add_i32 s47, 0, 0x18000
	s_add_i32 s48, 0, 0x1c000
	v_add_u32_e32 v142, s47, v147
	v_add_u32_e32 v156, s47, v148
	v_add_u32_e32 v164, s52, v148
	v_add_u32_e32 v168, s48, v147
	v_add_u32_e32 v176, s48, v148
	ds_read_b128 v[142:145], v142
	ds_read_b128 v[156:159], v156
	ds_read_b128 v[160:163], v155
	ds_read_b128 v[164:167], v164
	ds_read_b128 v[172:175], v168
	ds_read_b128 v[176:179], v176
	v_add_u32_e32 v168, s53, v147
	v_add_u32_e32 v184, s53, v148
	ds_read_b128 v[180:183], v168
	ds_read_b128 v[184:187], v184
	s_add_u32 s24, s24, 0x80000
	s_addc_u32 s25, s25, 0
	s_mov_b32 m0, s38
	v_lshl_add_u64 v[240:241], s[24:25], 0, v[136:137]
	ds_read_b128 v[188:191], v154 offset:32768
	ds_read_b128 v[192:195], v154 offset:33792
	ds_read_b128 v[196:199], v154 offset:34816
	ds_read_b128 v[200:203], v154 offset:35840
	ds_read_b128 v[204:207], v154 offset:36864
	ds_read_b128 v[208:211], v154 offset:37888
	ds_read_b128 v[226:229], v154 offset:38912
	ds_read_b128 v[230:233], v154 offset:39936
	global_load_lds_dwordx4 v[240:241], off
	v_lshl_add_u64 v[240:241], s[24:25], 0, v[134:135]
	s_mov_b32 m0, s39
	s_nop 0
	global_load_lds_dwordx4 v[240:241], off
	s_waitcnt vmcnt(8)
	s_waitcnt lgkmcnt(0)
	s_barrier
	v_mfma_f32_16x16x32_bf16 v[128:131], v[142:145], v[188:191], v[128:131]
	v_mfma_f32_16x16x32_bf16 v[128:131], v[156:159], v[192:195], v[128:131]
	v_mfma_f32_16x16x32_bf16 v[112:115], v[142:145], v[196:199], v[112:115]
	v_mfma_f32_16x16x32_bf16 v[112:115], v[156:159], v[200:203], v[112:115]
	v_mfma_f32_16x16x32_bf16 v[96:99], v[142:145], v[204:207], v[96:99]
	v_mfma_f32_16x16x32_bf16 v[96:99], v[156:159], v[208:211], v[96:99]
	v_mfma_f32_16x16x32_bf16 v[80:83], v[142:145], v[226:229], v[80:83]
	v_mfma_f32_16x16x32_bf16 v[80:83], v[156:159], v[230:233], v[80:83]
	v_mfma_f32_16x16x32_bf16 v[120:123], v[160:163], v[188:191], v[120:123]
	v_mfma_f32_16x16x32_bf16 v[120:123], v[164:167], v[192:195], v[120:123]
	v_mfma_f32_16x16x32_bf16 v[104:107], v[160:163], v[196:199], v[104:107]
	v_mfma_f32_16x16x32_bf16 v[104:107], v[164:167], v[200:203], v[104:107]
	v_mfma_f32_16x16x32_bf16 v[88:91], v[160:163], v[204:207], v[88:91]
	v_mfma_f32_16x16x32_bf16 v[88:91], v[164:167], v[208:211], v[88:91]
	v_mfma_f32_16x16x32_bf16 v[72:75], v[160:163], v[226:229], v[72:75]
	v_mfma_f32_16x16x32_bf16 v[72:75], v[164:167], v[230:233], v[72:75]
	v_mfma_f32_16x16x32_bf16 v[124:127], v[172:175], v[188:191], v[124:127]
	v_mfma_f32_16x16x32_bf16 v[124:127], v[176:179], v[192:195], v[124:127]
	v_mfma_f32_16x16x32_bf16 v[108:111], v[172:175], v[196:199], v[108:111]
	v_mfma_f32_16x16x32_bf16 v[108:111], v[176:179], v[200:203], v[108:111]
	v_mfma_f32_16x16x32_bf16 v[92:95], v[172:175], v[204:207], v[92:95]
	v_mfma_f32_16x16x32_bf16 v[92:95], v[176:179], v[208:211], v[92:95]
	v_mfma_f32_16x16x32_bf16 v[76:79], v[172:175], v[226:229], v[76:79]
	v_mfma_f32_16x16x32_bf16 v[76:79], v[176:179], v[230:233], v[76:79]
	v_mfma_f32_16x16x32_bf16 v[116:119], v[180:183], v[188:191], v[116:119]
	v_mfma_f32_16x16x32_bf16 v[116:119], v[184:187], v[192:195], v[116:119]
	v_mfma_f32_16x16x32_bf16 v[100:103], v[180:183], v[196:199], v[100:103]
	v_mfma_f32_16x16x32_bf16 v[100:103], v[184:187], v[200:203], v[100:103]
	v_mfma_f32_16x16x32_bf16 v[84:87], v[180:183], v[204:207], v[84:87]
	v_mfma_f32_16x16x32_bf16 v[84:87], v[184:187], v[208:211], v[84:87]
	v_mfma_f32_16x16x32_bf16 v[68:71], v[180:183], v[226:229], v[68:71]
	v_mfma_f32_16x16x32_bf16 v[68:71], v[184:187], v[230:233], v[68:71]
	s_barrier
; #define PG8_STAGE(bufoff, gbase, voff) do { _Pragma("unroll") for (int _i = 0; _i < 2; ++_i) \
;         __builtin_amdgcn_global_load_lds((const unsigned*)((const char*)(gbase) + (voff)[_i]), (PG8_LAS unsigned*)(lds + (bufoff) + ldsw + _i * 8192), 16, 0, 0); } while (0)
; #define PG8_LDA(dst, b, h) do { _Pragma("unroll") for (int m = 0; m < 4; ++m) _Pragma("unroll") for (int k = 0; k < 2; ++k) dst[m][k] = *(const PG8_LAS bf16x8*)(lds + PG8_SA(b, h) + aoffk[k] + m * 2048); } while (0)
; #define PG8_MMA(ai, bj, At, Bt) do { __builtin_amdgcn_s_setprio(1); _Pragma("unroll") for (int m = 0; m < 4; ++m) _Pragma("unroll") for (int n = 0; n < 2; ++n) _Pragma("unroll") for (int k = 0; k < 2; ++k) \
;         acc[ai][bj][m][n] = __builtin_amdgcn_mfma_f32_16x16x32_bf16(Bt[n][k], At[m][k], acc[ai][bj][m][n], 0, 0, 0); __builtin_amdgcn_s_setprio(0); } while (0)
; #define PG8_WAIT_V(n) asm volatile("s_waitcnt vmcnt(" #n ")" ::: "memory")
; #define PG8_WAIT_L(n) asm volatile("s_waitcnt lgkmcnt(" #n ")" ::: "memory")
; #define PG8_BAR __builtin_amdgcn_s_barrier()
; #define PG8_SCHED __builtin_amdgcn_sched_barrier(0)
; template <class Epi, class Sched, bool ALIGN_EPI = false, bool SP2 = false>
; __device__ __forceinline__ void gemm_phase(PG8_LAS unsigned char* lds, const Gemm g, const Sched& S, const Epi& E) {
;     ...
;             PG8_LDA(At, 1, 1); PG8_STAGE(PG8_SB(1, 0), b3, voffB); PG8_STAGE(PG8_SB(1, 1), b3 + hstepB, voffB); PG8_STAGE(PG8_SA(1, 0), a3, voffA);
;             PG8_WAIT_V(8); PG8_WAIT_L(0); PG8_BAR; PG8_MMA(1, 0, At, B0); PG8_MMA(1, 1, At, B1); PG8_BAR; PG8_SCHED;
	s_add_i32 s24, s47, s34
	v_lshl_add_u64 v[212:213], v[212:213], 0, s[56:57]
	s_mov_b32 m0, s24
	ds_read_b128 v[188:191], v154 offset:49152
	ds_read_b128 v[192:195], v154 offset:50176
	ds_read_b128 v[196:199], v154 offset:51200
	ds_read_b128 v[200:203], v154 offset:52224
	ds_read_b128 v[204:207], v154 offset:53248
	ds_read_b128 v[208:211], v154 offset:54272
	ds_read_b128 v[226:229], v154 offset:55296
	ds_read_b128 v[230:233], v154 offset:56320
	global_load_lds_dwordx4 v[212:213], off
	s_add_i32 m0, s24, 0x2000
	s_add_u32 s22, s22, 0x80080
	v_lshl_add_u64 v[212:213], v[234:235], 0, s[56:57]
	s_addc_u32 s23, s23, 0
	s_add_i32 s24, s48, s34
	global_load_lds_dwordx4 v[212:213], off
	v_lshl_add_u64 v[212:213], s[22:23], 0, v[2:3]
	s_mov_b32 m0, s24
	s_nop 0
	global_load_lds_dwordx4 v[212:213], off
	v_lshl_add_u64 v[212:213], s[22:23], 0, v[132:133]
	s_add_i32 m0, s24, 0x2000
	s_nop 0
	global_load_lds_dwordx4 v[212:213], off
	v_lshl_add_u64 v[212:213], v[236:237], 0, s[56:57]
	s_mov_b32 m0, s40
	s_nop 0
	global_load_lds_dwordx4 v[212:213], off
	v_lshl_add_u64 v[212:213], v[238:239], 0, s[56:57]
	s_mov_b32 m0, s41
	s_nop 0
	global_load_lds_dwordx4 v[212:213], off
	s_waitcnt vmcnt(8)
	s_waitcnt lgkmcnt(0)
	s_barrier
	v_mfma_f32_16x16x32_bf16 v[64:67], v[142:145], v[188:191], v[64:67]
	v_mfma_f32_16x16x32_bf16 v[64:67], v[156:159], v[192:195], v[64:67]
	v_mfma_f32_16x16x32_bf16 v[48:51], v[142:145], v[196:199], v[48:51]
	v_mfma_f32_16x16x32_bf16 v[48:51], v[156:159], v[200:203], v[48:51]
	v_mfma_f32_16x16x32_bf16 v[32:35], v[142:145], v[204:207], v[32:35]
	v_mfma_f32_16x16x32_bf16 v[32:35], v[156:159], v[208:211], v[32:35]
	v_mfma_f32_16x16x32_bf16 v[16:19], v[142:145], v[226:229], v[16:19]
	v_mfma_f32_16x16x32_bf16 v[16:19], v[156:159], v[230:233], v[16:19]
	v_mfma_f32_16x16x32_bf16 v[56:59], v[160:163], v[188:191], v[56:59]
	v_mfma_f32_16x16x32_bf16 v[56:59], v[164:167], v[192:195], v[56:59]
	v_mfma_f32_16x16x32_bf16 v[40:43], v[160:163], v[196:199], v[40:43]
	v_mfma_f32_16x16x32_bf16 v[40:43], v[164:167], v[200:203], v[40:43]
	v_mfma_f32_16x16x32_bf16 v[24:27], v[160:163], v[204:207], v[24:27]
	v_mfma_f32_16x16x32_bf16 v[24:27], v[164:167], v[208:211], v[24:27]
	v_mfma_f32_16x16x32_bf16 v[8:11], v[160:163], v[226:229], v[8:11]
	v_mfma_f32_16x16x32_bf16 v[8:11], v[164:167], v[230:233], v[8:11]
	v_mfma_f32_16x16x32_bf16 v[60:63], v[172:175], v[188:191], v[60:63]
	v_mfma_f32_16x16x32_bf16 v[60:63], v[176:179], v[192:195], v[60:63]
	v_mfma_f32_16x16x32_bf16 v[44:47], v[172:175], v[196:199], v[44:47]
	v_mfma_f32_16x16x32_bf16 v[44:47], v[176:179], v[200:203], v[44:47]
	v_mfma_f32_16x16x32_bf16 v[28:31], v[172:175], v[204:207], v[28:31]
	v_mfma_f32_16x16x32_bf16 v[28:31], v[176:179], v[208:211], v[28:31]
	v_mfma_f32_16x16x32_bf16 v[12:15], v[172:175], v[226:229], v[12:15]
	v_mfma_f32_16x16x32_bf16 v[12:15], v[176:179], v[230:233], v[12:15]
	v_mfma_f32_16x16x32_bf16 v[52:55], v[180:183], v[188:191], v[52:55]
	v_mfma_f32_16x16x32_bf16 v[52:55], v[184:187], v[192:195], v[52:55]
	v_mfma_f32_16x16x32_bf16 v[36:39], v[180:183], v[196:199], v[36:39]
	v_mfma_f32_16x16x32_bf16 v[36:39], v[184:187], v[200:203], v[36:39]
	v_mfma_f32_16x16x32_bf16 v[20:23], v[180:183], v[204:207], v[20:23]
	v_mfma_f32_16x16x32_bf16 v[20:23], v[184:187], v[208:211], v[20:23]
	v_mfma_f32_16x16x32_bf16 v[4:7], v[180:183], v[226:229], v[4:7]
	v_mfma_f32_16x16x32_bf16 v[4:7], v[184:187], v[230:233], v[4:7]
	s_barrier
	s_add_i32 s46, s46, 2
	s_add_u32 s20, s20, 0x100
	s_addc_u32 s21, s21, 0
	s_add_u32 s44, s44, 0x100
	s_addc_u32 s45, s45, 0
	s_cmp_gt_u32 s46, 29
	s_cbranch_scc0 .LBB0_296

; #define PG8_STAGE(bufoff, gbase, voff) do { _Pragma("unroll") for (int _i = 0; _i < 2; ++_i) \
;         __builtin_amdgcn_global_load_lds((const unsigned*)((const char*)(gbase) + (voff)[_i]), (PG8_LAS unsigned*)(lds + (bufoff) + ldsw + _i * 8192), 16, 0, 0); } while (0)
; #define PG8_LDA(dst, b, h) do { _Pragma("unroll") for (int m = 0; m < 4; ++m) _Pragma("unroll") for (int k = 0; k < 2; ++k) dst[m][k] = *(const PG8_LAS bf16x8*)(lds + PG8_SA(b, h) + aoffk[k] + m * 2048); } while (0)
; #define PG8_LDB(dst, b, h) do { _Pragma("unroll") for (int n = 0; n < 2; ++n) _Pragma("unroll") for (int k = 0; k < 2; ++k) dst[n][k] = *(const PG8_LAS bf16x8*)(lds + PG8_SB(b, h) + boffk[k] + n * 2048); } while (0)
; #define PG8_MMA(ai, bj, At, Bt) do { __builtin_amdgcn_s_setprio(1); _Pragma("unroll") for (int m = 0; m < 4; ++m) _Pragma("unroll") for (int n = 0; n < 2; ++n) _Pragma("unroll") for (int k = 0; k < 2; ++k) \
;         acc[ai][bj][m][n] = __builtin_amdgcn_mfma_f32_16x16x32_bf16(Bt[n][k], At[m][k], acc[ai][bj][m][n], 0, 0, 0); __builtin_amdgcn_s_setprio(0); } while (0)
; #define PG8_WAIT_V(n) asm volatile("s_waitcnt vmcnt(" #n ")" ::: "memory")
; #define PG8_WAIT_L(n) asm volatile("s_waitcnt lgkmcnt(" #n ")" ::: "memory")
; #define PG8_BAR __builtin_amdgcn_s_barrier()
; #define PG8_SCHED __builtin_amdgcn_sched_barrier(0)
; template <class Epi, class Sched, bool ALIGN_EPI = false, bool SP2 = false>
; __device__ __forceinline__ void gemm_phase(PG8_LAS unsigned char* lds, const Gemm g, const Sched& S, const Epi& E) {
;     ...
;             PG8_LDB(B0, 0, 0); PG8_LDB(B1, 0, 1); PG8_SCHED; PG8_LDA(At, 0, 0); PG8_STAGE(PG8_SA(1, 1), a1 + hstepA, voffA);
;             PG8_WAIT_V(8); PG8_WAIT_L(0); PG8_BAR; PG8_MMA(0, 0, At, B0); PG8_MMA(0, 1, At, B1); PG8_BAR; PG8_SCHED;
;             PG8_LDA(At, 0, 1); PG8_STAGE(PG8_SB(0, 0), b2, voffB); PG8_STAGE(PG8_SB(0, 1), b2 + hstepB, voffB); PG8_STAGE(PG8_SA(0, 0), a2, voffA);
.Lgemm_first_1:
	s_add_i32 s51, s18, 2
	s_add_u32 s16, s14, 0x100
	s_addc_u32 s17, s15, 0
	s_add_i32 s52, 0, 0x10000
	s_cmp_eq_u32 s9, s18
	v_add_u32_e32 v142, s52, v145
	s_cselect_b32 s21, s11, s17
	s_cselect_b32 s20, s10, s16
	v_add_u32_e32 v143, s52, v146
	ds_read_b128 v[150:153], v142
	ds_read_b128 v[154:157], v143
	v_add_u32_e32 v142, s54, v145
	s_cselect_b32 s19, s13, s50
	s_cselect_b32 s18, s12, s49
	s_add_i32 s53, 0, 0x14000
	v_add_u32_e32 v143, s54, v146
	ds_read_b128 v[158:161], v142
	ds_read_b128 v[162:165], v143
	v_add_u32_e32 v142, s53, v145
	v_add_u32_e32 v143, s53, v146
	ds_read_b128 v[172:175], v142
	ds_read_b128 v[176:179], v143
	v_add_u32_e32 v142, s55, v145
	v_add_u32_e32 v143, s55, v146
	ds_read_b128 v[180:183], v142
	ds_read_b128 v[184:187], v143
	v_lshl_add_u64 v[142:143], s[14:15], 0, v[138:139]
	s_add_i32 m0, s28, 0xc000
	ds_read_b128 v[188:191], v148
	ds_read_b128 v[192:195], v148 offset:1024
	ds_read_b128 v[196:199], v148 offset:2048
	ds_read_b128 v[200:203], v148 offset:3072
	ds_read_b128 v[204:207], v148 offset:4096
	ds_read_b128 v[208:211], v148 offset:5120
	ds_read_b128 v[226:229], v148 offset:6144
	ds_read_b128 v[230:233], v148 offset:7168
	global_load_lds_dwordx4 v[142:143], off
	v_lshl_add_u64 v[142:143], s[14:15], 0, v[140:141]
	s_add_i32 m0, s28, 0xe000
	s_nop 0
	global_load_lds_dwordx4 v[142:143], off
	s_waitcnt vmcnt(8)
	s_waitcnt lgkmcnt(0)
	s_barrier
	v_mfma_f32_16x16x32_bf16 v[128:131], v[150:153], v[188:191], 0
	v_mfma_f32_16x16x32_bf16 v[128:131], v[154:157], v[192:195], v[128:131]
	v_mfma_f32_16x16x32_bf16 v[120:123], v[150:153], v[196:199], 0
	v_mfma_f32_16x16x32_bf16 v[120:123], v[154:157], v[200:203], v[120:123]
	v_mfma_f32_16x16x32_bf16 v[104:107], v[150:153], v[204:207], 0
	v_mfma_f32_16x16x32_bf16 v[104:107], v[154:157], v[208:211], v[104:107]
	v_mfma_f32_16x16x32_bf16 v[88:91], v[150:153], v[226:229], 0
	v_mfma_f32_16x16x32_bf16 v[88:91], v[154:157], v[230:233], v[88:91]
	v_mfma_f32_16x16x32_bf16 v[124:127], v[158:161], v[188:191], 0
	v_mfma_f32_16x16x32_bf16 v[124:127], v[162:165], v[192:195], v[124:127]
	v_mfma_f32_16x16x32_bf16 v[112:115], v[158:161], v[196:199], 0
	v_mfma_f32_16x16x32_bf16 v[112:115], v[162:165], v[200:203], v[112:115]
	v_mfma_f32_16x16x32_bf16 v[96:99], v[158:161], v[204:207], 0
	v_mfma_f32_16x16x32_bf16 v[96:99], v[162:165], v[208:211], v[96:99]
	v_mfma_f32_16x16x32_bf16 v[80:83], v[158:161], v[226:229], 0
	v_mfma_f32_16x16x32_bf16 v[80:83], v[162:165], v[230:233], v[80:83]
	v_mfma_f32_16x16x32_bf16 v[116:119], v[172:175], v[188:191], 0
	v_mfma_f32_16x16x32_bf16 v[116:119], v[176:179], v[192:195], v[116:119]
	v_mfma_f32_16x16x32_bf16 v[100:103], v[172:175], v[196:199], 0
	v_mfma_f32_16x16x32_bf16 v[100:103], v[176:179], v[200:203], v[100:103]
	v_mfma_f32_16x16x32_bf16 v[84:87], v[172:175], v[204:207], 0
	v_mfma_f32_16x16x32_bf16 v[84:87], v[176:179], v[208:211], v[84:87]
	v_mfma_f32_16x16x32_bf16 v[72:75], v[172:175], v[226:229], 0
	v_mfma_f32_16x16x32_bf16 v[72:75], v[176:179], v[230:233], v[72:75]
	v_mfma_f32_16x16x32_bf16 v[108:111], v[180:183], v[188:191], 0
	v_mfma_f32_16x16x32_bf16 v[108:111], v[184:187], v[192:195], v[108:111]
	v_mfma_f32_16x16x32_bf16 v[92:95], v[180:183], v[196:199], 0
	v_mfma_f32_16x16x32_bf16 v[92:95], v[184:187], v[200:203], v[92:95]
	v_mfma_f32_16x16x32_bf16 v[76:79], v[180:183], v[204:207], 0
	v_mfma_f32_16x16x32_bf16 v[76:79], v[184:187], v[208:211], v[76:79]
	v_mfma_f32_16x16x32_bf16 v[68:71], v[180:183], v[226:229], 0
	v_mfma_f32_16x16x32_bf16 v[68:71], v[184:187], v[230:233], v[68:71]
	s_barrier
	s_add_i32 s14, s52, s27
	v_lshl_add_u64 v[142:143], s[18:19], 0, v[2:3]
	s_mov_b32 m0, s14
	ds_read_b128 v[188:191], v148 offset:16384
	ds_read_b128 v[192:195], v148 offset:17408
	ds_read_b128 v[196:199], v148 offset:18432
	ds_read_b128 v[200:203], v148 offset:19456
	ds_read_b128 v[204:207], v148 offset:20480
	ds_read_b128 v[208:211], v148 offset:21504
	ds_read_b128 v[226:229], v148 offset:22528
	ds_read_b128 v[230:233], v148 offset:23552
	global_load_lds_dwordx4 v[142:143], off
	s_add_i32 m0, s14, 0x2000
	s_add_u32 s14, s18, 0x160000
	v_lshl_add_u64 v[166:167], s[18:19], 0, v[136:137]
	s_addc_u32 s15, s19, 0
	s_add_i32 s52, s53, s27
	global_load_lds_dwordx4 v[166:167], off
	v_lshl_add_u64 v[212:213], s[14:15], 0, v[2:3]
	s_mov_b32 m0, s52
	v_lshl_add_u64 v[234:235], s[20:21], 0, v[134:135]
	global_load_lds_dwordx4 v[212:213], off
	v_lshl_add_u64 v[212:213], s[14:15], 0, v[136:137]
	s_add_i32 m0, s52, 0x2000
	s_nop 0
	global_load_lds_dwordx4 v[212:213], off
	v_lshl_add_u64 v[212:213], s[20:21], 0, v[132:133]
	s_mov_b32 m0, s28
	s_nop 0
	global_load_lds_dwordx4 v[212:213], off
	s_mov_b32 m0, s29
	s_nop 0
	global_load_lds_dwordx4 v[234:235], off
	s_waitcnt vmcnt(8)
	s_waitcnt lgkmcnt(0)
	s_barrier
; #define PG8_STAGE(bufoff, gbase, voff) do { _Pragma("unroll") for (int _i = 0; _i < 2; ++_i) \
;         __builtin_amdgcn_global_load_lds((const unsigned*)((const char*)(gbase) + (voff)[_i]), (PG8_LAS unsigned*)(lds + (bufoff) + ldsw + _i * 8192), 16, 0, 0); } while (0)
; #define PG8_LDA(dst, b, h) do { _Pragma("unroll") for (int m = 0; m < 4; ++m) _Pragma("unroll") for (int k = 0; k < 2; ++k) dst[m][k] = *(const PG8_LAS bf16x8*)(lds + PG8_SA(b, h) + aoffk[k] + m * 2048); } while (0)
; #define PG8_LDB(dst, b, h) do { _Pragma("unroll") for (int n = 0; n < 2; ++n) _Pragma("unroll") for (int k = 0; k < 2; ++k) dst[n][k] = *(const PG8_LAS bf16x8*)(lds + PG8_SB(b, h) + boffk[k] + n * 2048); } while (0)
; #define PG8_MMA(ai, bj, At, Bt) do { __builtin_amdgcn_s_setprio(1); _Pragma("unroll") for (int m = 0; m < 4; ++m) _Pragma("unroll") for (int n = 0; n < 2; ++n) _Pragma("unroll") for (int k = 0; k < 2; ++k) \
;         acc[ai][bj][m][n] = __builtin_amdgcn_mfma_f32_16x16x32_bf16(Bt[n][k], At[m][k], acc[ai][bj][m][n], 0, 0, 0); __builtin_amdgcn_s_setprio(0); } while (0)
; #define PG8_WAIT_V(n) asm volatile("s_waitcnt vmcnt(" #n ")" ::: "memory")
; #define PG8_WAIT_L(n) asm volatile("s_waitcnt lgkmcnt(" #n ")" ::: "memory")
; #define PG8_BAR __builtin_amdgcn_s_barrier()
; #define PG8_SCHED __builtin_amdgcn_sched_barrier(0)
; template <class Epi, class Sched, bool ALIGN_EPI = false, bool SP2 = false>
; __device__ __forceinline__ void gemm_phase(PG8_LAS unsigned char* lds, const Gemm g, const Sched& S, const Epi& E) {
;     ...
;             PG8_WAIT_V(8); PG8_WAIT_L(0); PG8_BAR; PG8_MMA(1, 0, At, B0); PG8_MMA(1, 1, At, B1); PG8_BAR; PG8_SCHED;
;             PG8_LDB(B0, 1, 0); PG8_LDB(B1, 1, 1); PG8_SCHED; PG8_LDA(At, 1, 0); PG8_STAGE(PG8_SA(0, 1), a2 + hstepA, voffA);
;             PG8_WAIT_V(8); PG8_WAIT_L(0); PG8_BAR; PG8_MMA(0, 0, At, B0); PG8_MMA(0, 1, At, B1); PG8_BAR; PG8_SCHED;
	v_mfma_f32_16x16x32_bf16 v[64:67], v[150:153], v[188:191], 0
	v_mfma_f32_16x16x32_bf16 v[64:67], v[154:157], v[192:195], v[64:67]
	v_mfma_f32_16x16x32_bf16 v[56:59], v[150:153], v[196:199], 0
	v_mfma_f32_16x16x32_bf16 v[56:59], v[154:157], v[200:203], v[56:59]
	v_mfma_f32_16x16x32_bf16 v[40:43], v[150:153], v[204:207], 0
	v_mfma_f32_16x16x32_bf16 v[40:43], v[154:157], v[208:211], v[40:43]
	v_mfma_f32_16x16x32_bf16 v[24:27], v[150:153], v[226:229], 0
	v_mfma_f32_16x16x32_bf16 v[24:27], v[154:157], v[230:233], v[24:27]
	v_mfma_f32_16x16x32_bf16 v[60:63], v[158:161], v[188:191], 0
	v_mfma_f32_16x16x32_bf16 v[60:63], v[162:165], v[192:195], v[60:63]
	v_mfma_f32_16x16x32_bf16 v[48:51], v[158:161], v[196:199], 0
	v_mfma_f32_16x16x32_bf16 v[48:51], v[162:165], v[200:203], v[48:51]
	v_mfma_f32_16x16x32_bf16 v[32:35], v[158:161], v[204:207], 0
	v_mfma_f32_16x16x32_bf16 v[32:35], v[162:165], v[208:211], v[32:35]
	v_mfma_f32_16x16x32_bf16 v[16:19], v[158:161], v[226:229], 0
	v_mfma_f32_16x16x32_bf16 v[16:19], v[162:165], v[230:233], v[16:19]
	v_mfma_f32_16x16x32_bf16 v[52:55], v[172:175], v[188:191], 0
	v_mfma_f32_16x16x32_bf16 v[52:55], v[176:179], v[192:195], v[52:55]
	v_mfma_f32_16x16x32_bf16 v[36:39], v[172:175], v[196:199], 0
	v_mfma_f32_16x16x32_bf16 v[36:39], v[176:179], v[200:203], v[36:39]
	v_mfma_f32_16x16x32_bf16 v[20:23], v[172:175], v[204:207], 0
	v_mfma_f32_16x16x32_bf16 v[20:23], v[176:179], v[208:211], v[20:23]
	v_mfma_f32_16x16x32_bf16 v[8:11], v[172:175], v[226:229], 0
	v_mfma_f32_16x16x32_bf16 v[8:11], v[176:179], v[230:233], v[8:11]
	v_mfma_f32_16x16x32_bf16 v[44:47], v[180:183], v[188:191], 0
	v_mfma_f32_16x16x32_bf16 v[44:47], v[184:187], v[192:195], v[44:47]
	v_mfma_f32_16x16x32_bf16 v[28:31], v[180:183], v[196:199], 0
	v_mfma_f32_16x16x32_bf16 v[28:31], v[184:187], v[200:203], v[28:31]
	v_mfma_f32_16x16x32_bf16 v[12:15], v[180:183], v[204:207], 0
	v_mfma_f32_16x16x32_bf16 v[12:15], v[184:187], v[208:211], v[12:15]
	v_mfma_f32_16x16x32_bf16 v[4:7], v[180:183], v[226:229], 0
	v_mfma_f32_16x16x32_bf16 v[4:7], v[184:187], v[230:233], v[4:7]
	s_barrier
	s_add_i32 s52, 0, 0x18000
	v_add_u32_e32 v149, s52, v145
	v_add_u32_e32 v154, s52, v146
	ds_read_b128 v[150:153], v149
	ds_read_b128 v[154:157], v154
	v_add_u32_e32 v149, s56, v145
	v_add_u32_e32 v162, s56, v146
	s_add_i32 s53, 0, 0x1c000
	ds_read_b128 v[158:161], v149
	ds_read_b128 v[162:165], v162
	v_add_u32_e32 v149, s53, v145
	v_add_u32_e32 v168, s53, v146
	ds_read_b128 v[172:175], v149
	ds_read_b128 v[176:179], v168
	v_add_u32_e32 v149, s57, v145
	v_add_u32_e32 v168, s57, v146
	ds_read_b128 v[180:183], v149
	ds_read_b128 v[184:187], v168
	s_add_u32 s14, s20, 0x160000
	s_addc_u32 s15, s21, 0
	s_mov_b32 m0, s30
	v_lshl_add_u64 v[236:237], s[14:15], 0, v[132:133]
	ds_read_b128 v[188:191], v148 offset:32768
	ds_read_b128 v[192:195], v148 offset:33792
	ds_read_b128 v[196:199], v148 offset:34816
	ds_read_b128 v[200:203], v148 offset:35840
	ds_read_b128 v[204:207], v148 offset:36864
	ds_read_b128 v[208:211], v148 offset:37888
	ds_read_b128 v[226:229], v148 offset:38912
	ds_read_b128 v[230:233], v148 offset:39936
	global_load_lds_dwordx4 v[236:237], off
	v_lshl_add_u64 v[236:237], s[14:15], 0, v[134:135]
	s_mov_b32 m0, s31
	s_nop 0
	global_load_lds_dwordx4 v[236:237], off
	s_waitcnt vmcnt(8)
	s_waitcnt lgkmcnt(0)
	s_barrier
	v_mfma_f32_16x16x32_bf16 v[128:131], v[150:153], v[188:191], v[128:131]
	v_mfma_f32_16x16x32_bf16 v[128:131], v[154:157], v[192:195], v[128:131]
	v_mfma_f32_16x16x32_bf16 v[120:123], v[150:153], v[196:199], v[120:123]
	v_mfma_f32_16x16x32_bf16 v[120:123], v[154:157], v[200:203], v[120:123]
	v_mfma_f32_16x16x32_bf16 v[104:107], v[150:153], v[204:207], v[104:107]
	v_mfma_f32_16x16x32_bf16 v[104:107], v[154:157], v[208:211], v[104:107]
	v_mfma_f32_16x16x32_bf16 v[88:91], v[150:153], v[226:229], v[88:91]
	v_mfma_f32_16x16x32_bf16 v[88:91], v[154:157], v[230:233], v[88:91]
	v_mfma_f32_16x16x32_bf16 v[124:127], v[158:161], v[188:191], v[124:127]
	v_mfma_f32_16x16x32_bf16 v[124:127], v[162:165], v[192:195], v[124:127]
	v_mfma_f32_16x16x32_bf16 v[112:115], v[158:161], v[196:199], v[112:115]
	v_mfma_f32_16x16x32_bf16 v[112:115], v[162:165], v[200:203], v[112:115]
	v_mfma_f32_16x16x32_bf16 v[96:99], v[158:161], v[204:207], v[96:99]
	v_mfma_f32_16x16x32_bf16 v[96:99], v[162:165], v[208:211], v[96:99]
	v_mfma_f32_16x16x32_bf16 v[80:83], v[158:161], v[226:229], v[80:83]
	v_mfma_f32_16x16x32_bf16 v[80:83], v[162:165], v[230:233], v[80:83]
	v_mfma_f32_16x16x32_bf16 v[116:119], v[172:175], v[188:191], v[116:119]
	v_mfma_f32_16x16x32_bf16 v[116:119], v[176:179], v[192:195], v[116:119]
	v_mfma_f32_16x16x32_bf16 v[100:103], v[172:175], v[196:199], v[100:103]
	v_mfma_f32_16x16x32_bf16 v[100:103], v[176:179], v[200:203], v[100:103]
	v_mfma_f32_16x16x32_bf16 v[84:87], v[172:175], v[204:207], v[84:87]
	v_mfma_f32_16x16x32_bf16 v[84:87], v[176:179], v[208:211], v[84:87]
	v_mfma_f32_16x16x32_bf16 v[72:75], v[172:175], v[226:229], v[72:75]
	v_mfma_f32_16x16x32_bf16 v[72:75], v[176:179], v[230:233], v[72:75]
	v_mfma_f32_16x16x32_bf16 v[108:111], v[180:183], v[188:191], v[108:111]
	v_mfma_f32_16x16x32_bf16 v[108:111], v[184:187], v[192:195], v[108:111]
	v_mfma_f32_16x16x32_bf16 v[92:95], v[180:183], v[196:199], v[92:95]
	v_mfma_f32_16x16x32_bf16 v[92:95], v[184:187], v[200:203], v[92:95]
	v_mfma_f32_16x16x32_bf16 v[76:79], v[180:183], v[204:207], v[76:79]
	v_mfma_f32_16x16x32_bf16 v[76:79], v[184:187], v[208:211], v[76:79]
	v_mfma_f32_16x16x32_bf16 v[68:71], v[180:183], v[226:229], v[68:71]
	v_mfma_f32_16x16x32_bf16 v[68:71], v[184:187], v[230:233], v[68:71]
	s_barrier
; #define PG8_STAGE(bufoff, gbase, voff) do { _Pragma("unroll") for (int _i = 0; _i < 2; ++_i) \
;         __builtin_amdgcn_global_load_lds((const unsigned*)((const char*)(gbase) + (voff)[_i]), (PG8_LAS unsigned*)(lds + (bufoff) + ldsw + _i * 8192), 16, 0, 0); } while (0)
; #define PG8_LDA(dst, b, h) do { _Pragma("unroll") for (int m = 0; m < 4; ++m) _Pragma("unroll") for (int k = 0; k < 2; ++k) dst[m][k] = *(const PG8_LAS bf16x8*)(lds + PG8_SA(b, h) + aoffk[k] + m * 2048); } while (0)
; #define PG8_MMA(ai, bj, At, Bt) do { __builtin_amdgcn_s_setprio(1); _Pragma("unroll") for (int m = 0; m < 4; ++m) _Pragma("unroll") for (int n = 0; n < 2; ++n) _Pragma("unroll") for (int k = 0; k < 2; ++k) \
;         acc[ai][bj][m][n] = __builtin_amdgcn_mfma_f32_16x16x32_bf16(Bt[n][k], At[m][k], acc[ai][bj][m][n], 0, 0, 0); __builtin_amdgcn_s_setprio(0); } while (0)
; #define PG8_WAIT_V(n) asm volatile("s_waitcnt vmcnt(" #n ")" ::: "memory")
; #define PG8_WAIT_L(n) asm volatile("s_waitcnt lgkmcnt(" #n ")" ::: "memory")
; #define PG8_BAR __builtin_amdgcn_s_barrier()
; #define PG8_SCHED __builtin_amdgcn_sched_barrier(0)
; template <class Epi, class Sched, bool ALIGN_EPI = false, bool SP2 = false>
; __device__ __forceinline__ void gemm_phase(PG8_LAS unsigned char* lds, const Gemm g, const Sched& S, const Epi& E) {
;     ...
;         for (int t = 0; t < nt; t += 2) {
;             const bool last = (t == nt - 2);
;             const char* a1 = cA + (size_t)(t + 1) * kstep;
;             const char* a2 = last ? nA : cA + (size_t)(t + 2) * kstep; const char* b2 = last ? nB : cB + (size_t)(t + 2) * kstep;
;             const char* a3 = a2 + kstep; const char* b3 = b2 + kstep;
;             if (last && has_next) S.a_ready(nxt);
;     ...
;             PG8_LDA(At, 1, 1); PG8_STAGE(PG8_SB(1, 0), b3, voffB); PG8_STAGE(PG8_SB(1, 1), b3 + hstepB, voffB); PG8_STAGE(PG8_SA(1, 0), a3, voffA);
;             PG8_WAIT_V(8); PG8_WAIT_L(0); PG8_BAR; PG8_MMA(1, 0, At, B0); PG8_MMA(1, 1, At, B1); PG8_BAR; PG8_SCHED;
	s_add_i32 s14, s52, s27
	v_lshl_add_u64 v[142:143], v[142:143], 0, s[58:59]
	s_mov_b32 m0, s14
	ds_read_b128 v[188:191], v148 offset:49152
	ds_read_b128 v[192:195], v148 offset:50176
	ds_read_b128 v[196:199], v148 offset:51200
	ds_read_b128 v[200:203], v148 offset:52224
	ds_read_b128 v[204:207], v148 offset:53248
	ds_read_b128 v[208:211], v148 offset:54272
	ds_read_b128 v[226:229], v148 offset:55296
	ds_read_b128 v[230:233], v148 offset:56320
	global_load_lds_dwordx4 v[142:143], off
	s_add_i32 m0, s14, 0x2000
	s_add_u32 s14, s18, 0x160080
	v_lshl_add_u64 v[142:143], v[166:167], 0, s[58:59]
	s_addc_u32 s15, s19, 0
	s_add_i32 s18, s53, s27
	global_load_lds_dwordx4 v[142:143], off
	v_lshl_add_u64 v[142:143], s[14:15], 0, v[2:3]
	s_mov_b32 m0, s18
	s_nop 0
	global_load_lds_dwordx4 v[142:143], off
	v_lshl_add_u64 v[142:143], s[14:15], 0, v[136:137]
	s_add_i32 m0, s18, 0x2000
	s_nop 0
	global_load_lds_dwordx4 v[142:143], off
	v_lshl_add_u64 v[142:143], v[212:213], 0, s[58:59]
	s_mov_b32 m0, s38
	s_nop 0
	global_load_lds_dwordx4 v[142:143], off
	v_lshl_add_u64 v[142:143], v[234:235], 0, s[58:59]
	s_mov_b32 m0, s39
	s_nop 0
	global_load_lds_dwordx4 v[142:143], off
	s_waitcnt vmcnt(8)
	s_waitcnt lgkmcnt(0)
	s_barrier
	v_mfma_f32_16x16x32_bf16 v[64:67], v[150:153], v[188:191], v[64:67]
	v_mfma_f32_16x16x32_bf16 v[64:67], v[154:157], v[192:195], v[64:67]
	v_mfma_f32_16x16x32_bf16 v[56:59], v[150:153], v[196:199], v[56:59]
	v_mfma_f32_16x16x32_bf16 v[56:59], v[154:157], v[200:203], v[56:59]
	v_mfma_f32_16x16x32_bf16 v[40:43], v[150:153], v[204:207], v[40:43]
	v_mfma_f32_16x16x32_bf16 v[40:43], v[154:157], v[208:211], v[40:43]
	v_mfma_f32_16x16x32_bf16 v[24:27], v[150:153], v[226:229], v[24:27]
	v_mfma_f32_16x16x32_bf16 v[24:27], v[154:157], v[230:233], v[24:27]
	v_mfma_f32_16x16x32_bf16 v[60:63], v[158:161], v[188:191], v[60:63]
	v_mfma_f32_16x16x32_bf16 v[60:63], v[162:165], v[192:195], v[60:63]
	v_mfma_f32_16x16x32_bf16 v[48:51], v[158:161], v[196:199], v[48:51]
	v_mfma_f32_16x16x32_bf16 v[48:51], v[162:165], v[200:203], v[48:51]
	v_mfma_f32_16x16x32_bf16 v[32:35], v[158:161], v[204:207], v[32:35]
	v_mfma_f32_16x16x32_bf16 v[32:35], v[162:165], v[208:211], v[32:35]
	v_mfma_f32_16x16x32_bf16 v[16:19], v[158:161], v[226:229], v[16:19]
	v_mfma_f32_16x16x32_bf16 v[16:19], v[162:165], v[230:233], v[16:19]
	v_mfma_f32_16x16x32_bf16 v[52:55], v[172:175], v[188:191], v[52:55]
	v_mfma_f32_16x16x32_bf16 v[52:55], v[176:179], v[192:195], v[52:55]
	v_mfma_f32_16x16x32_bf16 v[36:39], v[172:175], v[196:199], v[36:39]
	v_mfma_f32_16x16x32_bf16 v[36:39], v[176:179], v[200:203], v[36:39]
	v_mfma_f32_16x16x32_bf16 v[20:23], v[172:175], v[204:207], v[20:23]
	v_mfma_f32_16x16x32_bf16 v[20:23], v[176:179], v[208:211], v[20:23]
	v_mfma_f32_16x16x32_bf16 v[8:11], v[172:175], v[226:229], v[8:11]
	v_mfma_f32_16x16x32_bf16 v[8:11], v[176:179], v[230:233], v[8:11]
	v_mfma_f32_16x16x32_bf16 v[44:47], v[180:183], v[188:191], v[44:47]
	v_mfma_f32_16x16x32_bf16 v[44:47], v[184:187], v[192:195], v[44:47]
	v_mfma_f32_16x16x32_bf16 v[28:31], v[180:183], v[196:199], v[28:31]
	v_mfma_f32_16x16x32_bf16 v[28:31], v[184:187], v[200:203], v[28:31]
	v_mfma_f32_16x16x32_bf16 v[12:15], v[180:183], v[204:207], v[12:15]
	v_mfma_f32_16x16x32_bf16 v[12:15], v[184:187], v[208:211], v[12:15]
	v_mfma_f32_16x16x32_bf16 v[4:7], v[180:183], v[226:229], v[4:7]
	v_mfma_f32_16x16x32_bf16 v[4:7], v[184:187], v[230:233], v[4:7]
	s_barrier
	s_add_u32 s49, s49, 0x100
	s_addc_u32 s50, s50, 0
	s_cmp_ge_i32 s51, s44
	s_mov_b64 s[14:15], s[16:17]
	s_mov_b32 s18, s51
	s_cbranch_scc0 .LBB0_430
	s_branch .Lgemm_after_1
.LBB0_430:
	s_add_i32 s51, s18, 2
	s_add_u32 s16, s14, 0x100
	s_addc_u32 s17, s15, 0
	s_add_i32 s52, 0, 0x10000
	s_cmp_eq_u32 s9, s18
	v_add_u32_e32 v142, s52, v145
	s_cselect_b32 s21, s11, s17
	s_cselect_b32 s20, s10, s16
	v_add_u32_e32 v143, s52, v146
	ds_read_b128 v[150:153], v142
	ds_read_b128 v[154:157], v143
	v_add_u32_e32 v142, s54, v145
	s_cselect_b32 s19, s13, s50
	s_cselect_b32 s18, s12, s49
	s_add_i32 s53, 0, 0x14000
	v_add_u32_e32 v143, s54, v146
	ds_read_b128 v[158:161], v142
	ds_read_b128 v[162:165], v143
	v_add_u32_e32 v142, s53, v145
	v_add_u32_e32 v143, s53, v146
	ds_read_b128 v[172:175], v142
	ds_read_b128 v[176:179], v143
	v_add_u32_e32 v142, s55, v145
	v_add_u32_e32 v143, s55, v146
	ds_read_b128 v[180:183], v142
	ds_read_b128 v[184:187], v143
	v_lshl_add_u64 v[142:143], s[14:15], 0, v[138:139]
	s_add_i32 m0, s28, 0xc000
	ds_read_b128 v[188:191], v148
	ds_read_b128 v[192:195], v148 offset:1024
	ds_read_b128 v[196:199], v148 offset:2048
	ds_read_b128 v[200:203], v148 offset:3072
	ds_read_b128 v[204:207], v148 offset:4096
	ds_read_b128 v[208:211], v148 offset:5120
	ds_read_b128 v[226:229], v148 offset:6144
	ds_read_b128 v[230:233], v148 offset:7168
	global_load_lds_dwordx4 v[142:143], off
	v_lshl_add_u64 v[142:143], s[14:15], 0, v[140:141]
	s_add_i32 m0, s28, 0xe000
	s_nop 0
	global_load_lds_dwordx4 v[142:143], off
	s_waitcnt vmcnt(8)
	s_waitcnt lgkmcnt(0)
	s_barrier
; #define PG8_STAGE(bufoff, gbase, voff) do { _Pragma("unroll") for (int _i = 0; _i < 2; ++_i) \
;         __builtin_amdgcn_global_load_lds((const unsigned*)((const char*)(gbase) + (voff)[_i]), (PG8_LAS unsigned*)(lds + (bufoff) + ldsw + _i * 8192), 16, 0, 0); } while (0)
; #define PG8_LDA(dst, b, h) do { _Pragma("unroll") for (int m = 0; m < 4; ++m) _Pragma("unroll") for (int k = 0; k < 2; ++k) dst[m][k] = *(const PG8_LAS bf16x8*)(lds + PG8_SA(b, h) + aoffk[k] + m * 2048); } while (0)
; #define PG8_MMA(ai, bj, At, Bt) do { __builtin_amdgcn_s_setprio(1); _Pragma("unroll") for (int m = 0; m < 4; ++m) _Pragma("unroll") for (int n = 0; n < 2; ++n) _Pragma("unroll") for (int k = 0; k < 2; ++k) \
;         acc[ai][bj][m][n] = __builtin_amdgcn_mfma_f32_16x16x32_bf16(Bt[n][k], At[m][k], acc[ai][bj][m][n], 0, 0, 0); __builtin_amdgcn_s_setprio(0); } while (0)
; #define PG8_WAIT_V(n) asm volatile("s_waitcnt vmcnt(" #n ")" ::: "memory")
; #define PG8_WAIT_L(n) asm volatile("s_waitcnt lgkmcnt(" #n ")" ::: "memory")
; #define PG8_BAR __builtin_amdgcn_s_barrier()
; #define PG8_SCHED __builtin_amdgcn_sched_barrier(0)
; template <class Epi, class Sched, bool ALIGN_EPI = false, bool SP2 = false>
; __device__ __forceinline__ void gemm_phase(PG8_LAS unsigned char* lds, const Gemm g, const Sched& S, const Epi& E) {
;     ...
;             PG8_WAIT_V(8); PG8_WAIT_L(0); PG8_BAR; PG8_MMA(0, 0, At, B0); PG8_MMA(0, 1, At, B1); PG8_BAR; PG8_SCHED;
;             PG8_LDA(At, 0, 1); PG8_STAGE(PG8_SB(0, 0), b2, voffB); PG8_STAGE(PG8_SB(0, 1), b2 + hstepB, voffB); PG8_STAGE(PG8_SA(0, 0), a2, voffA);
;             PG8_WAIT_V(8); PG8_WAIT_L(0); PG8_BAR; PG8_MMA(1, 0, At, B0); PG8_MMA(1, 1, At, B1); PG8_BAR; PG8_SCHED;
	v_mfma_f32_16x16x32_bf16 v[128:131], v[150:153], v[188:191], v[128:131]
	v_mfma_f32_16x16x32_bf16 v[128:131], v[154:157], v[192:195], v[128:131]
	v_mfma_f32_16x16x32_bf16 v[120:123], v[150:153], v[196:199], v[120:123]
	v_mfma_f32_16x16x32_bf16 v[120:123], v[154:157], v[200:203], v[120:123]
	v_mfma_f32_16x16x32_bf16 v[104:107], v[150:153], v[204:207], v[104:107]
	v_mfma_f32_16x16x32_bf16 v[104:107], v[154:157], v[208:211], v[104:107]
	v_mfma_f32_16x16x32_bf16 v[88:91], v[150:153], v[226:229], v[88:91]
	v_mfma_f32_16x16x32_bf16 v[88:91], v[154:157], v[230:233], v[88:91]
	v_mfma_f32_16x16x32_bf16 v[124:127], v[158:161], v[188:191], v[124:127]
	v_mfma_f32_16x16x32_bf16 v[124:127], v[162:165], v[192:195], v[124:127]
	v_mfma_f32_16x16x32_bf16 v[112:115], v[158:161], v[196:199], v[112:115]
	v_mfma_f32_16x16x32_bf16 v[112:115], v[162:165], v[200:203], v[112:115]
	v_mfma_f32_16x16x32_bf16 v[96:99], v[158:161], v[204:207], v[96:99]
	v_mfma_f32_16x16x32_bf16 v[96:99], v[162:165], v[208:211], v[96:99]
	v_mfma_f32_16x16x32_bf16 v[80:83], v[158:161], v[226:229], v[80:83]
	v_mfma_f32_16x16x32_bf16 v[80:83], v[162:165], v[230:233], v[80:83]
	v_mfma_f32_16x16x32_bf16 v[116:119], v[172:175], v[188:191], v[116:119]
	v_mfma_f32_16x16x32_bf16 v[116:119], v[176:179], v[192:195], v[116:119]
	v_mfma_f32_16x16x32_bf16 v[100:103], v[172:175], v[196:199], v[100:103]
	v_mfma_f32_16x16x32_bf16 v[100:103], v[176:179], v[200:203], v[100:103]
	v_mfma_f32_16x16x32_bf16 v[84:87], v[172:175], v[204:207], v[84:87]
	v_mfma_f32_16x16x32_bf16 v[84:87], v[176:179], v[208:211], v[84:87]
	v_mfma_f32_16x16x32_bf16 v[72:75], v[172:175], v[226:229], v[72:75]
	v_mfma_f32_16x16x32_bf16 v[72:75], v[176:179], v[230:233], v[72:75]
	v_mfma_f32_16x16x32_bf16 v[108:111], v[180:183], v[188:191], v[108:111]
	v_mfma_f32_16x16x32_bf16 v[108:111], v[184:187], v[192:195], v[108:111]
	v_mfma_f32_16x16x32_bf16 v[92:95], v[180:183], v[196:199], v[92:95]
	v_mfma_f32_16x16x32_bf16 v[92:95], v[184:187], v[200:203], v[92:95]
	v_mfma_f32_16x16x32_bf16 v[76:79], v[180:183], v[204:207], v[76:79]
	v_mfma_f32_16x16x32_bf16 v[76:79], v[184:187], v[208:211], v[76:79]
	v_mfma_f32_16x16x32_bf16 v[68:71], v[180:183], v[226:229], v[68:71]
	v_mfma_f32_16x16x32_bf16 v[68:71], v[184:187], v[230:233], v[68:71]
	s_barrier
	s_add_i32 s14, s52, s27
	v_lshl_add_u64 v[142:143], s[18:19], 0, v[2:3]
	s_mov_b32 m0, s14
	ds_read_b128 v[188:191], v148 offset:16384
	ds_read_b128 v[192:195], v148 offset:17408
	ds_read_b128 v[196:199], v148 offset:18432
	ds_read_b128 v[200:203], v148 offset:19456
	ds_read_b128 v[204:207], v148 offset:20480
	ds_read_b128 v[208:211], v148 offset:21504
	ds_read_b128 v[226:229], v148 offset:22528
	ds_read_b128 v[230:233], v148 offset:23552
	global_load_lds_dwordx4 v[142:143], off
	s_add_i32 m0, s14, 0x2000
	s_add_u32 s14, s18, 0x160000
	v_lshl_add_u64 v[166:167], s[18:19], 0, v[136:137]
	s_addc_u32 s15, s19, 0
	s_add_i32 s52, s53, s27
	global_load_lds_dwordx4 v[166:167], off
	v_lshl_add_u64 v[212:213], s[14:15], 0, v[2:3]
	s_mov_b32 m0, s52
	v_lshl_add_u64 v[234:235], s[20:21], 0, v[134:135]
	global_load_lds_dwordx4 v[212:213], off
	v_lshl_add_u64 v[212:213], s[14:15], 0, v[136:137]
	s_add_i32 m0, s52, 0x2000
	s_nop 0
	global_load_lds_dwordx4 v[212:213], off
	v_lshl_add_u64 v[212:213], s[20:21], 0, v[132:133]
	s_mov_b32 m0, s28
	s_nop 0
	global_load_lds_dwordx4 v[212:213], off
	s_mov_b32 m0, s29
	s_nop 0
	global_load_lds_dwordx4 v[234:235], off
	s_waitcnt vmcnt(8)
	s_waitcnt lgkmcnt(0)
	s_barrier
	v_mfma_f32_16x16x32_bf16 v[64:67], v[150:153], v[188:191], v[64:67]
	v_mfma_f32_16x16x32_bf16 v[64:67], v[154:157], v[192:195], v[64:67]
	v_mfma_f32_16x16x32_bf16 v[56:59], v[150:153], v[196:199], v[56:59]
	v_mfma_f32_16x16x32_bf16 v[56:59], v[154:157], v[200:203], v[56:59]
	v_mfma_f32_16x16x32_bf16 v[40:43], v[150:153], v[204:207], v[40:43]
	v_mfma_f32_16x16x32_bf16 v[40:43], v[154:157], v[208:211], v[40:43]
	v_mfma_f32_16x16x32_bf16 v[24:27], v[150:153], v[226:229], v[24:27]
	v_mfma_f32_16x16x32_bf16 v[24:27], v[154:157], v[230:233], v[24:27]
	v_mfma_f32_16x16x32_bf16 v[60:63], v[158:161], v[188:191], v[60:63]
	v_mfma_f32_16x16x32_bf16 v[60:63], v[162:165], v[192:195], v[60:63]
	v_mfma_f32_16x16x32_bf16 v[48:51], v[158:161], v[196:199], v[48:51]
	v_mfma_f32_16x16x32_bf16 v[48:51], v[162:165], v[200:203], v[48:51]
	v_mfma_f32_16x16x32_bf16 v[32:35], v[158:161], v[204:207], v[32:35]
	v_mfma_f32_16x16x32_bf16 v[32:35], v[162:165], v[208:211], v[32:35]
	v_mfma_f32_16x16x32_bf16 v[16:19], v[158:161], v[226:229], v[16:19]
	v_mfma_f32_16x16x32_bf16 v[16:19], v[162:165], v[230:233], v[16:19]
	v_mfma_f32_16x16x32_bf16 v[52:55], v[172:175], v[188:191], v[52:55]
	v_mfma_f32_16x16x32_bf16 v[52:55], v[176:179], v[192:195], v[52:55]
	v_mfma_f32_16x16x32_bf16 v[36:39], v[172:175], v[196:199], v[36:39]
	v_mfma_f32_16x16x32_bf16 v[36:39], v[176:179], v[200:203], v[36:39]
	v_mfma_f32_16x16x32_bf16 v[20:23], v[172:175], v[204:207], v[20:23]
	v_mfma_f32_16x16x32_bf16 v[20:23], v[176:179], v[208:211], v[20:23]
	v_mfma_f32_16x16x32_bf16 v[8:11], v[172:175], v[226:229], v[8:11]
	v_mfma_f32_16x16x32_bf16 v[8:11], v[176:179], v[230:233], v[8:11]
	v_mfma_f32_16x16x32_bf16 v[44:47], v[180:183], v[188:191], v[44:47]
	v_mfma_f32_16x16x32_bf16 v[44:47], v[184:187], v[192:195], v[44:47]
	v_mfma_f32_16x16x32_bf16 v[28:31], v[180:183], v[196:199], v[28:31]
	v_mfma_f32_16x16x32_bf16 v[28:31], v[184:187], v[200:203], v[28:31]
	v_mfma_f32_16x16x32_bf16 v[12:15], v[180:183], v[204:207], v[12:15]
	v_mfma_f32_16x16x32_bf16 v[12:15], v[184:187], v[208:211], v[12:15]
	v_mfma_f32_16x16x32_bf16 v[4:7], v[180:183], v[226:229], v[4:7]
	v_mfma_f32_16x16x32_bf16 v[4:7], v[184:187], v[230:233], v[4:7]
	s_barrier
; #define PG8_STAGE(bufoff, gbase, voff) do { _Pragma("unroll") for (int _i = 0; _i < 2; ++_i) \
;         __builtin_amdgcn_global_load_lds((const unsigned*)((const char*)(gbase) + (voff)[_i]), (PG8_LAS unsigned*)(lds + (bufoff) + ldsw + _i * 8192), 16, 0, 0); } while (0)
; #define PG8_LDA(dst, b, h) do { _Pragma("unroll") for (int m = 0; m < 4; ++m) _Pragma("unroll") for (int k = 0; k < 2; ++k) dst[m][k] = *(const PG8_LAS bf16x8*)(lds + PG8_SA(b, h) + aoffk[k] + m * 2048); } while (0)
; #define PG8_LDB(dst, b, h) do { _Pragma("unroll") for (int n = 0; n < 2; ++n) _Pragma("unroll") for (int k = 0; k < 2; ++k) dst[n][k] = *(const PG8_LAS bf16x8*)(lds + PG8_SB(b, h) + boffk[k] + n * 2048); } while (0)
; #define PG8_MMA(ai, bj, At, Bt) do { __builtin_amdgcn_s_setprio(1); _Pragma("unroll") for (int m = 0; m < 4; ++m) _Pragma("unroll") for (int n = 0; n < 2; ++n) _Pragma("unroll") for (int k = 0; k < 2; ++k) \
;         acc[ai][bj][m][n] = __builtin_amdgcn_mfma_f32_16x16x32_bf16(Bt[n][k], At[m][k], acc[ai][bj][m][n], 0, 0, 0); __builtin_amdgcn_s_setprio(0); } while (0)
; #define PG8_WAIT_V(n) asm volatile("s_waitcnt vmcnt(" #n ")" ::: "memory")
; #define PG8_WAIT_L(n) asm volatile("s_waitcnt lgkmcnt(" #n ")" ::: "memory")
; #define PG8_BAR __builtin_amdgcn_s_barrier()
; #define PG8_SCHED __builtin_amdgcn_sched_barrier(0)
; template <class Epi, class Sched, bool ALIGN_EPI = false, bool SP2 = false>
; __device__ __forceinline__ void gemm_phase(PG8_LAS unsigned char* lds, const Gemm g, const Sched& S, const Epi& E) {
;     ...
;             PG8_LDB(B0, 1, 0); PG8_LDB(B1, 1, 1); PG8_SCHED; PG8_LDA(At, 1, 0); PG8_STAGE(PG8_SA(0, 1), a2 + hstepA, voffA);
;             PG8_WAIT_V(8); PG8_WAIT_L(0); PG8_BAR; PG8_MMA(0, 0, At, B0); PG8_MMA(0, 1, At, B1); PG8_BAR; PG8_SCHED;
	s_add_i32 s52, 0, 0x18000
	v_add_u32_e32 v149, s52, v145
	v_add_u32_e32 v154, s52, v146
	ds_read_b128 v[150:153], v149
	ds_read_b128 v[154:157], v154
	v_add_u32_e32 v149, s56, v145
	v_add_u32_e32 v162, s56, v146
	s_add_i32 s53, 0, 0x1c000
	ds_read_b128 v[158:161], v149
	ds_read_b128 v[162:165], v162
	v_add_u32_e32 v149, s53, v145
	v_add_u32_e32 v168, s53, v146
	ds_read_b128 v[172:175], v149
	ds_read_b128 v[176:179], v168
	v_add_u32_e32 v149, s57, v145
	v_add_u32_e32 v168, s57, v146
	ds_read_b128 v[180:183], v149
	ds_read_b128 v[184:187], v168
	s_add_u32 s14, s20, 0x160000
	s_addc_u32 s15, s21, 0
	s_mov_b32 m0, s30
	v_lshl_add_u64 v[236:237], s[14:15], 0, v[132:133]
	ds_read_b128 v[188:191], v148 offset:32768
	ds_read_b128 v[192:195], v148 offset:33792
	ds_read_b128 v[196:199], v148 offset:34816
	ds_read_b128 v[200:203], v148 offset:35840
	ds_read_b128 v[204:207], v148 offset:36864
	ds_read_b128 v[208:211], v148 offset:37888
	ds_read_b128 v[226:229], v148 offset:38912
	ds_read_b128 v[230:233], v148 offset:39936
	global_load_lds_dwordx4 v[236:237], off
	v_lshl_add_u64 v[236:237], s[14:15], 0, v[134:135]
	s_mov_b32 m0, s31
	s_nop 0
	global_load_lds_dwordx4 v[236:237], off
	s_waitcnt vmcnt(8)
	s_waitcnt lgkmcnt(0)
	s_barrier
	v_mfma_f32_16x16x32_bf16 v[128:131], v[150:153], v[188:191], v[128:131]
	v_mfma_f32_16x16x32_bf16 v[128:131], v[154:157], v[192:195], v[128:131]
	v_mfma_f32_16x16x32_bf16 v[120:123], v[150:153], v[196:199], v[120:123]
	v_mfma_f32_16x16x32_bf16 v[120:123], v[154:157], v[200:203], v[120:123]
	v_mfma_f32_16x16x32_bf16 v[104:107], v[150:153], v[204:207], v[104:107]
	v_mfma_f32_16x16x32_bf16 v[104:107], v[154:157], v[208:211], v[104:107]
	v_mfma_f32_16x16x32_bf16 v[88:91], v[150:153], v[226:229], v[88:91]
	v_mfma_f32_16x16x32_bf16 v[88:91], v[154:157], v[230:233], v[88:91]
	v_mfma_f32_16x16x32_bf16 v[124:127], v[158:161], v[188:191], v[124:127]
	v_mfma_f32_16x16x32_bf16 v[124:127], v[162:165], v[192:195], v[124:127]
	v_mfma_f32_16x16x32_bf16 v[112:115], v[158:161], v[196:199], v[112:115]
	v_mfma_f32_16x16x32_bf16 v[112:115], v[162:165], v[200:203], v[112:115]
	v_mfma_f32_16x16x32_bf16 v[96:99], v[158:161], v[204:207], v[96:99]
	v_mfma_f32_16x16x32_bf16 v[96:99], v[162:165], v[208:211], v[96:99]
	v_mfma_f32_16x16x32_bf16 v[80:83], v[158:161], v[226:229], v[80:83]
	v_mfma_f32_16x16x32_bf16 v[80:83], v[162:165], v[230:233], v[80:83]
	v_mfma_f32_16x16x32_bf16 v[116:119], v[172:175], v[188:191], v[116:119]
	v_mfma_f32_16x16x32_bf16 v[116:119], v[176:179], v[192:195], v[116:119]
	v_mfma_f32_16x16x32_bf16 v[100:103], v[172:175], v[196:199], v[100:103]
	v_mfma_f32_16x16x32_bf16 v[100:103], v[176:179], v[200:203], v[100:103]
	v_mfma_f32_16x16x32_bf16 v[84:87], v[172:175], v[204:207], v[84:87]
	v_mfma_f32_16x16x32_bf16 v[84:87], v[176:179], v[208:211], v[84:87]
	v_mfma_f32_16x16x32_bf16 v[72:75], v[172:175], v[226:229], v[72:75]
	v_mfma_f32_16x16x32_bf16 v[72:75], v[176:179], v[230:233], v[72:75]
	v_mfma_f32_16x16x32_bf16 v[108:111], v[180:183], v[188:191], v[108:111]
	v_mfma_f32_16x16x32_bf16 v[108:111], v[184:187], v[192:195], v[108:111]
	v_mfma_f32_16x16x32_bf16 v[92:95], v[180:183], v[196:199], v[92:95]
	v_mfma_f32_16x16x32_bf16 v[92:95], v[184:187], v[200:203], v[92:95]
	v_mfma_f32_16x16x32_bf16 v[76:79], v[180:183], v[204:207], v[76:79]
	v_mfma_f32_16x16x32_bf16 v[76:79], v[184:187], v[208:211], v[76:79]
	v_mfma_f32_16x16x32_bf16 v[68:71], v[180:183], v[226:229], v[68:71]
	v_mfma_f32_16x16x32_bf16 v[68:71], v[184:187], v[230:233], v[68:71]
	s_barrier
; #define PG8_STAGE(bufoff, gbase, voff) do { _Pragma("unroll") for (int _i = 0; _i < 2; ++_i) \
;         __builtin_amdgcn_global_load_lds((const unsigned*)((const char*)(gbase) + (voff)[_i]), (PG8_LAS unsigned*)(lds + (bufoff) + ldsw + _i * 8192), 16, 0, 0); } while (0)
; #define PG8_LDA(dst, b, h) do { _Pragma("unroll") for (int m = 0; m < 4; ++m) _Pragma("unroll") for (int k = 0; k < 2; ++k) dst[m][k] = *(const PG8_LAS bf16x8*)(lds + PG8_SA(b, h) + aoffk[k] + m * 2048); } while (0)
; #define PG8_MMA(ai, bj, At, Bt) do { __builtin_amdgcn_s_setprio(1); _Pragma("unroll") for (int m = 0; m < 4; ++m) _Pragma("unroll") for (int n = 0; n < 2; ++n) _Pragma("unroll") for (int k = 0; k < 2; ++k) \
;         acc[ai][bj][m][n] = __builtin_amdgcn_mfma_f32_16x16x32_bf16(Bt[n][k], At[m][k], acc[ai][bj][m][n], 0, 0, 0); __builtin_amdgcn_s_setprio(0); } while (0)
; #define PG8_WAIT_V(n) asm volatile("s_waitcnt vmcnt(" #n ")" ::: "memory")
; #define PG8_WAIT_L(n) asm volatile("s_waitcnt lgkmcnt(" #n ")" ::: "memory")
; #define PG8_BAR __builtin_amdgcn_s_barrier()
; #define PG8_SCHED __builtin_amdgcn_sched_barrier(0)
; template <class Epi, class Sched, bool ALIGN_EPI = false, bool SP2 = false>
; __device__ __forceinline__ void gemm_phase(PG8_LAS unsigned char* lds, const Gemm g, const Sched& S, const Epi& E) {
;     ...
;             PG8_LDA(At, 1, 1); PG8_STAGE(PG8_SB(1, 0), b3, voffB); PG8_STAGE(PG8_SB(1, 1), b3 + hstepB, voffB); PG8_STAGE(PG8_SA(1, 0), a3, voffA);
;             PG8_WAIT_V(8); PG8_WAIT_L(0); PG8_BAR; PG8_MMA(1, 0, At, B0); PG8_MMA(1, 1, At, B1); PG8_BAR; PG8_SCHED;
	s_add_i32 s14, s52, s27
	v_lshl_add_u64 v[142:143], v[142:143], 0, s[58:59]
	s_mov_b32 m0, s14
	ds_read_b128 v[188:191], v148 offset:49152
	ds_read_b128 v[192:195], v148 offset:50176
	ds_read_b128 v[196:199], v148 offset:51200
	ds_read_b128 v[200:203], v148 offset:52224
	ds_read_b128 v[204:207], v148 offset:53248
	ds_read_b128 v[208:211], v148 offset:54272
	ds_read_b128 v[226:229], v148 offset:55296
	ds_read_b128 v[230:233], v148 offset:56320
	global_load_lds_dwordx4 v[142:143], off
	s_add_i32 m0, s14, 0x2000
	s_add_u32 s14, s18, 0x160080
	v_lshl_add_u64 v[142:143], v[166:167], 0, s[58:59]
	s_addc_u32 s15, s19, 0
	s_add_i32 s18, s53, s27
	global_load_lds_dwordx4 v[142:143], off
	v_lshl_add_u64 v[142:143], s[14:15], 0, v[2:3]
	s_mov_b32 m0, s18
	s_nop 0
	global_load_lds_dwordx4 v[142:143], off
	v_lshl_add_u64 v[142:143], s[14:15], 0, v[136:137]
	s_add_i32 m0, s18, 0x2000
	s_nop 0
	global_load_lds_dwordx4 v[142:143], off
	v_lshl_add_u64 v[142:143], v[212:213], 0, s[58:59]
	s_mov_b32 m0, s38
	s_nop 0
	global_load_lds_dwordx4 v[142:143], off
	v_lshl_add_u64 v[142:143], v[234:235], 0, s[58:59]
	s_mov_b32 m0, s39
	s_nop 0
	global_load_lds_dwordx4 v[142:143], off
	s_waitcnt vmcnt(8)
	s_waitcnt lgkmcnt(0)
	s_barrier
	v_mfma_f32_16x16x32_bf16 v[64:67], v[150:153], v[188:191], v[64:67]
	v_mfma_f32_16x16x32_bf16 v[64:67], v[154:157], v[192:195], v[64:67]
	v_mfma_f32_16x16x32_bf16 v[56:59], v[150:153], v[196:199], v[56:59]
	v_mfma_f32_16x16x32_bf16 v[56:59], v[154:157], v[200:203], v[56:59]
	v_mfma_f32_16x16x32_bf16 v[40:43], v[150:153], v[204:207], v[40:43]
	v_mfma_f32_16x16x32_bf16 v[40:43], v[154:157], v[208:211], v[40:43]
	v_mfma_f32_16x16x32_bf16 v[24:27], v[150:153], v[226:229], v[24:27]
	v_mfma_f32_16x16x32_bf16 v[24:27], v[154:157], v[230:233], v[24:27]
	v_mfma_f32_16x16x32_bf16 v[60:63], v[158:161], v[188:191], v[60:63]
	v_mfma_f32_16x16x32_bf16 v[60:63], v[162:165], v[192:195], v[60:63]
	v_mfma_f32_16x16x32_bf16 v[48:51], v[158:161], v[196:199], v[48:51]
	v_mfma_f32_16x16x32_bf16 v[48:51], v[162:165], v[200:203], v[48:51]
	v_mfma_f32_16x16x32_bf16 v[32:35], v[158:161], v[204:207], v[32:35]
	v_mfma_f32_16x16x32_bf16 v[32:35], v[162:165], v[208:211], v[32:35]
	v_mfma_f32_16x16x32_bf16 v[16:19], v[158:161], v[226:229], v[16:19]
	v_mfma_f32_16x16x32_bf16 v[16:19], v[162:165], v[230:233], v[16:19]
	v_mfma_f32_16x16x32_bf16 v[52:55], v[172:175], v[188:191], v[52:55]
	v_mfma_f32_16x16x32_bf16 v[52:55], v[176:179], v[192:195], v[52:55]
	v_mfma_f32_16x16x32_bf16 v[36:39], v[172:175], v[196:199], v[36:39]
	v_mfma_f32_16x16x32_bf16 v[36:39], v[176:179], v[200:203], v[36:39]
	v_mfma_f32_16x16x32_bf16 v[20:23], v[172:175], v[204:207], v[20:23]
	v_mfma_f32_16x16x32_bf16 v[20:23], v[176:179], v[208:211], v[20:23]
	v_mfma_f32_16x16x32_bf16 v[8:11], v[172:175], v[226:229], v[8:11]
	v_mfma_f32_16x16x32_bf16 v[8:11], v[176:179], v[230:233], v[8:11]
	v_mfma_f32_16x16x32_bf16 v[44:47], v[180:183], v[188:191], v[44:47]
	v_mfma_f32_16x16x32_bf16 v[44:47], v[184:187], v[192:195], v[44:47]
	v_mfma_f32_16x16x32_bf16 v[28:31], v[180:183], v[196:199], v[28:31]
	v_mfma_f32_16x16x32_bf16 v[28:31], v[184:187], v[200:203], v[28:31]
	v_mfma_f32_16x16x32_bf16 v[12:15], v[180:183], v[204:207], v[12:15]
	v_mfma_f32_16x16x32_bf16 v[12:15], v[184:187], v[208:211], v[12:15]
	v_mfma_f32_16x16x32_bf16 v[4:7], v[180:183], v[226:229], v[4:7]
	v_mfma_f32_16x16x32_bf16 v[4:7], v[184:187], v[230:233], v[4:7]
	s_barrier
	s_add_u32 s49, s49, 0x100
	s_addc_u32 s50, s50, 0
	s_cmp_ge_i32 s51, s44
	s_mov_b64 s[14:15], s[16:17]
	s_mov_b32 s18, s51
	s_cbranch_scc0 .LBB0_430

; #define PG8_STAGE(bufoff, gbase, voff) do { _Pragma("unroll") for (int _i = 0; _i < 2; ++_i) \
;         __builtin_amdgcn_global_load_lds((const unsigned*)((const char*)(gbase) + (voff)[_i]), (PG8_LAS unsigned*)(lds + (bufoff) + ldsw + _i * 8192), 16, 0, 0); } while (0)
; #define PG8_LDA(dst, b, h) do { _Pragma("unroll") for (int m = 0; m < 4; ++m) _Pragma("unroll") for (int k = 0; k < 2; ++k) dst[m][k] = *(const PG8_LAS bf16x8*)(lds + PG8_SA(b, h) + aoffk[k] + m * 2048); } while (0)
; #define PG8_LDB(dst, b, h) do { _Pragma("unroll") for (int n = 0; n < 2; ++n) _Pragma("unroll") for (int k = 0; k < 2; ++k) dst[n][k] = *(const PG8_LAS bf16x8*)(lds + PG8_SB(b, h) + boffk[k] + n * 2048); } while (0)
; #define PG8_MMA(ai, bj, At, Bt) do { __builtin_amdgcn_s_setprio(1); _Pragma("unroll") for (int m = 0; m < 4; ++m) _Pragma("unroll") for (int n = 0; n < 2; ++n) _Pragma("unroll") for (int k = 0; k < 2; ++k) \
;         acc[ai][bj][m][n] = __builtin_amdgcn_mfma_f32_16x16x32_bf16(Bt[n][k], At[m][k], acc[ai][bj][m][n], 0, 0, 0); __builtin_amdgcn_s_setprio(0); } while (0)
; #define PG8_WAIT_V(n) asm volatile("s_waitcnt vmcnt(" #n ")" ::: "memory")
; #define PG8_WAIT_L(n) asm volatile("s_waitcnt lgkmcnt(" #n ")" ::: "memory")
; #define PG8_BAR __builtin_amdgcn_s_barrier()
; #define PG8_SCHED __builtin_amdgcn_sched_barrier(0)
; template <class Epi, class Sched, bool ALIGN_EPI = false, bool SP2 = false>
; __device__ __forceinline__ void gemm_phase(PG8_LAS unsigned char* lds, const Gemm g, const Sched& S, const Epi& E) {
;     ...
;             PG8_LDB(B0, 0, 0); PG8_LDB(B1, 0, 1); PG8_SCHED; PG8_LDA(At, 0, 0); PG8_STAGE(PG8_SA(1, 1), a1 + hstepA, voffA);
;             PG8_WAIT_V(8); PG8_WAIT_L(0); PG8_BAR; PG8_MMA(0, 0, At, B0); PG8_MMA(0, 1, At, B1); PG8_BAR; PG8_SCHED;
;             PG8_LDA(At, 0, 1); PG8_STAGE(PG8_SB(0, 0), b2, voffB); PG8_STAGE(PG8_SB(0, 1), b2 + hstepB, voffB); PG8_STAGE(PG8_SA(0, 0), a2, voffA);
.Lgemm_first_2:
	s_add_u32 s20, s18, 0xfff80080
	s_addc_u32 s21, s19, -1
	s_add_i32 s45, 0, 0x10000
	s_cmp_eq_u32 s44, 28
	v_add_u32_e32 v142, s45, v147
	v_add_u32_e32 v151, s45, v148
	s_cselect_b32 s23, s9, s21
	s_cselect_b32 s22, s40, s20
	ds_read_b128 v[142:145], v142
	ds_read_b128 v[152:155], v151
	v_add_u32_e32 v151, s49, v147
	v_add_u32_e32 v160, s49, v148
	s_cselect_b32 s21, s7, s43
	s_cselect_b32 s20, s41, s42
	s_add_i32 s48, 0, 0x14000
	ds_read_b128 v[156:159], v151
	ds_read_b128 v[160:163], v160
	v_add_u32_e32 v151, s48, v147
	v_add_u32_e32 v168, s48, v148
	ds_read_b128 v[164:167], v151
	ds_read_b128 v[172:175], v168
	v_add_u32_e32 v151, s50, v147
	v_add_u32_e32 v168, s50, v148
	ds_read_b128 v[176:179], v151
	ds_read_b128 v[180:183], v168
	v_lshl_add_u64 v[212:213], s[18:19], 0, v[138:139]
	s_add_i32 m0, s33, 0xc000
	ds_read_b128 v[184:187], v150
	ds_read_b128 v[188:191], v150 offset:1024
	ds_read_b128 v[192:195], v150 offset:2048
	ds_read_b128 v[196:199], v150 offset:3072
	ds_read_b128 v[200:203], v150 offset:4096
	ds_read_b128 v[204:207], v150 offset:5120
	ds_read_b128 v[208:211], v150 offset:6144
	ds_read_b128 v[226:229], v150 offset:7168
	global_load_lds_dwordx4 v[212:213], off
	v_lshl_add_u64 v[212:213], s[18:19], 0, v[140:141]
	s_add_i32 m0, s33, 0xe000
	s_nop 0
	global_load_lds_dwordx4 v[212:213], off
	s_waitcnt vmcnt(8)
	s_waitcnt lgkmcnt(0)
	s_barrier
	v_mfma_f32_16x16x32_bf16 v[128:131], v[142:145], v[184:187], 0
	v_mfma_f32_16x16x32_bf16 v[128:131], v[152:155], v[188:191], v[128:131]
	v_mfma_f32_16x16x32_bf16 v[120:123], v[142:145], v[192:195], 0
	v_mfma_f32_16x16x32_bf16 v[120:123], v[152:155], v[196:199], v[120:123]
	v_mfma_f32_16x16x32_bf16 v[104:107], v[142:145], v[200:203], 0
	v_mfma_f32_16x16x32_bf16 v[104:107], v[152:155], v[204:207], v[104:107]
	v_mfma_f32_16x16x32_bf16 v[88:91], v[142:145], v[208:211], 0
	v_mfma_f32_16x16x32_bf16 v[88:91], v[152:155], v[226:229], v[88:91]
	v_mfma_f32_16x16x32_bf16 v[124:127], v[156:159], v[184:187], 0
	v_mfma_f32_16x16x32_bf16 v[124:127], v[160:163], v[188:191], v[124:127]
	v_mfma_f32_16x16x32_bf16 v[112:115], v[156:159], v[192:195], 0
	v_mfma_f32_16x16x32_bf16 v[112:115], v[160:163], v[196:199], v[112:115]
	v_mfma_f32_16x16x32_bf16 v[96:99], v[156:159], v[200:203], 0
	v_mfma_f32_16x16x32_bf16 v[96:99], v[160:163], v[204:207], v[96:99]
	v_mfma_f32_16x16x32_bf16 v[80:83], v[156:159], v[208:211], 0
	v_mfma_f32_16x16x32_bf16 v[80:83], v[160:163], v[226:229], v[80:83]
	v_mfma_f32_16x16x32_bf16 v[116:119], v[164:167], v[184:187], 0
	v_mfma_f32_16x16x32_bf16 v[116:119], v[172:175], v[188:191], v[116:119]
	v_mfma_f32_16x16x32_bf16 v[100:103], v[164:167], v[192:195], 0
	v_mfma_f32_16x16x32_bf16 v[100:103], v[172:175], v[196:199], v[100:103]
	v_mfma_f32_16x16x32_bf16 v[84:87], v[164:167], v[200:203], 0
	v_mfma_f32_16x16x32_bf16 v[84:87], v[172:175], v[204:207], v[84:87]
	v_mfma_f32_16x16x32_bf16 v[72:75], v[164:167], v[208:211], 0
	v_mfma_f32_16x16x32_bf16 v[72:75], v[172:175], v[226:229], v[72:75]
	v_mfma_f32_16x16x32_bf16 v[108:111], v[176:179], v[184:187], 0
	v_mfma_f32_16x16x32_bf16 v[108:111], v[180:183], v[188:191], v[108:111]
	v_mfma_f32_16x16x32_bf16 v[92:95], v[176:179], v[192:195], 0
	v_mfma_f32_16x16x32_bf16 v[92:95], v[180:183], v[196:199], v[92:95]
	v_mfma_f32_16x16x32_bf16 v[76:79], v[176:179], v[200:203], 0
	v_mfma_f32_16x16x32_bf16 v[76:79], v[180:183], v[204:207], v[76:79]
	v_mfma_f32_16x16x32_bf16 v[68:71], v[176:179], v[208:211], 0
	v_mfma_f32_16x16x32_bf16 v[68:71], v[180:183], v[226:229], v[68:71]
	s_barrier
	s_add_i32 s45, s45, s30
	v_lshl_add_u64 v[212:213], s[20:21], 0, v[2:3]
	s_mov_b32 m0, s45
	ds_read_b128 v[184:187], v150 offset:16384
	ds_read_b128 v[188:191], v150 offset:17408
	ds_read_b128 v[192:195], v150 offset:18432
	ds_read_b128 v[196:199], v150 offset:19456
	ds_read_b128 v[200:203], v150 offset:20480
	ds_read_b128 v[204:207], v150 offset:21504
	ds_read_b128 v[208:211], v150 offset:22528
	ds_read_b128 v[226:229], v150 offset:23552
	global_load_lds_dwordx4 v[212:213], off
	s_add_i32 m0, s45, 0x2000
	s_add_u32 s46, s20, 0x80000
	v_lshl_add_u64 v[230:231], s[20:21], 0, v[132:133]
	s_addc_u32 s47, s21, 0
	s_add_i32 s45, s48, s30
	global_load_lds_dwordx4 v[230:231], off
	v_lshl_add_u64 v[232:233], s[46:47], 0, v[2:3]
	s_mov_b32 m0, s45
	v_lshl_add_u64 v[234:235], s[22:23], 0, v[134:135]
	global_load_lds_dwordx4 v[232:233], off
	v_lshl_add_u64 v[232:233], s[46:47], 0, v[132:133]
	s_add_i32 m0, s45, 0x2000
	s_nop 0
	global_load_lds_dwordx4 v[232:233], off
	v_lshl_add_u64 v[232:233], s[22:23], 0, v[136:137]
	s_mov_b32 m0, s33
	s_nop 0
	global_load_lds_dwordx4 v[232:233], off
	s_mov_b32 m0, s34
	s_nop 0
	global_load_lds_dwordx4 v[234:235], off
	s_waitcnt vmcnt(8)
	s_waitcnt lgkmcnt(0)
	s_barrier
; #define PG8_STAGE(bufoff, gbase, voff) do { _Pragma("unroll") for (int _i = 0; _i < 2; ++_i) \
;         __builtin_amdgcn_global_load_lds((const unsigned*)((const char*)(gbase) + (voff)[_i]), (PG8_LAS unsigned*)(lds + (bufoff) + ldsw + _i * 8192), 16, 0, 0); } while (0)
; #define PG8_LDA(dst, b, h) do { _Pragma("unroll") for (int m = 0; m < 4; ++m) _Pragma("unroll") for (int k = 0; k < 2; ++k) dst[m][k] = *(const PG8_LAS bf16x8*)(lds + PG8_SA(b, h) + aoffk[k] + m * 2048); } while (0)
; #define PG8_LDB(dst, b, h) do { _Pragma("unroll") for (int n = 0; n < 2; ++n) _Pragma("unroll") for (int k = 0; k < 2; ++k) dst[n][k] = *(const PG8_LAS bf16x8*)(lds + PG8_SB(b, h) + boffk[k] + n * 2048); } while (0)
; #define PG8_MMA(ai, bj, At, Bt) do { __builtin_amdgcn_s_setprio(1); _Pragma("unroll") for (int m = 0; m < 4; ++m) _Pragma("unroll") for (int n = 0; n < 2; ++n) _Pragma("unroll") for (int k = 0; k < 2; ++k) \
;         acc[ai][bj][m][n] = __builtin_amdgcn_mfma_f32_16x16x32_bf16(Bt[n][k], At[m][k], acc[ai][bj][m][n], 0, 0, 0); __builtin_amdgcn_s_setprio(0); } while (0)
; #define PG8_WAIT_V(n) asm volatile("s_waitcnt vmcnt(" #n ")" ::: "memory")
; #define PG8_WAIT_L(n) asm volatile("s_waitcnt lgkmcnt(" #n ")" ::: "memory")
; #define PG8_BAR __builtin_amdgcn_s_barrier()
; #define PG8_SCHED __builtin_amdgcn_sched_barrier(0)
; template <class Epi, class Sched, bool ALIGN_EPI = false, bool SP2 = false>
; __device__ __forceinline__ void gemm_phase(PG8_LAS unsigned char* lds, const Gemm g, const Sched& S, const Epi& E) {
;     ...
;             PG8_WAIT_V(8); PG8_WAIT_L(0); PG8_BAR; PG8_MMA(1, 0, At, B0); PG8_MMA(1, 1, At, B1); PG8_BAR; PG8_SCHED;
;             PG8_LDB(B0, 1, 0); PG8_LDB(B1, 1, 1); PG8_SCHED; PG8_LDA(At, 1, 0); PG8_STAGE(PG8_SA(0, 1), a2 + hstepA, voffA);
;             PG8_WAIT_V(8); PG8_WAIT_L(0); PG8_BAR; PG8_MMA(0, 0, At, B0); PG8_MMA(0, 1, At, B1); PG8_BAR; PG8_SCHED;
	v_mfma_f32_16x16x32_bf16 v[64:67], v[142:145], v[184:187], 0
	v_mfma_f32_16x16x32_bf16 v[64:67], v[152:155], v[188:191], v[64:67]
	v_mfma_f32_16x16x32_bf16 v[56:59], v[142:145], v[192:195], 0
	v_mfma_f32_16x16x32_bf16 v[56:59], v[152:155], v[196:199], v[56:59]
	v_mfma_f32_16x16x32_bf16 v[40:43], v[142:145], v[200:203], 0
	v_mfma_f32_16x16x32_bf16 v[40:43], v[152:155], v[204:207], v[40:43]
	v_mfma_f32_16x16x32_bf16 v[24:27], v[142:145], v[208:211], 0
	v_mfma_f32_16x16x32_bf16 v[24:27], v[152:155], v[226:229], v[24:27]
	v_mfma_f32_16x16x32_bf16 v[60:63], v[156:159], v[184:187], 0
	v_mfma_f32_16x16x32_bf16 v[60:63], v[160:163], v[188:191], v[60:63]
	v_mfma_f32_16x16x32_bf16 v[48:51], v[156:159], v[192:195], 0
	v_mfma_f32_16x16x32_bf16 v[48:51], v[160:163], v[196:199], v[48:51]
	v_mfma_f32_16x16x32_bf16 v[32:35], v[156:159], v[200:203], 0
	v_mfma_f32_16x16x32_bf16 v[32:35], v[160:163], v[204:207], v[32:35]
	v_mfma_f32_16x16x32_bf16 v[16:19], v[156:159], v[208:211], 0
	v_mfma_f32_16x16x32_bf16 v[16:19], v[160:163], v[226:229], v[16:19]
	v_mfma_f32_16x16x32_bf16 v[52:55], v[164:167], v[184:187], 0
	v_mfma_f32_16x16x32_bf16 v[52:55], v[172:175], v[188:191], v[52:55]
	v_mfma_f32_16x16x32_bf16 v[36:39], v[164:167], v[192:195], 0
	v_mfma_f32_16x16x32_bf16 v[36:39], v[172:175], v[196:199], v[36:39]
	v_mfma_f32_16x16x32_bf16 v[20:23], v[164:167], v[200:203], 0
	v_mfma_f32_16x16x32_bf16 v[20:23], v[172:175], v[204:207], v[20:23]
	v_mfma_f32_16x16x32_bf16 v[8:11], v[164:167], v[208:211], 0
	v_mfma_f32_16x16x32_bf16 v[8:11], v[172:175], v[226:229], v[8:11]
	v_mfma_f32_16x16x32_bf16 v[44:47], v[176:179], v[184:187], 0
	v_mfma_f32_16x16x32_bf16 v[44:47], v[180:183], v[188:191], v[44:47]
	v_mfma_f32_16x16x32_bf16 v[28:31], v[176:179], v[192:195], 0
	v_mfma_f32_16x16x32_bf16 v[28:31], v[180:183], v[196:199], v[28:31]
	v_mfma_f32_16x16x32_bf16 v[12:15], v[176:179], v[200:203], 0
	v_mfma_f32_16x16x32_bf16 v[12:15], v[180:183], v[204:207], v[12:15]
	v_mfma_f32_16x16x32_bf16 v[4:7], v[176:179], v[208:211], 0
	v_mfma_f32_16x16x32_bf16 v[4:7], v[180:183], v[226:229], v[4:7]
	s_barrier
	s_add_i32 s45, 0, 0x18000
	v_add_u32_e32 v142, s45, v147
	v_add_u32_e32 v151, s45, v148
	ds_read_b128 v[142:145], v142
	ds_read_b128 v[152:155], v151
	v_add_u32_e32 v151, s51, v147
	v_add_u32_e32 v160, s51, v148
	s_add_i32 s46, 0, 0x1c000
	ds_read_b128 v[156:159], v151
	ds_read_b128 v[160:163], v160
	v_add_u32_e32 v151, s46, v147
	v_add_u32_e32 v168, s46, v148
	ds_read_b128 v[164:167], v151
	ds_read_b128 v[172:175], v168
	v_add_u32_e32 v151, s52, v147
	v_add_u32_e32 v168, s52, v148
	ds_read_b128 v[176:179], v151
	ds_read_b128 v[180:183], v168
	s_add_u32 s22, s22, 0x80000
	s_addc_u32 s23, s23, 0
	s_mov_b32 m0, s35
	v_lshl_add_u64 v[236:237], s[22:23], 0, v[136:137]
	ds_read_b128 v[184:187], v150 offset:32768
	ds_read_b128 v[188:191], v150 offset:33792
	ds_read_b128 v[192:195], v150 offset:34816
	ds_read_b128 v[196:199], v150 offset:35840
	ds_read_b128 v[200:203], v150 offset:36864
	ds_read_b128 v[204:207], v150 offset:37888
	ds_read_b128 v[208:211], v150 offset:38912
	ds_read_b128 v[226:229], v150 offset:39936
	global_load_lds_dwordx4 v[236:237], off
	v_lshl_add_u64 v[236:237], s[22:23], 0, v[134:135]
	s_mov_b32 m0, s36
	s_nop 0
	global_load_lds_dwordx4 v[236:237], off
	s_waitcnt vmcnt(8)
	s_waitcnt lgkmcnt(0)
	s_barrier
	v_mfma_f32_16x16x32_bf16 v[128:131], v[142:145], v[184:187], v[128:131]
	v_mfma_f32_16x16x32_bf16 v[128:131], v[152:155], v[188:191], v[128:131]
	v_mfma_f32_16x16x32_bf16 v[120:123], v[142:145], v[192:195], v[120:123]
	v_mfma_f32_16x16x32_bf16 v[120:123], v[152:155], v[196:199], v[120:123]
	v_mfma_f32_16x16x32_bf16 v[104:107], v[142:145], v[200:203], v[104:107]
	v_mfma_f32_16x16x32_bf16 v[104:107], v[152:155], v[204:207], v[104:107]
	v_mfma_f32_16x16x32_bf16 v[88:91], v[142:145], v[208:211], v[88:91]
	v_mfma_f32_16x16x32_bf16 v[88:91], v[152:155], v[226:229], v[88:91]
	v_mfma_f32_16x16x32_bf16 v[124:127], v[156:159], v[184:187], v[124:127]
	v_mfma_f32_16x16x32_bf16 v[124:127], v[160:163], v[188:191], v[124:127]
	v_mfma_f32_16x16x32_bf16 v[112:115], v[156:159], v[192:195], v[112:115]
	v_mfma_f32_16x16x32_bf16 v[112:115], v[160:163], v[196:199], v[112:115]
	v_mfma_f32_16x16x32_bf16 v[96:99], v[156:159], v[200:203], v[96:99]
	v_mfma_f32_16x16x32_bf16 v[96:99], v[160:163], v[204:207], v[96:99]
	v_mfma_f32_16x16x32_bf16 v[80:83], v[156:159], v[208:211], v[80:83]
	v_mfma_f32_16x16x32_bf16 v[80:83], v[160:163], v[226:229], v[80:83]
	v_mfma_f32_16x16x32_bf16 v[116:119], v[164:167], v[184:187], v[116:119]
	v_mfma_f32_16x16x32_bf16 v[116:119], v[172:175], v[188:191], v[116:119]
	v_mfma_f32_16x16x32_bf16 v[100:103], v[164:167], v[192:195], v[100:103]
	v_mfma_f32_16x16x32_bf16 v[100:103], v[172:175], v[196:199], v[100:103]
	v_mfma_f32_16x16x32_bf16 v[84:87], v[164:167], v[200:203], v[84:87]
	v_mfma_f32_16x16x32_bf16 v[84:87], v[172:175], v[204:207], v[84:87]
	v_mfma_f32_16x16x32_bf16 v[72:75], v[164:167], v[208:211], v[72:75]
	v_mfma_f32_16x16x32_bf16 v[72:75], v[172:175], v[226:229], v[72:75]
	v_mfma_f32_16x16x32_bf16 v[108:111], v[176:179], v[184:187], v[108:111]
	v_mfma_f32_16x16x32_bf16 v[108:111], v[180:183], v[188:191], v[108:111]
	v_mfma_f32_16x16x32_bf16 v[92:95], v[176:179], v[192:195], v[92:95]
	v_mfma_f32_16x16x32_bf16 v[92:95], v[180:183], v[196:199], v[92:95]
	v_mfma_f32_16x16x32_bf16 v[76:79], v[176:179], v[200:203], v[76:79]
	v_mfma_f32_16x16x32_bf16 v[76:79], v[180:183], v[204:207], v[76:79]
	v_mfma_f32_16x16x32_bf16 v[68:71], v[176:179], v[208:211], v[68:71]
	v_mfma_f32_16x16x32_bf16 v[68:71], v[180:183], v[226:229], v[68:71]
	s_barrier
; #define PG8_STAGE(bufoff, gbase, voff) do { _Pragma("unroll") for (int _i = 0; _i < 2; ++_i) \
;         __builtin_amdgcn_global_load_lds((const unsigned*)((const char*)(gbase) + (voff)[_i]), (PG8_LAS unsigned*)(lds + (bufoff) + ldsw + _i * 8192), 16, 0, 0); } while (0)
; #define PG8_LDA(dst, b, h) do { _Pragma("unroll") for (int m = 0; m < 4; ++m) _Pragma("unroll") for (int k = 0; k < 2; ++k) dst[m][k] = *(const PG8_LAS bf16x8*)(lds + PG8_SA(b, h) + aoffk[k] + m * 2048); } while (0)
; #define PG8_MMA(ai, bj, At, Bt) do { __builtin_amdgcn_s_setprio(1); _Pragma("unroll") for (int m = 0; m < 4; ++m) _Pragma("unroll") for (int n = 0; n < 2; ++n) _Pragma("unroll") for (int k = 0; k < 2; ++k) \
;         acc[ai][bj][m][n] = __builtin_amdgcn_mfma_f32_16x16x32_bf16(Bt[n][k], At[m][k], acc[ai][bj][m][n], 0, 0, 0); __builtin_amdgcn_s_setprio(0); } while (0)
; #define PG8_WAIT_V(n) asm volatile("s_waitcnt vmcnt(" #n ")" ::: "memory")
; #define PG8_WAIT_L(n) asm volatile("s_waitcnt lgkmcnt(" #n ")" ::: "memory")
; #define PG8_BAR __builtin_amdgcn_s_barrier()
; #define PG8_SCHED __builtin_amdgcn_sched_barrier(0)
; template <class Epi, class Sched, bool ALIGN_EPI = false, bool SP2 = false>
; __device__ __forceinline__ void gemm_phase(PG8_LAS unsigned char* lds, const Gemm g, const Sched& S, const Epi& E) {
;     ...
;         for (int t = 0; t < nt; t += 2) {
;             const bool last = (t == nt - 2);
;             const char* a1 = cA + (size_t)(t + 1) * kstep;
;             const char* a2 = last ? nA : cA + (size_t)(t + 2) * kstep; const char* b2 = last ? nB : cB + (size_t)(t + 2) * kstep;
;             const char* a3 = a2 + kstep; const char* b3 = b2 + kstep;
;             if (last && has_next) S.a_ready(nxt);
;     ...
;             PG8_LDA(At, 1, 1); PG8_STAGE(PG8_SB(1, 0), b3, voffB); PG8_STAGE(PG8_SB(1, 1), b3 + hstepB, voffB); PG8_STAGE(PG8_SA(1, 0), a3, voffA);
;             PG8_WAIT_V(8); PG8_WAIT_L(0); PG8_BAR; PG8_MMA(1, 0, At, B0); PG8_MMA(1, 1, At, B1); PG8_BAR; PG8_SCHED;
	s_add_i32 s22, s45, s30
	v_lshl_add_u64 v[212:213], v[212:213], 0, s[56:57]
	s_mov_b32 m0, s22
	ds_read_b128 v[184:187], v150 offset:49152
	ds_read_b128 v[188:191], v150 offset:50176
	ds_read_b128 v[192:195], v150 offset:51200
	ds_read_b128 v[196:199], v150 offset:52224
	ds_read_b128 v[200:203], v150 offset:53248
	ds_read_b128 v[204:207], v150 offset:54272
	ds_read_b128 v[208:211], v150 offset:55296
	ds_read_b128 v[226:229], v150 offset:56320
	global_load_lds_dwordx4 v[212:213], off
	s_add_i32 m0, s22, 0x2000
	s_add_u32 s20, s20, 0x80080
	v_lshl_add_u64 v[212:213], v[230:231], 0, s[56:57]
	s_addc_u32 s21, s21, 0
	s_add_i32 s22, s46, s30
	global_load_lds_dwordx4 v[212:213], off
	v_lshl_add_u64 v[212:213], s[20:21], 0, v[2:3]
	s_mov_b32 m0, s22
	s_nop 0
	global_load_lds_dwordx4 v[212:213], off
	v_lshl_add_u64 v[212:213], s[20:21], 0, v[132:133]
	s_add_i32 m0, s22, 0x2000
	s_nop 0
	global_load_lds_dwordx4 v[212:213], off
	v_lshl_add_u64 v[212:213], v[232:233], 0, s[56:57]
	s_mov_b32 m0, s37
	s_nop 0
	global_load_lds_dwordx4 v[212:213], off
	v_lshl_add_u64 v[212:213], v[234:235], 0, s[56:57]
	s_mov_b32 m0, s38
	s_nop 0
	global_load_lds_dwordx4 v[212:213], off
	s_waitcnt vmcnt(8)
	s_waitcnt lgkmcnt(0)
	s_barrier
	v_mfma_f32_16x16x32_bf16 v[64:67], v[142:145], v[184:187], v[64:67]
	v_mfma_f32_16x16x32_bf16 v[64:67], v[152:155], v[188:191], v[64:67]
	v_mfma_f32_16x16x32_bf16 v[56:59], v[142:145], v[192:195], v[56:59]
	v_mfma_f32_16x16x32_bf16 v[56:59], v[152:155], v[196:199], v[56:59]
	v_mfma_f32_16x16x32_bf16 v[40:43], v[142:145], v[200:203], v[40:43]
	v_mfma_f32_16x16x32_bf16 v[40:43], v[152:155], v[204:207], v[40:43]
	v_mfma_f32_16x16x32_bf16 v[24:27], v[142:145], v[208:211], v[24:27]
	v_mfma_f32_16x16x32_bf16 v[24:27], v[152:155], v[226:229], v[24:27]
	v_mfma_f32_16x16x32_bf16 v[60:63], v[156:159], v[184:187], v[60:63]
	v_mfma_f32_16x16x32_bf16 v[60:63], v[160:163], v[188:191], v[60:63]
	v_mfma_f32_16x16x32_bf16 v[48:51], v[156:159], v[192:195], v[48:51]
	v_mfma_f32_16x16x32_bf16 v[48:51], v[160:163], v[196:199], v[48:51]
	v_mfma_f32_16x16x32_bf16 v[32:35], v[156:159], v[200:203], v[32:35]
	v_mfma_f32_16x16x32_bf16 v[32:35], v[160:163], v[204:207], v[32:35]
	v_mfma_f32_16x16x32_bf16 v[16:19], v[156:159], v[208:211], v[16:19]
	v_mfma_f32_16x16x32_bf16 v[16:19], v[160:163], v[226:229], v[16:19]
	v_mfma_f32_16x16x32_bf16 v[52:55], v[164:167], v[184:187], v[52:55]
	v_mfma_f32_16x16x32_bf16 v[52:55], v[172:175], v[188:191], v[52:55]
	v_mfma_f32_16x16x32_bf16 v[36:39], v[164:167], v[192:195], v[36:39]
	v_mfma_f32_16x16x32_bf16 v[36:39], v[172:175], v[196:199], v[36:39]
	v_mfma_f32_16x16x32_bf16 v[20:23], v[164:167], v[200:203], v[20:23]
	v_mfma_f32_16x16x32_bf16 v[20:23], v[172:175], v[204:207], v[20:23]
	v_mfma_f32_16x16x32_bf16 v[8:11], v[164:167], v[208:211], v[8:11]
	v_mfma_f32_16x16x32_bf16 v[8:11], v[172:175], v[226:229], v[8:11]
	v_mfma_f32_16x16x32_bf16 v[44:47], v[176:179], v[184:187], v[44:47]
	v_mfma_f32_16x16x32_bf16 v[44:47], v[180:183], v[188:191], v[44:47]
	v_mfma_f32_16x16x32_bf16 v[28:31], v[176:179], v[192:195], v[28:31]
	v_mfma_f32_16x16x32_bf16 v[28:31], v[180:183], v[196:199], v[28:31]
	v_mfma_f32_16x16x32_bf16 v[12:15], v[176:179], v[200:203], v[12:15]
	v_mfma_f32_16x16x32_bf16 v[12:15], v[180:183], v[204:207], v[12:15]
	v_mfma_f32_16x16x32_bf16 v[4:7], v[176:179], v[208:211], v[4:7]
	v_mfma_f32_16x16x32_bf16 v[4:7], v[180:183], v[226:229], v[4:7]
	s_barrier
	s_add_i32 s44, s44, 2
	s_add_u32 s18, s18, 0x100
	s_addc_u32 s19, s19, 0
	s_add_u32 s42, s42, 0x100
	s_addc_u32 s43, s43, 0
	s_cmp_gt_u32 s44, 29
	s_cbranch_scc0 .LBB0_663
	s_branch .Lgemm_after_2
.LBB0_663:
	s_add_u32 s20, s18, 0xfff80080
	s_addc_u32 s21, s19, -1
	s_add_i32 s45, 0, 0x10000
	s_cmp_eq_u32 s44, 28
	v_add_u32_e32 v142, s45, v147
	v_add_u32_e32 v151, s45, v148
	s_cselect_b32 s23, s9, s21
	s_cselect_b32 s22, s40, s20
	ds_read_b128 v[142:145], v142
	ds_read_b128 v[152:155], v151
	v_add_u32_e32 v151, s49, v147
	v_add_u32_e32 v160, s49, v148
	s_cselect_b32 s21, s7, s43
	s_cselect_b32 s20, s41, s42
	s_add_i32 s48, 0, 0x14000
	ds_read_b128 v[156:159], v151
	ds_read_b128 v[160:163], v160
	v_add_u32_e32 v151, s48, v147
	v_add_u32_e32 v168, s48, v148
	ds_read_b128 v[164:167], v151
	ds_read_b128 v[172:175], v168
	v_add_u32_e32 v151, s50, v147
	v_add_u32_e32 v168, s50, v148
	ds_read_b128 v[176:179], v151
	ds_read_b128 v[180:183], v168
	v_lshl_add_u64 v[212:213], s[18:19], 0, v[138:139]
	s_add_i32 m0, s33, 0xc000
	ds_read_b128 v[184:187], v150
	ds_read_b128 v[188:191], v150 offset:1024
	ds_read_b128 v[192:195], v150 offset:2048
	ds_read_b128 v[196:199], v150 offset:3072
	ds_read_b128 v[200:203], v150 offset:4096
	ds_read_b128 v[204:207], v150 offset:5120
	ds_read_b128 v[208:211], v150 offset:6144
	ds_read_b128 v[226:229], v150 offset:7168
	global_load_lds_dwordx4 v[212:213], off
	v_lshl_add_u64 v[212:213], s[18:19], 0, v[140:141]
	s_add_i32 m0, s33, 0xe000
	s_nop 0
	global_load_lds_dwordx4 v[212:213], off
	s_waitcnt vmcnt(8)
	s_waitcnt lgkmcnt(0)
	s_barrier
; #define PG8_STAGE(bufoff, gbase, voff) do { _Pragma("unroll") for (int _i = 0; _i < 2; ++_i) \
;         __builtin_amdgcn_global_load_lds((const unsigned*)((const char*)(gbase) + (voff)[_i]), (PG8_LAS unsigned*)(lds + (bufoff) + ldsw + _i * 8192), 16, 0, 0); } while (0)
; #define PG8_LDA(dst, b, h) do { _Pragma("unroll") for (int m = 0; m < 4; ++m) _Pragma("unroll") for (int k = 0; k < 2; ++k) dst[m][k] = *(const PG8_LAS bf16x8*)(lds + PG8_SA(b, h) + aoffk[k] + m * 2048); } while (0)
; #define PG8_MMA(ai, bj, At, Bt) do { __builtin_amdgcn_s_setprio(1); _Pragma("unroll") for (int m = 0; m < 4; ++m) _Pragma("unroll") for (int n = 0; n < 2; ++n) _Pragma("unroll") for (int k = 0; k < 2; ++k) \
;         acc[ai][bj][m][n] = __builtin_amdgcn_mfma_f32_16x16x32_bf16(Bt[n][k], At[m][k], acc[ai][bj][m][n], 0, 0, 0); __builtin_amdgcn_s_setprio(0); } while (0)
; #define PG8_WAIT_V(n) asm volatile("s_waitcnt vmcnt(" #n ")" ::: "memory")
; #define PG8_WAIT_L(n) asm volatile("s_waitcnt lgkmcnt(" #n ")" ::: "memory")
; #define PG8_BAR __builtin_amdgcn_s_barrier()
; #define PG8_SCHED __builtin_amdgcn_sched_barrier(0)
; template <class Epi, class Sched, bool ALIGN_EPI = false, bool SP2 = false>
; __device__ __forceinline__ void gemm_phase(PG8_LAS unsigned char* lds, const Gemm g, const Sched& S, const Epi& E) {
;     ...
;             PG8_WAIT_V(8); PG8_WAIT_L(0); PG8_BAR; PG8_MMA(0, 0, At, B0); PG8_MMA(0, 1, At, B1); PG8_BAR; PG8_SCHED;
;             PG8_LDA(At, 0, 1); PG8_STAGE(PG8_SB(0, 0), b2, voffB); PG8_STAGE(PG8_SB(0, 1), b2 + hstepB, voffB); PG8_STAGE(PG8_SA(0, 0), a2, voffA);
;             PG8_WAIT_V(8); PG8_WAIT_L(0); PG8_BAR; PG8_MMA(1, 0, At, B0); PG8_MMA(1, 1, At, B1); PG8_BAR; PG8_SCHED;
	v_mfma_f32_16x16x32_bf16 v[128:131], v[142:145], v[184:187], v[128:131]
	v_mfma_f32_16x16x32_bf16 v[128:131], v[152:155], v[188:191], v[128:131]
	v_mfma_f32_16x16x32_bf16 v[120:123], v[142:145], v[192:195], v[120:123]
	v_mfma_f32_16x16x32_bf16 v[120:123], v[152:155], v[196:199], v[120:123]
	v_mfma_f32_16x16x32_bf16 v[104:107], v[142:145], v[200:203], v[104:107]
	v_mfma_f32_16x16x32_bf16 v[104:107], v[152:155], v[204:207], v[104:107]
	v_mfma_f32_16x16x32_bf16 v[88:91], v[142:145], v[208:211], v[88:91]
	v_mfma_f32_16x16x32_bf16 v[88:91], v[152:155], v[226:229], v[88:91]
	v_mfma_f32_16x16x32_bf16 v[124:127], v[156:159], v[184:187], v[124:127]
	v_mfma_f32_16x16x32_bf16 v[124:127], v[160:163], v[188:191], v[124:127]
	v_mfma_f32_16x16x32_bf16 v[112:115], v[156:159], v[192:195], v[112:115]
	v_mfma_f32_16x16x32_bf16 v[112:115], v[160:163], v[196:199], v[112:115]
	v_mfma_f32_16x16x32_bf16 v[96:99], v[156:159], v[200:203], v[96:99]
	v_mfma_f32_16x16x32_bf16 v[96:99], v[160:163], v[204:207], v[96:99]
	v_mfma_f32_16x16x32_bf16 v[80:83], v[156:159], v[208:211], v[80:83]
	v_mfma_f32_16x16x32_bf16 v[80:83], v[160:163], v[226:229], v[80:83]
	v_mfma_f32_16x16x32_bf16 v[116:119], v[164:167], v[184:187], v[116:119]
	v_mfma_f32_16x16x32_bf16 v[116:119], v[172:175], v[188:191], v[116:119]
	v_mfma_f32_16x16x32_bf16 v[100:103], v[164:167], v[192:195], v[100:103]
	v_mfma_f32_16x16x32_bf16 v[100:103], v[172:175], v[196:199], v[100:103]
	v_mfma_f32_16x16x32_bf16 v[84:87], v[164:167], v[200:203], v[84:87]
	v_mfma_f32_16x16x32_bf16 v[84:87], v[172:175], v[204:207], v[84:87]
	v_mfma_f32_16x16x32_bf16 v[72:75], v[164:167], v[208:211], v[72:75]
	v_mfma_f32_16x16x32_bf16 v[72:75], v[172:175], v[226:229], v[72:75]
	v_mfma_f32_16x16x32_bf16 v[108:111], v[176:179], v[184:187], v[108:111]
	v_mfma_f32_16x16x32_bf16 v[108:111], v[180:183], v[188:191], v[108:111]
	v_mfma_f32_16x16x32_bf16 v[92:95], v[176:179], v[192:195], v[92:95]
	v_mfma_f32_16x16x32_bf16 v[92:95], v[180:183], v[196:199], v[92:95]
	v_mfma_f32_16x16x32_bf16 v[76:79], v[176:179], v[200:203], v[76:79]
	v_mfma_f32_16x16x32_bf16 v[76:79], v[180:183], v[204:207], v[76:79]
	v_mfma_f32_16x16x32_bf16 v[68:71], v[176:179], v[208:211], v[68:71]
	v_mfma_f32_16x16x32_bf16 v[68:71], v[180:183], v[226:229], v[68:71]
	s_barrier
	s_add_i32 s45, s45, s30
	v_lshl_add_u64 v[212:213], s[20:21], 0, v[2:3]
	s_mov_b32 m0, s45
	ds_read_b128 v[184:187], v150 offset:16384
	ds_read_b128 v[188:191], v150 offset:17408
	ds_read_b128 v[192:195], v150 offset:18432
	ds_read_b128 v[196:199], v150 offset:19456
	ds_read_b128 v[200:203], v150 offset:20480
	ds_read_b128 v[204:207], v150 offset:21504
	ds_read_b128 v[208:211], v150 offset:22528
	ds_read_b128 v[226:229], v150 offset:23552
	global_load_lds_dwordx4 v[212:213], off
	s_add_i32 m0, s45, 0x2000
	s_add_u32 s46, s20, 0x80000
	v_lshl_add_u64 v[230:231], s[20:21], 0, v[132:133]
	s_addc_u32 s47, s21, 0
	s_add_i32 s45, s48, s30
	global_load_lds_dwordx4 v[230:231], off
	v_lshl_add_u64 v[232:233], s[46:47], 0, v[2:3]
	s_mov_b32 m0, s45
	v_lshl_add_u64 v[234:235], s[22:23], 0, v[134:135]
	global_load_lds_dwordx4 v[232:233], off
	v_lshl_add_u64 v[232:233], s[46:47], 0, v[132:133]
	s_add_i32 m0, s45, 0x2000
	s_nop 0
	global_load_lds_dwordx4 v[232:233], off
	v_lshl_add_u64 v[232:233], s[22:23], 0, v[136:137]
	s_mov_b32 m0, s33
	s_nop 0
	global_load_lds_dwordx4 v[232:233], off
	s_mov_b32 m0, s34
	s_nop 0
	global_load_lds_dwordx4 v[234:235], off
	s_waitcnt vmcnt(8)
	s_waitcnt lgkmcnt(0)
	s_barrier
	v_mfma_f32_16x16x32_bf16 v[64:67], v[142:145], v[184:187], v[64:67]
	v_mfma_f32_16x16x32_bf16 v[64:67], v[152:155], v[188:191], v[64:67]
	v_mfma_f32_16x16x32_bf16 v[56:59], v[142:145], v[192:195], v[56:59]
	v_mfma_f32_16x16x32_bf16 v[56:59], v[152:155], v[196:199], v[56:59]
	v_mfma_f32_16x16x32_bf16 v[40:43], v[142:145], v[200:203], v[40:43]
	v_mfma_f32_16x16x32_bf16 v[40:43], v[152:155], v[204:207], v[40:43]
	v_mfma_f32_16x16x32_bf16 v[24:27], v[142:145], v[208:211], v[24:27]
	v_mfma_f32_16x16x32_bf16 v[24:27], v[152:155], v[226:229], v[24:27]
	v_mfma_f32_16x16x32_bf16 v[60:63], v[156:159], v[184:187], v[60:63]
	v_mfma_f32_16x16x32_bf16 v[60:63], v[160:163], v[188:191], v[60:63]
	v_mfma_f32_16x16x32_bf16 v[48:51], v[156:159], v[192:195], v[48:51]
	v_mfma_f32_16x16x32_bf16 v[48:51], v[160:163], v[196:199], v[48:51]
	v_mfma_f32_16x16x32_bf16 v[32:35], v[156:159], v[200:203], v[32:35]
	v_mfma_f32_16x16x32_bf16 v[32:35], v[160:163], v[204:207], v[32:35]
	v_mfma_f32_16x16x32_bf16 v[16:19], v[156:159], v[208:211], v[16:19]
	v_mfma_f32_16x16x32_bf16 v[16:19], v[160:163], v[226:229], v[16:19]
	v_mfma_f32_16x16x32_bf16 v[52:55], v[164:167], v[184:187], v[52:55]
	v_mfma_f32_16x16x32_bf16 v[52:55], v[172:175], v[188:191], v[52:55]
	v_mfma_f32_16x16x32_bf16 v[36:39], v[164:167], v[192:195], v[36:39]
	v_mfma_f32_16x16x32_bf16 v[36:39], v[172:175], v[196:199], v[36:39]
	v_mfma_f32_16x16x32_bf16 v[20:23], v[164:167], v[200:203], v[20:23]
	v_mfma_f32_16x16x32_bf16 v[20:23], v[172:175], v[204:207], v[20:23]
	v_mfma_f32_16x16x32_bf16 v[8:11], v[164:167], v[208:211], v[8:11]
	v_mfma_f32_16x16x32_bf16 v[8:11], v[172:175], v[226:229], v[8:11]
	v_mfma_f32_16x16x32_bf16 v[44:47], v[176:179], v[184:187], v[44:47]
	v_mfma_f32_16x16x32_bf16 v[44:47], v[180:183], v[188:191], v[44:47]
	v_mfma_f32_16x16x32_bf16 v[28:31], v[176:179], v[192:195], v[28:31]
	v_mfma_f32_16x16x32_bf16 v[28:31], v[180:183], v[196:199], v[28:31]
	v_mfma_f32_16x16x32_bf16 v[12:15], v[176:179], v[200:203], v[12:15]
	v_mfma_f32_16x16x32_bf16 v[12:15], v[180:183], v[204:207], v[12:15]
	v_mfma_f32_16x16x32_bf16 v[4:7], v[176:179], v[208:211], v[4:7]
	v_mfma_f32_16x16x32_bf16 v[4:7], v[180:183], v[226:229], v[4:7]
	s_barrier
; #define PG8_STAGE(bufoff, gbase, voff) do { _Pragma("unroll") for (int _i = 0; _i < 2; ++_i) \
;         __builtin_amdgcn_global_load_lds((const unsigned*)((const char*)(gbase) + (voff)[_i]), (PG8_LAS unsigned*)(lds + (bufoff) + ldsw + _i * 8192), 16, 0, 0); } while (0)
; #define PG8_LDA(dst, b, h) do { _Pragma("unroll") for (int m = 0; m < 4; ++m) _Pragma("unroll") for (int k = 0; k < 2; ++k) dst[m][k] = *(const PG8_LAS bf16x8*)(lds + PG8_SA(b, h) + aoffk[k] + m * 2048); } while (0)
; #define PG8_LDB(dst, b, h) do { _Pragma("unroll") for (int n = 0; n < 2; ++n) _Pragma("unroll") for (int k = 0; k < 2; ++k) dst[n][k] = *(const PG8_LAS bf16x8*)(lds + PG8_SB(b, h) + boffk[k] + n * 2048); } while (0)
; #define PG8_MMA(ai, bj, At, Bt) do { __builtin_amdgcn_s_setprio(1); _Pragma("unroll") for (int m = 0; m < 4; ++m) _Pragma("unroll") for (int n = 0; n < 2; ++n) _Pragma("unroll") for (int k = 0; k < 2; ++k) \
;         acc[ai][bj][m][n] = __builtin_amdgcn_mfma_f32_16x16x32_bf16(Bt[n][k], At[m][k], acc[ai][bj][m][n], 0, 0, 0); __builtin_amdgcn_s_setprio(0); } while (0)
; #define PG8_WAIT_V(n) asm volatile("s_waitcnt vmcnt(" #n ")" ::: "memory")
; #define PG8_WAIT_L(n) asm volatile("s_waitcnt lgkmcnt(" #n ")" ::: "memory")
; #define PG8_BAR __builtin_amdgcn_s_barrier()
; #define PG8_SCHED __builtin_amdgcn_sched_barrier(0)
; template <class Epi, class Sched, bool ALIGN_EPI = false, bool SP2 = false>
; __device__ __forceinline__ void gemm_phase(PG8_LAS unsigned char* lds, const Gemm g, const Sched& S, const Epi& E) {
;     ...
;             PG8_LDB(B0, 1, 0); PG8_LDB(B1, 1, 1); PG8_SCHED; PG8_LDA(At, 1, 0); PG8_STAGE(PG8_SA(0, 1), a2 + hstepA, voffA);
;             PG8_WAIT_V(8); PG8_WAIT_L(0); PG8_BAR; PG8_MMA(0, 0, At, B0); PG8_MMA(0, 1, At, B1); PG8_BAR; PG8_SCHED;
	s_add_i32 s45, 0, 0x18000
	v_add_u32_e32 v142, s45, v147
	v_add_u32_e32 v151, s45, v148
	ds_read_b128 v[142:145], v142
	ds_read_b128 v[152:155], v151
	v_add_u32_e32 v151, s51, v147
	v_add_u32_e32 v160, s51, v148
	s_add_i32 s46, 0, 0x1c000
	ds_read_b128 v[156:159], v151
	ds_read_b128 v[160:163], v160
	v_add_u32_e32 v151, s46, v147
	v_add_u32_e32 v168, s46, v148
	ds_read_b128 v[164:167], v151
	ds_read_b128 v[172:175], v168
	v_add_u32_e32 v151, s52, v147
	v_add_u32_e32 v168, s52, v148
	ds_read_b128 v[176:179], v151
	ds_read_b128 v[180:183], v168
	s_add_u32 s22, s22, 0x80000
	s_addc_u32 s23, s23, 0
	s_mov_b32 m0, s35
	v_lshl_add_u64 v[236:237], s[22:23], 0, v[136:137]
	ds_read_b128 v[184:187], v150 offset:32768
	ds_read_b128 v[188:191], v150 offset:33792
	ds_read_b128 v[192:195], v150 offset:34816
	ds_read_b128 v[196:199], v150 offset:35840
	ds_read_b128 v[200:203], v150 offset:36864
	ds_read_b128 v[204:207], v150 offset:37888
	ds_read_b128 v[208:211], v150 offset:38912
	ds_read_b128 v[226:229], v150 offset:39936
	global_load_lds_dwordx4 v[236:237], off
	v_lshl_add_u64 v[236:237], s[22:23], 0, v[134:135]
	s_mov_b32 m0, s36
	s_nop 0
	global_load_lds_dwordx4 v[236:237], off
	s_waitcnt vmcnt(8)
	s_waitcnt lgkmcnt(0)
	s_barrier
	v_mfma_f32_16x16x32_bf16 v[128:131], v[142:145], v[184:187], v[128:131]
	v_mfma_f32_16x16x32_bf16 v[128:131], v[152:155], v[188:191], v[128:131]
	v_mfma_f32_16x16x32_bf16 v[120:123], v[142:145], v[192:195], v[120:123]
	v_mfma_f32_16x16x32_bf16 v[120:123], v[152:155], v[196:199], v[120:123]
	v_mfma_f32_16x16x32_bf16 v[104:107], v[142:145], v[200:203], v[104:107]
	v_mfma_f32_16x16x32_bf16 v[104:107], v[152:155], v[204:207], v[104:107]
	v_mfma_f32_16x16x32_bf16 v[88:91], v[142:145], v[208:211], v[88:91]
	v_mfma_f32_16x16x32_bf16 v[88:91], v[152:155], v[226:229], v[88:91]
	v_mfma_f32_16x16x32_bf16 v[124:127], v[156:159], v[184:187], v[124:127]
	v_mfma_f32_16x16x32_bf16 v[124:127], v[160:163], v[188:191], v[124:127]
	v_mfma_f32_16x16x32_bf16 v[112:115], v[156:159], v[192:195], v[112:115]
	v_mfma_f32_16x16x32_bf16 v[112:115], v[160:163], v[196:199], v[112:115]
	v_mfma_f32_16x16x32_bf16 v[96:99], v[156:159], v[200:203], v[96:99]
	v_mfma_f32_16x16x32_bf16 v[96:99], v[160:163], v[204:207], v[96:99]
	v_mfma_f32_16x16x32_bf16 v[80:83], v[156:159], v[208:211], v[80:83]
	v_mfma_f32_16x16x32_bf16 v[80:83], v[160:163], v[226:229], v[80:83]
	v_mfma_f32_16x16x32_bf16 v[116:119], v[164:167], v[184:187], v[116:119]
	v_mfma_f32_16x16x32_bf16 v[116:119], v[172:175], v[188:191], v[116:119]
	v_mfma_f32_16x16x32_bf16 v[100:103], v[164:167], v[192:195], v[100:103]
	v_mfma_f32_16x16x32_bf16 v[100:103], v[172:175], v[196:199], v[100:103]
	v_mfma_f32_16x16x32_bf16 v[84:87], v[164:167], v[200:203], v[84:87]
	v_mfma_f32_16x16x32_bf16 v[84:87], v[172:175], v[204:207], v[84:87]
	v_mfma_f32_16x16x32_bf16 v[72:75], v[164:167], v[208:211], v[72:75]
	v_mfma_f32_16x16x32_bf16 v[72:75], v[172:175], v[226:229], v[72:75]
	v_mfma_f32_16x16x32_bf16 v[108:111], v[176:179], v[184:187], v[108:111]
	v_mfma_f32_16x16x32_bf16 v[108:111], v[180:183], v[188:191], v[108:111]
	v_mfma_f32_16x16x32_bf16 v[92:95], v[176:179], v[192:195], v[92:95]
	v_mfma_f32_16x16x32_bf16 v[92:95], v[180:183], v[196:199], v[92:95]
	v_mfma_f32_16x16x32_bf16 v[76:79], v[176:179], v[200:203], v[76:79]
	v_mfma_f32_16x16x32_bf16 v[76:79], v[180:183], v[204:207], v[76:79]
	v_mfma_f32_16x16x32_bf16 v[68:71], v[176:179], v[208:211], v[68:71]
	v_mfma_f32_16x16x32_bf16 v[68:71], v[180:183], v[226:229], v[68:71]
	s_barrier
; #define PG8_STAGE(bufoff, gbase, voff) do { _Pragma("unroll") for (int _i = 0; _i < 2; ++_i) \
;         __builtin_amdgcn_global_load_lds((const unsigned*)((const char*)(gbase) + (voff)[_i]), (PG8_LAS unsigned*)(lds + (bufoff) + ldsw + _i * 8192), 16, 0, 0); } while (0)
; #define PG8_LDA(dst, b, h) do { _Pragma("unroll") for (int m = 0; m < 4; ++m) _Pragma("unroll") for (int k = 0; k < 2; ++k) dst[m][k] = *(const PG8_LAS bf16x8*)(lds + PG8_SA(b, h) + aoffk[k] + m * 2048); } while (0)
; #define PG8_MMA(ai, bj, At, Bt) do { __builtin_amdgcn_s_setprio(1); _Pragma("unroll") for (int m = 0; m < 4; ++m) _Pragma("unroll") for (int n = 0; n < 2; ++n) _Pragma("unroll") for (int k = 0; k < 2; ++k) \
;         acc[ai][bj][m][n] = __builtin_amdgcn_mfma_f32_16x16x32_bf16(Bt[n][k], At[m][k], acc[ai][bj][m][n], 0, 0, 0); __builtin_amdgcn_s_setprio(0); } while (0)
; #define PG8_WAIT_V(n) asm volatile("s_waitcnt vmcnt(" #n ")" ::: "memory")
; #define PG8_WAIT_L(n) asm volatile("s_waitcnt lgkmcnt(" #n ")" ::: "memory")
; #define PG8_BAR __builtin_amdgcn_s_barrier()
; #define PG8_SCHED __builtin_amdgcn_sched_barrier(0)
; template <class Epi, class Sched, bool ALIGN_EPI = false, bool SP2 = false>
; __device__ __forceinline__ void gemm_phase(PG8_LAS unsigned char* lds, const Gemm g, const Sched& S, const Epi& E) {
;     ...
;         for (int t = 0; t < nt; t += 2) {
;             const bool last = (t == nt - 2);
;             const char* a1 = cA + (size_t)(t + 1) * kstep;
;             const char* a2 = last ? nA : cA + (size_t)(t + 2) * kstep; const char* b2 = last ? nB : cB + (size_t)(t + 2) * kstep;
;             const char* a3 = a2 + kstep; const char* b3 = b2 + kstep;
;     ...
;             PG8_LDA(At, 1, 1); PG8_STAGE(PG8_SB(1, 0), b3, voffB); PG8_STAGE(PG8_SB(1, 1), b3 + hstepB, voffB); PG8_STAGE(PG8_SA(1, 0), a3, voffA);
;             PG8_WAIT_V(8); PG8_WAIT_L(0); PG8_BAR; PG8_MMA(1, 0, At, B0); PG8_MMA(1, 1, At, B1); PG8_BAR; PG8_SCHED;
	s_add_i32 s22, s45, s30
	v_lshl_add_u64 v[212:213], v[212:213], 0, s[56:57]
	s_mov_b32 m0, s22
	ds_read_b128 v[184:187], v150 offset:49152
	ds_read_b128 v[188:191], v150 offset:50176
	ds_read_b128 v[192:195], v150 offset:51200
	ds_read_b128 v[196:199], v150 offset:52224
	ds_read_b128 v[200:203], v150 offset:53248
	ds_read_b128 v[204:207], v150 offset:54272
	ds_read_b128 v[208:211], v150 offset:55296
	ds_read_b128 v[226:229], v150 offset:56320
	global_load_lds_dwordx4 v[212:213], off
	s_add_i32 m0, s22, 0x2000
	s_add_u32 s20, s20, 0x80080
	v_lshl_add_u64 v[212:213], v[230:231], 0, s[56:57]
	s_addc_u32 s21, s21, 0
	s_add_i32 s22, s46, s30
	global_load_lds_dwordx4 v[212:213], off
	v_lshl_add_u64 v[212:213], s[20:21], 0, v[2:3]
	s_mov_b32 m0, s22
	s_nop 0
	global_load_lds_dwordx4 v[212:213], off
	v_lshl_add_u64 v[212:213], s[20:21], 0, v[132:133]
	s_add_i32 m0, s22, 0x2000
	s_nop 0
	global_load_lds_dwordx4 v[212:213], off
	v_lshl_add_u64 v[212:213], v[232:233], 0, s[56:57]
	s_mov_b32 m0, s37
	s_nop 0
	global_load_lds_dwordx4 v[212:213], off
	v_lshl_add_u64 v[212:213], v[234:235], 0, s[56:57]
	s_mov_b32 m0, s38
	s_nop 0
	global_load_lds_dwordx4 v[212:213], off
	s_waitcnt vmcnt(8)
	s_waitcnt lgkmcnt(0)
	s_barrier
	v_mfma_f32_16x16x32_bf16 v[64:67], v[142:145], v[184:187], v[64:67]
	v_mfma_f32_16x16x32_bf16 v[64:67], v[152:155], v[188:191], v[64:67]
	v_mfma_f32_16x16x32_bf16 v[56:59], v[142:145], v[192:195], v[56:59]
	v_mfma_f32_16x16x32_bf16 v[56:59], v[152:155], v[196:199], v[56:59]
	v_mfma_f32_16x16x32_bf16 v[40:43], v[142:145], v[200:203], v[40:43]
	v_mfma_f32_16x16x32_bf16 v[40:43], v[152:155], v[204:207], v[40:43]
	v_mfma_f32_16x16x32_bf16 v[24:27], v[142:145], v[208:211], v[24:27]
	v_mfma_f32_16x16x32_bf16 v[24:27], v[152:155], v[226:229], v[24:27]
	v_mfma_f32_16x16x32_bf16 v[60:63], v[156:159], v[184:187], v[60:63]
	v_mfma_f32_16x16x32_bf16 v[60:63], v[160:163], v[188:191], v[60:63]
	v_mfma_f32_16x16x32_bf16 v[48:51], v[156:159], v[192:195], v[48:51]
	v_mfma_f32_16x16x32_bf16 v[48:51], v[160:163], v[196:199], v[48:51]
	v_mfma_f32_16x16x32_bf16 v[32:35], v[156:159], v[200:203], v[32:35]
	v_mfma_f32_16x16x32_bf16 v[32:35], v[160:163], v[204:207], v[32:35]
	v_mfma_f32_16x16x32_bf16 v[16:19], v[156:159], v[208:211], v[16:19]
	v_mfma_f32_16x16x32_bf16 v[16:19], v[160:163], v[226:229], v[16:19]
	v_mfma_f32_16x16x32_bf16 v[52:55], v[164:167], v[184:187], v[52:55]
	v_mfma_f32_16x16x32_bf16 v[52:55], v[172:175], v[188:191], v[52:55]
	v_mfma_f32_16x16x32_bf16 v[36:39], v[164:167], v[192:195], v[36:39]
	v_mfma_f32_16x16x32_bf16 v[36:39], v[172:175], v[196:199], v[36:39]
	v_mfma_f32_16x16x32_bf16 v[20:23], v[164:167], v[200:203], v[20:23]
	v_mfma_f32_16x16x32_bf16 v[20:23], v[172:175], v[204:207], v[20:23]
	v_mfma_f32_16x16x32_bf16 v[8:11], v[164:167], v[208:211], v[8:11]
	v_mfma_f32_16x16x32_bf16 v[8:11], v[172:175], v[226:229], v[8:11]
	v_mfma_f32_16x16x32_bf16 v[44:47], v[176:179], v[184:187], v[44:47]
	v_mfma_f32_16x16x32_bf16 v[44:47], v[180:183], v[188:191], v[44:47]
	v_mfma_f32_16x16x32_bf16 v[28:31], v[176:179], v[192:195], v[28:31]
	v_mfma_f32_16x16x32_bf16 v[28:31], v[180:183], v[196:199], v[28:31]
	v_mfma_f32_16x16x32_bf16 v[12:15], v[176:179], v[200:203], v[12:15]
	v_mfma_f32_16x16x32_bf16 v[12:15], v[180:183], v[204:207], v[12:15]
	v_mfma_f32_16x16x32_bf16 v[4:7], v[176:179], v[208:211], v[4:7]
	v_mfma_f32_16x16x32_bf16 v[4:7], v[180:183], v[226:229], v[4:7]
	s_barrier
	s_add_i32 s44, s44, 2
	s_add_u32 s18, s18, 0x100
	s_addc_u32 s19, s19, 0
	s_add_u32 s42, s42, 0x100
	s_addc_u32 s43, s43, 0
	s_cmp_gt_u32 s44, 29
	s_cbranch_scc0 .LBB0_663

; #define PG8_STAGE(bufoff, gbase, voff) do { _Pragma("unroll") for (int _i = 0; _i < 2; ++_i) \
;         __builtin_amdgcn_global_load_lds((const unsigned*)((const char*)(gbase) + (voff)[_i]), (PG8_LAS unsigned*)(lds + (bufoff) + ldsw + _i * 8192), 16, 0, 0); } while (0)
; #define PG8_LDA(dst, b, h) do { _Pragma("unroll") for (int m = 0; m < 4; ++m) _Pragma("unroll") for (int k = 0; k < 2; ++k) dst[m][k] = *(const PG8_LAS bf16x8*)(lds + PG8_SA(b, h) + aoffk[k] + m * 2048); } while (0)
; #define PG8_LDB(dst, b, h) do { _Pragma("unroll") for (int n = 0; n < 2; ++n) _Pragma("unroll") for (int k = 0; k < 2; ++k) dst[n][k] = *(const PG8_LAS bf16x8*)(lds + PG8_SB(b, h) + boffk[k] + n * 2048); } while (0)
; #define PG8_MMA(ai, bj, At, Bt) do { __builtin_amdgcn_s_setprio(1); _Pragma("unroll") for (int m = 0; m < 4; ++m) _Pragma("unroll") for (int n = 0; n < 2; ++n) _Pragma("unroll") for (int k = 0; k < 2; ++k) \
;         acc[ai][bj][m][n] = __builtin_amdgcn_mfma_f32_16x16x32_bf16(Bt[n][k], At[m][k], acc[ai][bj][m][n], 0, 0, 0); __builtin_amdgcn_s_setprio(0); } while (0)
; #define PG8_WAIT_V(n) asm volatile("s_waitcnt vmcnt(" #n ")" ::: "memory")
; #define PG8_WAIT_L(n) asm volatile("s_waitcnt lgkmcnt(" #n ")" ::: "memory")
; template <class Epi, class Sched, bool ALIGN_EPI = false, bool SP2 = false>
; __device__ __forceinline__ void gemm_phase(PG8_LAS unsigned char* lds, const Gemm g, const Sched& S, const Epi& E) {
;     ...
;         for (int t = 0; t < nt; t += 2) {
;             const bool last = (t == nt - 2);
;             const char* a1 = cA + (size_t)(t + 1) * kstep;
;             const char* a2 = last ? nA : cA + (size_t)(t + 2) * kstep; const char* b2 = last ? nB : cB + (size_t)(t + 2) * kstep;
;             const char* a3 = a2 + kstep; const char* b3 = b2 + kstep;
;             if (last && has_next) S.a_ready(nxt);
;             if constexpr (SP2) {
;             PG8_LDB(B0, 0, 0); PG8_LDB(B1, 0, 1); PG8_SCHED; PG8_LDA(At, 0, 0); PG8_STAGE(PG8_SA(1, 1), a1 + hstepA, voffA);
;             PG8_WAIT_V(8); PG8_WAIT_L(0); PG8_BAR; PG8_MMA(0, 0, At, B0); PG8_MMA(0, 1, At, B1); PG8_BAR; PG8_SCHED;
;             PG8_LDA(At, 0, 1); PG8_STAGE(PG8_SB(0, 0), b2, voffB); PG8_STAGE(PG8_SB(0, 1), b2 + hstepB, voffB); PG8_STAGE(PG8_SA(0, 0), a2, voffA);
;             PG8_WAIT_V(8); PG8_WAIT_L(0); PG8_BAR; PG8_MMA(1, 0, At, B0); PG8_MMA(1, 1, At, B1); PG8_BAR; PG8_SCHED;
.Lgemm_first_3:
	s_add_i32 s48, s22, 2
	s_add_u32 s23, s20, 0xfff80080
	s_addc_u32 s24, s21, -1
	s_add_i32 s49, 0, 0x10000
	s_cmp_eq_u32 s11, s22
	v_add_u32_e32 v142, s49, v145
	s_cselect_b32 s25, s17, s24
	s_cselect_b32 s24, s16, s23
	v_add_u32_e32 v143, s49, v146
	ds_read_b128 v[150:153], v142
	ds_read_b128 v[154:157], v143
	v_add_u32_e32 v142, s53, v145
	s_cselect_b32 s23, s19, s15
	s_cselect_b32 s22, s18, s13
	s_add_i32 s52, 0, 0x14000
	v_add_u32_e32 v143, s53, v146
	ds_read_b128 v[158:161], v142
	ds_read_b128 v[162:165], v143
	v_add_u32_e32 v142, s52, v145
	v_add_u32_e32 v143, s52, v146
	ds_read_b128 v[172:175], v142
	ds_read_b128 v[176:179], v143
	v_add_u32_e32 v142, s54, v145
	v_add_u32_e32 v143, s54, v146
	ds_read_b128 v[180:183], v142
	ds_read_b128 v[184:187], v143
	v_lshl_add_u64 v[142:143], s[20:21], 0, v[138:139]
	s_add_i32 m0, s5, 0xc000
	ds_read_b128 v[188:191], v148
	ds_read_b128 v[192:195], v148 offset:1024
	ds_read_b128 v[196:199], v148 offset:2048
	ds_read_b128 v[200:203], v148 offset:3072
	ds_read_b128 v[204:207], v148 offset:4096
	ds_read_b128 v[208:211], v148 offset:5120
	ds_read_b128 v[226:229], v148 offset:6144
	ds_read_b128 v[230:233], v148 offset:7168
	global_load_lds_dwordx4 v[142:143], off
	v_lshl_add_u64 v[142:143], s[20:21], 0, v[140:141]
	s_add_i32 m0, s5, 0xe000
	s_nop 0
	global_load_lds_dwordx4 v[142:143], off
	s_waitcnt vmcnt(8)
	s_waitcnt lgkmcnt(0)
	s_barrier
	v_mfma_f32_16x16x32_bf16 v[128:131], v[150:153], v[188:191], 0
	v_mfma_f32_16x16x32_bf16 v[128:131], v[154:157], v[192:195], v[128:131]
	v_mfma_f32_16x16x32_bf16 v[120:123], v[150:153], v[196:199], 0
	v_mfma_f32_16x16x32_bf16 v[120:123], v[154:157], v[200:203], v[120:123]
	v_mfma_f32_16x16x32_bf16 v[104:107], v[150:153], v[204:207], 0
	v_mfma_f32_16x16x32_bf16 v[104:107], v[154:157], v[208:211], v[104:107]
	v_mfma_f32_16x16x32_bf16 v[88:91], v[150:153], v[226:229], 0
	v_mfma_f32_16x16x32_bf16 v[88:91], v[154:157], v[230:233], v[88:91]
	v_mfma_f32_16x16x32_bf16 v[124:127], v[158:161], v[188:191], 0
	v_mfma_f32_16x16x32_bf16 v[124:127], v[162:165], v[192:195], v[124:127]
	v_mfma_f32_16x16x32_bf16 v[112:115], v[158:161], v[196:199], 0
	v_mfma_f32_16x16x32_bf16 v[112:115], v[162:165], v[200:203], v[112:115]
	v_mfma_f32_16x16x32_bf16 v[96:99], v[158:161], v[204:207], 0
	v_mfma_f32_16x16x32_bf16 v[96:99], v[162:165], v[208:211], v[96:99]
	v_mfma_f32_16x16x32_bf16 v[80:83], v[158:161], v[226:229], 0
	v_mfma_f32_16x16x32_bf16 v[80:83], v[162:165], v[230:233], v[80:83]
	v_mfma_f32_16x16x32_bf16 v[116:119], v[172:175], v[188:191], 0
	v_mfma_f32_16x16x32_bf16 v[116:119], v[176:179], v[192:195], v[116:119]
	v_mfma_f32_16x16x32_bf16 v[100:103], v[172:175], v[196:199], 0
	v_mfma_f32_16x16x32_bf16 v[100:103], v[176:179], v[200:203], v[100:103]
	v_mfma_f32_16x16x32_bf16 v[84:87], v[172:175], v[204:207], 0
	v_mfma_f32_16x16x32_bf16 v[84:87], v[176:179], v[208:211], v[84:87]
	v_mfma_f32_16x16x32_bf16 v[72:75], v[172:175], v[226:229], 0
	v_mfma_f32_16x16x32_bf16 v[72:75], v[176:179], v[230:233], v[72:75]
	v_mfma_f32_16x16x32_bf16 v[108:111], v[180:183], v[188:191], 0
	v_mfma_f32_16x16x32_bf16 v[108:111], v[184:187], v[192:195], v[108:111]
	v_mfma_f32_16x16x32_bf16 v[92:95], v[180:183], v[196:199], 0
	v_mfma_f32_16x16x32_bf16 v[92:95], v[184:187], v[200:203], v[92:95]
	v_mfma_f32_16x16x32_bf16 v[76:79], v[180:183], v[204:207], 0
	v_mfma_f32_16x16x32_bf16 v[76:79], v[184:187], v[208:211], v[76:79]
	v_mfma_f32_16x16x32_bf16 v[68:71], v[180:183], v[226:229], 0
	v_mfma_f32_16x16x32_bf16 v[68:71], v[184:187], v[230:233], v[68:71]
	s_barrier
	s_add_i32 s49, s49, s33
	v_lshl_add_u64 v[142:143], s[22:23], 0, v[2:3]
	s_mov_b32 m0, s49
	ds_read_b128 v[188:191], v148 offset:16384
	ds_read_b128 v[192:195], v148 offset:17408
	ds_read_b128 v[196:199], v148 offset:18432
	ds_read_b128 v[200:203], v148 offset:19456
	ds_read_b128 v[204:207], v148 offset:20480
	ds_read_b128 v[208:211], v148 offset:21504
	ds_read_b128 v[226:229], v148 offset:22528
	ds_read_b128 v[230:233], v148 offset:23552
	global_load_lds_dwordx4 v[142:143], off
	s_add_i32 m0, s49, 0x2000
	s_add_u32 s50, s22, 0x80000
	v_lshl_add_u64 v[166:167], s[22:23], 0, v[136:137]
	s_addc_u32 s51, s23, 0
	s_add_i32 s49, s52, s33
	global_load_lds_dwordx4 v[166:167], off
	v_lshl_add_u64 v[212:213], s[50:51], 0, v[2:3]
	s_mov_b32 m0, s49
	v_lshl_add_u64 v[220:221], s[24:25], 0, v[134:135]
	global_load_lds_dwordx4 v[212:213], off
	v_lshl_add_u64 v[212:213], s[50:51], 0, v[136:137]
	s_add_i32 m0, s49, 0x2000
	s_nop 0
	global_load_lds_dwordx4 v[212:213], off
	v_lshl_add_u64 v[212:213], s[24:25], 0, v[132:133]
	s_mov_b32 m0, s5
	s_nop 0
	global_load_lds_dwordx4 v[212:213], off
	s_mov_b32 m0, s7
	s_nop 0
	global_load_lds_dwordx4 v[220:221], off
	s_waitcnt vmcnt(8)
	s_waitcnt lgkmcnt(0)
	s_barrier
; #define PG8_STAGE(bufoff, gbase, voff) do { _Pragma("unroll") for (int _i = 0; _i < 2; ++_i) \
;         __builtin_amdgcn_global_load_lds((const unsigned*)((const char*)(gbase) + (voff)[_i]), (PG8_LAS unsigned*)(lds + (bufoff) + ldsw + _i * 8192), 16, 0, 0); } while (0)
; #define PG8_LDA(dst, b, h) do { _Pragma("unroll") for (int m = 0; m < 4; ++m) _Pragma("unroll") for (int k = 0; k < 2; ++k) dst[m][k] = *(const PG8_LAS bf16x8*)(lds + PG8_SA(b, h) + aoffk[k] + m * 2048); } while (0)
; #define PG8_LDB(dst, b, h) do { _Pragma("unroll") for (int n = 0; n < 2; ++n) _Pragma("unroll") for (int k = 0; k < 2; ++k) dst[n][k] = *(const PG8_LAS bf16x8*)(lds + PG8_SB(b, h) + boffk[k] + n * 2048); } while (0)
; #define PG8_MMA(ai, bj, At, Bt) do { __builtin_amdgcn_s_setprio(1); _Pragma("unroll") for (int m = 0; m < 4; ++m) _Pragma("unroll") for (int n = 0; n < 2; ++n) _Pragma("unroll") for (int k = 0; k < 2; ++k) \
;         acc[ai][bj][m][n] = __builtin_amdgcn_mfma_f32_16x16x32_bf16(Bt[n][k], At[m][k], acc[ai][bj][m][n], 0, 0, 0); __builtin_amdgcn_s_setprio(0); } while (0)
; #define PG8_WAIT_V(n) asm volatile("s_waitcnt vmcnt(" #n ")" ::: "memory")
; #define PG8_WAIT_L(n) asm volatile("s_waitcnt lgkmcnt(" #n ")" ::: "memory")
; #define PG8_BAR __builtin_amdgcn_s_barrier()
; #define PG8_SCHED __builtin_amdgcn_sched_barrier(0)
; template <class Epi, class Sched, bool ALIGN_EPI = false, bool SP2 = false>
; __device__ __forceinline__ void gemm_phase(PG8_LAS unsigned char* lds, const Gemm g, const Sched& S, const Epi& E) {
;     ...
;             PG8_WAIT_V(8); PG8_WAIT_L(0); PG8_BAR; PG8_MMA(1, 0, At, B0); PG8_MMA(1, 1, At, B1); PG8_BAR; PG8_SCHED;
;             PG8_LDB(B0, 1, 0); PG8_LDB(B1, 1, 1); PG8_SCHED; PG8_LDA(At, 1, 0); PG8_STAGE(PG8_SA(0, 1), a2 + hstepA, voffA);
;             PG8_WAIT_V(8); PG8_WAIT_L(0); PG8_BAR; PG8_MMA(0, 0, At, B0); PG8_MMA(0, 1, At, B1); PG8_BAR; PG8_SCHED;
	v_mfma_f32_16x16x32_bf16 v[64:67], v[150:153], v[188:191], 0
	v_mfma_f32_16x16x32_bf16 v[64:67], v[154:157], v[192:195], v[64:67]
	v_mfma_f32_16x16x32_bf16 v[56:59], v[150:153], v[196:199], 0
	v_mfma_f32_16x16x32_bf16 v[56:59], v[154:157], v[200:203], v[56:59]
	v_mfma_f32_16x16x32_bf16 v[40:43], v[150:153], v[204:207], 0
	v_mfma_f32_16x16x32_bf16 v[40:43], v[154:157], v[208:211], v[40:43]
	v_mfma_f32_16x16x32_bf16 v[24:27], v[150:153], v[226:229], 0
	v_mfma_f32_16x16x32_bf16 v[24:27], v[154:157], v[230:233], v[24:27]
	v_mfma_f32_16x16x32_bf16 v[60:63], v[158:161], v[188:191], 0
	v_mfma_f32_16x16x32_bf16 v[60:63], v[162:165], v[192:195], v[60:63]
	v_mfma_f32_16x16x32_bf16 v[48:51], v[158:161], v[196:199], 0
	v_mfma_f32_16x16x32_bf16 v[48:51], v[162:165], v[200:203], v[48:51]
	v_mfma_f32_16x16x32_bf16 v[32:35], v[158:161], v[204:207], 0
	v_mfma_f32_16x16x32_bf16 v[32:35], v[162:165], v[208:211], v[32:35]
	v_mfma_f32_16x16x32_bf16 v[16:19], v[158:161], v[226:229], 0
	v_mfma_f32_16x16x32_bf16 v[16:19], v[162:165], v[230:233], v[16:19]
	v_mfma_f32_16x16x32_bf16 v[52:55], v[172:175], v[188:191], 0
	v_mfma_f32_16x16x32_bf16 v[52:55], v[176:179], v[192:195], v[52:55]
	v_mfma_f32_16x16x32_bf16 v[36:39], v[172:175], v[196:199], 0
	v_mfma_f32_16x16x32_bf16 v[36:39], v[176:179], v[200:203], v[36:39]
	v_mfma_f32_16x16x32_bf16 v[20:23], v[172:175], v[204:207], 0
	v_mfma_f32_16x16x32_bf16 v[20:23], v[176:179], v[208:211], v[20:23]
	v_mfma_f32_16x16x32_bf16 v[8:11], v[172:175], v[226:229], 0
	v_mfma_f32_16x16x32_bf16 v[8:11], v[176:179], v[230:233], v[8:11]
	v_mfma_f32_16x16x32_bf16 v[44:47], v[180:183], v[188:191], 0
	v_mfma_f32_16x16x32_bf16 v[44:47], v[184:187], v[192:195], v[44:47]
	v_mfma_f32_16x16x32_bf16 v[28:31], v[180:183], v[196:199], 0
	v_mfma_f32_16x16x32_bf16 v[28:31], v[184:187], v[200:203], v[28:31]
	v_mfma_f32_16x16x32_bf16 v[12:15], v[180:183], v[204:207], 0
	v_mfma_f32_16x16x32_bf16 v[12:15], v[184:187], v[208:211], v[12:15]
	v_mfma_f32_16x16x32_bf16 v[4:7], v[180:183], v[226:229], 0
	v_mfma_f32_16x16x32_bf16 v[4:7], v[184:187], v[230:233], v[4:7]
	s_barrier
	s_add_i32 s49, 0, 0x18000
	v_add_u32_e32 v149, s49, v145
	v_add_u32_e32 v154, s49, v146
	ds_read_b128 v[150:153], v149
	ds_read_b128 v[154:157], v154
	v_add_u32_e32 v149, s55, v145
	v_add_u32_e32 v162, s55, v146
	s_add_i32 s50, 0, 0x1c000
	ds_read_b128 v[158:161], v149
	ds_read_b128 v[162:165], v162
	v_add_u32_e32 v149, s50, v145
	v_add_u32_e32 v168, s50, v146
	ds_read_b128 v[172:175], v149
	ds_read_b128 v[176:179], v168
	v_add_u32_e32 v149, s56, v145
	v_add_u32_e32 v168, s56, v146
	ds_read_b128 v[180:183], v149
	ds_read_b128 v[184:187], v168
	s_add_u32 s24, s24, 0x80000
	s_addc_u32 s25, s25, 0
	s_mov_b32 m0, s34
	v_lshl_add_u64 v[234:235], s[24:25], 0, v[132:133]
	ds_read_b128 v[188:191], v148 offset:32768
	ds_read_b128 v[192:195], v148 offset:33792
	ds_read_b128 v[196:199], v148 offset:34816
	ds_read_b128 v[200:203], v148 offset:35840
	ds_read_b128 v[204:207], v148 offset:36864
	ds_read_b128 v[208:211], v148 offset:37888
	ds_read_b128 v[226:229], v148 offset:38912
	ds_read_b128 v[230:233], v148 offset:39936
	global_load_lds_dwordx4 v[234:235], off
	v_lshl_add_u64 v[234:235], s[24:25], 0, v[134:135]
	s_mov_b32 m0, s35
	s_nop 0
	global_load_lds_dwordx4 v[234:235], off
	s_waitcnt vmcnt(8)
	s_waitcnt lgkmcnt(0)
	s_barrier
	v_mfma_f32_16x16x32_bf16 v[128:131], v[150:153], v[188:191], v[128:131]
	v_mfma_f32_16x16x32_bf16 v[128:131], v[154:157], v[192:195], v[128:131]
	v_mfma_f32_16x16x32_bf16 v[120:123], v[150:153], v[196:199], v[120:123]
	v_mfma_f32_16x16x32_bf16 v[120:123], v[154:157], v[200:203], v[120:123]
	v_mfma_f32_16x16x32_bf16 v[104:107], v[150:153], v[204:207], v[104:107]
	v_mfma_f32_16x16x32_bf16 v[104:107], v[154:157], v[208:211], v[104:107]
	v_mfma_f32_16x16x32_bf16 v[88:91], v[150:153], v[226:229], v[88:91]
	v_mfma_f32_16x16x32_bf16 v[88:91], v[154:157], v[230:233], v[88:91]
	v_mfma_f32_16x16x32_bf16 v[124:127], v[158:161], v[188:191], v[124:127]
	v_mfma_f32_16x16x32_bf16 v[124:127], v[162:165], v[192:195], v[124:127]
	v_mfma_f32_16x16x32_bf16 v[112:115], v[158:161], v[196:199], v[112:115]
	v_mfma_f32_16x16x32_bf16 v[112:115], v[162:165], v[200:203], v[112:115]
	v_mfma_f32_16x16x32_bf16 v[96:99], v[158:161], v[204:207], v[96:99]
	v_mfma_f32_16x16x32_bf16 v[96:99], v[162:165], v[208:211], v[96:99]
	v_mfma_f32_16x16x32_bf16 v[80:83], v[158:161], v[226:229], v[80:83]
	v_mfma_f32_16x16x32_bf16 v[80:83], v[162:165], v[230:233], v[80:83]
	v_mfma_f32_16x16x32_bf16 v[116:119], v[172:175], v[188:191], v[116:119]
	v_mfma_f32_16x16x32_bf16 v[116:119], v[176:179], v[192:195], v[116:119]
	v_mfma_f32_16x16x32_bf16 v[100:103], v[172:175], v[196:199], v[100:103]
	v_mfma_f32_16x16x32_bf16 v[100:103], v[176:179], v[200:203], v[100:103]
	v_mfma_f32_16x16x32_bf16 v[84:87], v[172:175], v[204:207], v[84:87]
	v_mfma_f32_16x16x32_bf16 v[84:87], v[176:179], v[208:211], v[84:87]
	v_mfma_f32_16x16x32_bf16 v[72:75], v[172:175], v[226:229], v[72:75]
	v_mfma_f32_16x16x32_bf16 v[72:75], v[176:179], v[230:233], v[72:75]
	v_mfma_f32_16x16x32_bf16 v[108:111], v[180:183], v[188:191], v[108:111]
	v_mfma_f32_16x16x32_bf16 v[108:111], v[184:187], v[192:195], v[108:111]
	v_mfma_f32_16x16x32_bf16 v[92:95], v[180:183], v[196:199], v[92:95]
	v_mfma_f32_16x16x32_bf16 v[92:95], v[184:187], v[200:203], v[92:95]
	v_mfma_f32_16x16x32_bf16 v[76:79], v[180:183], v[204:207], v[76:79]
	v_mfma_f32_16x16x32_bf16 v[76:79], v[184:187], v[208:211], v[76:79]
	v_mfma_f32_16x16x32_bf16 v[68:71], v[180:183], v[226:229], v[68:71]
	v_mfma_f32_16x16x32_bf16 v[68:71], v[184:187], v[230:233], v[68:71]
	s_barrier
; #define PG8_STAGE(bufoff, gbase, voff) do { _Pragma("unroll") for (int _i = 0; _i < 2; ++_i) \
;         __builtin_amdgcn_global_load_lds((const unsigned*)((const char*)(gbase) + (voff)[_i]), (PG8_LAS unsigned*)(lds + (bufoff) + ldsw + _i * 8192), 16, 0, 0); } while (0)
; #define PG8_LDA(dst, b, h) do { _Pragma("unroll") for (int m = 0; m < 4; ++m) _Pragma("unroll") for (int k = 0; k < 2; ++k) dst[m][k] = *(const PG8_LAS bf16x8*)(lds + PG8_SA(b, h) + aoffk[k] + m * 2048); } while (0)
; #define PG8_LDB(dst, b, h) do { _Pragma("unroll") for (int n = 0; n < 2; ++n) _Pragma("unroll") for (int k = 0; k < 2; ++k) dst[n][k] = *(const PG8_LAS bf16x8*)(lds + PG8_SB(b, h) + boffk[k] + n * 2048); } while (0)
; #define PG8_MMA(ai, bj, At, Bt) do { __builtin_amdgcn_s_setprio(1); _Pragma("unroll") for (int m = 0; m < 4; ++m) _Pragma("unroll") for (int n = 0; n < 2; ++n) _Pragma("unroll") for (int k = 0; k < 2; ++k) \
;         acc[ai][bj][m][n] = __builtin_amdgcn_mfma_f32_16x16x32_bf16(Bt[n][k], At[m][k], acc[ai][bj][m][n], 0, 0, 0); __builtin_amdgcn_s_setprio(0); } while (0)
; #define PG8_WAIT_V(n) asm volatile("s_waitcnt vmcnt(" #n ")" ::: "memory")
; #define PG8_WAIT_L(n) asm volatile("s_waitcnt lgkmcnt(" #n ")" ::: "memory")
; template <class Epi, class Sched, bool ALIGN_EPI = false, bool SP2 = false>
; __device__ __forceinline__ void gemm_phase(PG8_LAS unsigned char* lds, const Gemm g, const Sched& S, const Epi& E) {
;     ...
;         for (int t = 0; t < nt; t += 2) {
;             const bool last = (t == nt - 2);
;             const char* a1 = cA + (size_t)(t + 1) * kstep;
;             const char* a2 = last ? nA : cA + (size_t)(t + 2) * kstep; const char* b2 = last ? nB : cB + (size_t)(t + 2) * kstep;
;             const char* a3 = a2 + kstep; const char* b3 = b2 + kstep;
;             if (last && has_next) S.a_ready(nxt);
;             if constexpr (SP2) {
;             PG8_LDB(B0, 0, 0); PG8_LDB(B1, 0, 1); PG8_SCHED; PG8_LDA(At, 0, 0); PG8_STAGE(PG8_SA(1, 1), a1 + hstepA, voffA);
;             PG8_WAIT_V(8); PG8_WAIT_L(0); PG8_BAR; PG8_MMA(0, 0, At, B0); PG8_MMA(0, 1, At, B1); PG8_BAR; PG8_SCHED;
;     ...
;             PG8_LDA(At, 1, 1); PG8_STAGE(PG8_SB(1, 0), b3, voffB); PG8_STAGE(PG8_SB(1, 1), b3 + hstepB, voffB); PG8_STAGE(PG8_SA(1, 0), a3, voffA);
;             PG8_WAIT_V(8); PG8_WAIT_L(0); PG8_BAR; PG8_MMA(1, 0, At, B0); PG8_MMA(1, 1, At, B1); PG8_BAR; PG8_SCHED;
	s_add_i32 s24, s49, s33
	v_lshl_add_u64 v[142:143], v[142:143], 0, s[58:59]
	s_mov_b32 m0, s24
	ds_read_b128 v[188:191], v148 offset:49152
	ds_read_b128 v[192:195], v148 offset:50176
	ds_read_b128 v[196:199], v148 offset:51200
	ds_read_b128 v[200:203], v148 offset:52224
	ds_read_b128 v[204:207], v148 offset:53248
	ds_read_b128 v[208:211], v148 offset:54272
	ds_read_b128 v[226:229], v148 offset:55296
	ds_read_b128 v[230:233], v148 offset:56320
	global_load_lds_dwordx4 v[142:143], off
	s_add_i32 m0, s24, 0x2000
	s_add_u32 s22, s22, 0x80080
	v_lshl_add_u64 v[142:143], v[166:167], 0, s[58:59]
	s_addc_u32 s23, s23, 0
	s_add_i32 s24, s50, s33
	global_load_lds_dwordx4 v[142:143], off
	v_lshl_add_u64 v[142:143], s[22:23], 0, v[2:3]
	s_mov_b32 m0, s24
	s_nop 0
	global_load_lds_dwordx4 v[142:143], off
	v_lshl_add_u64 v[142:143], s[22:23], 0, v[136:137]
	s_add_i32 m0, s24, 0x2000
	s_nop 0
	global_load_lds_dwordx4 v[142:143], off
	v_lshl_add_u64 v[142:143], v[212:213], 0, s[58:59]
	s_mov_b32 m0, s40
	s_nop 0
	global_load_lds_dwordx4 v[142:143], off
	v_lshl_add_u64 v[142:143], v[220:221], 0, s[58:59]
	s_mov_b32 m0, s41
	s_nop 0
	global_load_lds_dwordx4 v[142:143], off
	s_waitcnt vmcnt(8)
	s_waitcnt lgkmcnt(0)
	s_barrier
	v_mfma_f32_16x16x32_bf16 v[64:67], v[150:153], v[188:191], v[64:67]
	v_mfma_f32_16x16x32_bf16 v[64:67], v[154:157], v[192:195], v[64:67]
	v_mfma_f32_16x16x32_bf16 v[56:59], v[150:153], v[196:199], v[56:59]
	v_mfma_f32_16x16x32_bf16 v[56:59], v[154:157], v[200:203], v[56:59]
	v_mfma_f32_16x16x32_bf16 v[40:43], v[150:153], v[204:207], v[40:43]
	v_mfma_f32_16x16x32_bf16 v[40:43], v[154:157], v[208:211], v[40:43]
	v_mfma_f32_16x16x32_bf16 v[24:27], v[150:153], v[226:229], v[24:27]
	v_mfma_f32_16x16x32_bf16 v[24:27], v[154:157], v[230:233], v[24:27]
	v_mfma_f32_16x16x32_bf16 v[60:63], v[158:161], v[188:191], v[60:63]
	v_mfma_f32_16x16x32_bf16 v[60:63], v[162:165], v[192:195], v[60:63]
	v_mfma_f32_16x16x32_bf16 v[48:51], v[158:161], v[196:199], v[48:51]
	v_mfma_f32_16x16x32_bf16 v[48:51], v[162:165], v[200:203], v[48:51]
	v_mfma_f32_16x16x32_bf16 v[32:35], v[158:161], v[204:207], v[32:35]
	v_mfma_f32_16x16x32_bf16 v[32:35], v[162:165], v[208:211], v[32:35]
	v_mfma_f32_16x16x32_bf16 v[16:19], v[158:161], v[226:229], v[16:19]
	v_mfma_f32_16x16x32_bf16 v[16:19], v[162:165], v[230:233], v[16:19]
	v_mfma_f32_16x16x32_bf16 v[52:55], v[172:175], v[188:191], v[52:55]
	v_mfma_f32_16x16x32_bf16 v[52:55], v[176:179], v[192:195], v[52:55]
	v_mfma_f32_16x16x32_bf16 v[36:39], v[172:175], v[196:199], v[36:39]
	v_mfma_f32_16x16x32_bf16 v[36:39], v[176:179], v[200:203], v[36:39]
	v_mfma_f32_16x16x32_bf16 v[20:23], v[172:175], v[204:207], v[20:23]
	v_mfma_f32_16x16x32_bf16 v[20:23], v[176:179], v[208:211], v[20:23]
	v_mfma_f32_16x16x32_bf16 v[8:11], v[172:175], v[226:229], v[8:11]
	v_mfma_f32_16x16x32_bf16 v[8:11], v[176:179], v[230:233], v[8:11]
	v_mfma_f32_16x16x32_bf16 v[44:47], v[180:183], v[188:191], v[44:47]
	v_mfma_f32_16x16x32_bf16 v[44:47], v[184:187], v[192:195], v[44:47]
	v_mfma_f32_16x16x32_bf16 v[28:31], v[180:183], v[196:199], v[28:31]
	v_mfma_f32_16x16x32_bf16 v[28:31], v[184:187], v[200:203], v[28:31]
	v_mfma_f32_16x16x32_bf16 v[12:15], v[180:183], v[204:207], v[12:15]
	v_mfma_f32_16x16x32_bf16 v[12:15], v[184:187], v[208:211], v[12:15]
	v_mfma_f32_16x16x32_bf16 v[4:7], v[180:183], v[226:229], v[4:7]
	v_mfma_f32_16x16x32_bf16 v[4:7], v[184:187], v[230:233], v[4:7]
	s_barrier
	s_add_u32 s20, s20, 0x100
	s_addc_u32 s21, s21, 0
	s_add_u32 s13, s13, 0x100
	s_addc_u32 s15, s15, 0
	s_cmp_ge_i32 s48, s45
	s_mov_b32 s22, s48
	s_cbranch_scc0 .LBB0_1293
	s_branch .Lgemm_after_3
.LBB0_1293:
	s_add_i32 s48, s22, 2
	s_add_u32 s23, s20, 0xfff80080
	s_addc_u32 s24, s21, -1
	s_add_i32 s49, 0, 0x10000
	s_cmp_eq_u32 s11, s22
	v_add_u32_e32 v142, s49, v145
	s_cselect_b32 s25, s17, s24
	s_cselect_b32 s24, s16, s23
	v_add_u32_e32 v143, s49, v146
	ds_read_b128 v[150:153], v142
	ds_read_b128 v[154:157], v143
	v_add_u32_e32 v142, s53, v145
	s_cselect_b32 s23, s19, s15
	s_cselect_b32 s22, s18, s13
	s_add_i32 s52, 0, 0x14000
	v_add_u32_e32 v143, s53, v146
	ds_read_b128 v[158:161], v142
	ds_read_b128 v[162:165], v143
	v_add_u32_e32 v142, s52, v145
	v_add_u32_e32 v143, s52, v146
	ds_read_b128 v[172:175], v142
	ds_read_b128 v[176:179], v143
	v_add_u32_e32 v142, s54, v145
	v_add_u32_e32 v143, s54, v146
	ds_read_b128 v[180:183], v142
	ds_read_b128 v[184:187], v143
	v_lshl_add_u64 v[142:143], s[20:21], 0, v[138:139]
	s_add_i32 m0, s5, 0xc000
	ds_read_b128 v[188:191], v148
	ds_read_b128 v[192:195], v148 offset:1024
	ds_read_b128 v[196:199], v148 offset:2048
	ds_read_b128 v[200:203], v148 offset:3072
	ds_read_b128 v[204:207], v148 offset:4096
	ds_read_b128 v[208:211], v148 offset:5120
	ds_read_b128 v[226:229], v148 offset:6144
	ds_read_b128 v[230:233], v148 offset:7168
	global_load_lds_dwordx4 v[142:143], off
	v_lshl_add_u64 v[142:143], s[20:21], 0, v[140:141]
	s_add_i32 m0, s5, 0xe000
	s_nop 0
	global_load_lds_dwordx4 v[142:143], off
	s_waitcnt vmcnt(8)
	s_waitcnt lgkmcnt(0)
	s_barrier
; #define PG8_STAGE(bufoff, gbase, voff) do { _Pragma("unroll") for (int _i = 0; _i < 2; ++_i) \
;         __builtin_amdgcn_global_load_lds((const unsigned*)((const char*)(gbase) + (voff)[_i]), (PG8_LAS unsigned*)(lds + (bufoff) + ldsw + _i * 8192), 16, 0, 0); } while (0)
; #define PG8_LDA(dst, b, h) do { _Pragma("unroll") for (int m = 0; m < 4; ++m) _Pragma("unroll") for (int k = 0; k < 2; ++k) dst[m][k] = *(const PG8_LAS bf16x8*)(lds + PG8_SA(b, h) + aoffk[k] + m * 2048); } while (0)
; #define PG8_MMA(ai, bj, At, Bt) do { __builtin_amdgcn_s_setprio(1); _Pragma("unroll") for (int m = 0; m < 4; ++m) _Pragma("unroll") for (int n = 0; n < 2; ++n) _Pragma("unroll") for (int k = 0; k < 2; ++k) \
;         acc[ai][bj][m][n] = __builtin_amdgcn_mfma_f32_16x16x32_bf16(Bt[n][k], At[m][k], acc[ai][bj][m][n], 0, 0, 0); __builtin_amdgcn_s_setprio(0); } while (0)
; #define PG8_WAIT_V(n) asm volatile("s_waitcnt vmcnt(" #n ")" ::: "memory")
; #define PG8_WAIT_L(n) asm volatile("s_waitcnt lgkmcnt(" #n ")" ::: "memory")
; #define PG8_BAR __builtin_amdgcn_s_barrier()
; #define PG8_SCHED __builtin_amdgcn_sched_barrier(0)
; template <class Epi, class Sched, bool ALIGN_EPI = false, bool SP2 = false>
; __device__ __forceinline__ void gemm_phase(PG8_LAS unsigned char* lds, const Gemm g, const Sched& S, const Epi& E) {
;     ...
;             PG8_WAIT_V(8); PG8_WAIT_L(0); PG8_BAR; PG8_MMA(0, 0, At, B0); PG8_MMA(0, 1, At, B1); PG8_BAR; PG8_SCHED;
;             PG8_LDA(At, 0, 1); PG8_STAGE(PG8_SB(0, 0), b2, voffB); PG8_STAGE(PG8_SB(0, 1), b2 + hstepB, voffB); PG8_STAGE(PG8_SA(0, 0), a2, voffA);
;             PG8_WAIT_V(8); PG8_WAIT_L(0); PG8_BAR; PG8_MMA(1, 0, At, B0); PG8_MMA(1, 1, At, B1); PG8_BAR; PG8_SCHED;
	v_mfma_f32_16x16x32_bf16 v[128:131], v[150:153], v[188:191], v[128:131]
	v_mfma_f32_16x16x32_bf16 v[128:131], v[154:157], v[192:195], v[128:131]
	v_mfma_f32_16x16x32_bf16 v[120:123], v[150:153], v[196:199], v[120:123]
	v_mfma_f32_16x16x32_bf16 v[120:123], v[154:157], v[200:203], v[120:123]
	v_mfma_f32_16x16x32_bf16 v[104:107], v[150:153], v[204:207], v[104:107]
	v_mfma_f32_16x16x32_bf16 v[104:107], v[154:157], v[208:211], v[104:107]
	v_mfma_f32_16x16x32_bf16 v[88:91], v[150:153], v[226:229], v[88:91]
	v_mfma_f32_16x16x32_bf16 v[88:91], v[154:157], v[230:233], v[88:91]
	v_mfma_f32_16x16x32_bf16 v[124:127], v[158:161], v[188:191], v[124:127]
	v_mfma_f32_16x16x32_bf16 v[124:127], v[162:165], v[192:195], v[124:127]
	v_mfma_f32_16x16x32_bf16 v[112:115], v[158:161], v[196:199], v[112:115]
	v_mfma_f32_16x16x32_bf16 v[112:115], v[162:165], v[200:203], v[112:115]
	v_mfma_f32_16x16x32_bf16 v[96:99], v[158:161], v[204:207], v[96:99]
	v_mfma_f32_16x16x32_bf16 v[96:99], v[162:165], v[208:211], v[96:99]
	v_mfma_f32_16x16x32_bf16 v[80:83], v[158:161], v[226:229], v[80:83]
	v_mfma_f32_16x16x32_bf16 v[80:83], v[162:165], v[230:233], v[80:83]
	v_mfma_f32_16x16x32_bf16 v[116:119], v[172:175], v[188:191], v[116:119]
	v_mfma_f32_16x16x32_bf16 v[116:119], v[176:179], v[192:195], v[116:119]
	v_mfma_f32_16x16x32_bf16 v[100:103], v[172:175], v[196:199], v[100:103]
	v_mfma_f32_16x16x32_bf16 v[100:103], v[176:179], v[200:203], v[100:103]
	v_mfma_f32_16x16x32_bf16 v[84:87], v[172:175], v[204:207], v[84:87]
	v_mfma_f32_16x16x32_bf16 v[84:87], v[176:179], v[208:211], v[84:87]
	v_mfma_f32_16x16x32_bf16 v[72:75], v[172:175], v[226:229], v[72:75]
	v_mfma_f32_16x16x32_bf16 v[72:75], v[176:179], v[230:233], v[72:75]
	v_mfma_f32_16x16x32_bf16 v[108:111], v[180:183], v[188:191], v[108:111]
	v_mfma_f32_16x16x32_bf16 v[108:111], v[184:187], v[192:195], v[108:111]
	v_mfma_f32_16x16x32_bf16 v[92:95], v[180:183], v[196:199], v[92:95]
	v_mfma_f32_16x16x32_bf16 v[92:95], v[184:187], v[200:203], v[92:95]
	v_mfma_f32_16x16x32_bf16 v[76:79], v[180:183], v[204:207], v[76:79]
	v_mfma_f32_16x16x32_bf16 v[76:79], v[184:187], v[208:211], v[76:79]
	v_mfma_f32_16x16x32_bf16 v[68:71], v[180:183], v[226:229], v[68:71]
	v_mfma_f32_16x16x32_bf16 v[68:71], v[184:187], v[230:233], v[68:71]
	s_barrier
	s_add_i32 s49, s49, s33
	v_lshl_add_u64 v[142:143], s[22:23], 0, v[2:3]
	s_mov_b32 m0, s49
	ds_read_b128 v[188:191], v148 offset:16384
	ds_read_b128 v[192:195], v148 offset:17408
	ds_read_b128 v[196:199], v148 offset:18432
	ds_read_b128 v[200:203], v148 offset:19456
	ds_read_b128 v[204:207], v148 offset:20480
	ds_read_b128 v[208:211], v148 offset:21504
	ds_read_b128 v[226:229], v148 offset:22528
	ds_read_b128 v[230:233], v148 offset:23552
	global_load_lds_dwordx4 v[142:143], off
	s_add_i32 m0, s49, 0x2000
	s_add_u32 s50, s22, 0x80000
	v_lshl_add_u64 v[166:167], s[22:23], 0, v[136:137]
	s_addc_u32 s51, s23, 0
	s_add_i32 s49, s52, s33
	global_load_lds_dwordx4 v[166:167], off
	v_lshl_add_u64 v[212:213], s[50:51], 0, v[2:3]
	s_mov_b32 m0, s49
	v_lshl_add_u64 v[220:221], s[24:25], 0, v[134:135]
	global_load_lds_dwordx4 v[212:213], off
	v_lshl_add_u64 v[212:213], s[50:51], 0, v[136:137]
	s_add_i32 m0, s49, 0x2000
	s_nop 0
	global_load_lds_dwordx4 v[212:213], off
	v_lshl_add_u64 v[212:213], s[24:25], 0, v[132:133]
	s_mov_b32 m0, s5
	s_nop 0
	global_load_lds_dwordx4 v[212:213], off
	s_mov_b32 m0, s7
	s_nop 0
	global_load_lds_dwordx4 v[220:221], off
	s_waitcnt vmcnt(8)
	s_waitcnt lgkmcnt(0)
	s_barrier
	v_mfma_f32_16x16x32_bf16 v[64:67], v[150:153], v[188:191], v[64:67]
	v_mfma_f32_16x16x32_bf16 v[64:67], v[154:157], v[192:195], v[64:67]
	v_mfma_f32_16x16x32_bf16 v[56:59], v[150:153], v[196:199], v[56:59]
	v_mfma_f32_16x16x32_bf16 v[56:59], v[154:157], v[200:203], v[56:59]
	v_mfma_f32_16x16x32_bf16 v[40:43], v[150:153], v[204:207], v[40:43]
	v_mfma_f32_16x16x32_bf16 v[40:43], v[154:157], v[208:211], v[40:43]
	v_mfma_f32_16x16x32_bf16 v[24:27], v[150:153], v[226:229], v[24:27]
	v_mfma_f32_16x16x32_bf16 v[24:27], v[154:157], v[230:233], v[24:27]
	v_mfma_f32_16x16x32_bf16 v[60:63], v[158:161], v[188:191], v[60:63]
	v_mfma_f32_16x16x32_bf16 v[60:63], v[162:165], v[192:195], v[60:63]
	v_mfma_f32_16x16x32_bf16 v[48:51], v[158:161], v[196:199], v[48:51]
	v_mfma_f32_16x16x32_bf16 v[48:51], v[162:165], v[200:203], v[48:51]
	v_mfma_f32_16x16x32_bf16 v[32:35], v[158:161], v[204:207], v[32:35]
	v_mfma_f32_16x16x32_bf16 v[32:35], v[162:165], v[208:211], v[32:35]
	v_mfma_f32_16x16x32_bf16 v[16:19], v[158:161], v[226:229], v[16:19]
	v_mfma_f32_16x16x32_bf16 v[16:19], v[162:165], v[230:233], v[16:19]
	v_mfma_f32_16x16x32_bf16 v[52:55], v[172:175], v[188:191], v[52:55]
	v_mfma_f32_16x16x32_bf16 v[52:55], v[176:179], v[192:195], v[52:55]
	v_mfma_f32_16x16x32_bf16 v[36:39], v[172:175], v[196:199], v[36:39]
	v_mfma_f32_16x16x32_bf16 v[36:39], v[176:179], v[200:203], v[36:39]
	v_mfma_f32_16x16x32_bf16 v[20:23], v[172:175], v[204:207], v[20:23]
	v_mfma_f32_16x16x32_bf16 v[20:23], v[176:179], v[208:211], v[20:23]
	v_mfma_f32_16x16x32_bf16 v[8:11], v[172:175], v[226:229], v[8:11]
	v_mfma_f32_16x16x32_bf16 v[8:11], v[176:179], v[230:233], v[8:11]
	v_mfma_f32_16x16x32_bf16 v[44:47], v[180:183], v[188:191], v[44:47]
	v_mfma_f32_16x16x32_bf16 v[44:47], v[184:187], v[192:195], v[44:47]
	v_mfma_f32_16x16x32_bf16 v[28:31], v[180:183], v[196:199], v[28:31]
	v_mfma_f32_16x16x32_bf16 v[28:31], v[184:187], v[200:203], v[28:31]
	v_mfma_f32_16x16x32_bf16 v[12:15], v[180:183], v[204:207], v[12:15]
	v_mfma_f32_16x16x32_bf16 v[12:15], v[184:187], v[208:211], v[12:15]
	v_mfma_f32_16x16x32_bf16 v[4:7], v[180:183], v[226:229], v[4:7]
	v_mfma_f32_16x16x32_bf16 v[4:7], v[184:187], v[230:233], v[4:7]
	s_barrier
; #define PG8_STAGE(bufoff, gbase, voff) do { _Pragma("unroll") for (int _i = 0; _i < 2; ++_i) \
;         __builtin_amdgcn_global_load_lds((const unsigned*)((const char*)(gbase) + (voff)[_i]), (PG8_LAS unsigned*)(lds + (bufoff) + ldsw + _i * 8192), 16, 0, 0); } while (0)
; #define PG8_LDA(dst, b, h) do { _Pragma("unroll") for (int m = 0; m < 4; ++m) _Pragma("unroll") for (int k = 0; k < 2; ++k) dst[m][k] = *(const PG8_LAS bf16x8*)(lds + PG8_SA(b, h) + aoffk[k] + m * 2048); } while (0)
; #define PG8_LDB(dst, b, h) do { _Pragma("unroll") for (int n = 0; n < 2; ++n) _Pragma("unroll") for (int k = 0; k < 2; ++k) dst[n][k] = *(const PG8_LAS bf16x8*)(lds + PG8_SB(b, h) + boffk[k] + n * 2048); } while (0)
; #define PG8_MMA(ai, bj, At, Bt) do { __builtin_amdgcn_s_setprio(1); _Pragma("unroll") for (int m = 0; m < 4; ++m) _Pragma("unroll") for (int n = 0; n < 2; ++n) _Pragma("unroll") for (int k = 0; k < 2; ++k) \
;         acc[ai][bj][m][n] = __builtin_amdgcn_mfma_f32_16x16x32_bf16(Bt[n][k], At[m][k], acc[ai][bj][m][n], 0, 0, 0); __builtin_amdgcn_s_setprio(0); } while (0)
; #define PG8_WAIT_V(n) asm volatile("s_waitcnt vmcnt(" #n ")" ::: "memory")
; #define PG8_WAIT_L(n) asm volatile("s_waitcnt lgkmcnt(" #n ")" ::: "memory")
; #define PG8_BAR __builtin_amdgcn_s_barrier()
; #define PG8_SCHED __builtin_amdgcn_sched_barrier(0)
; template <class Epi, class Sched, bool ALIGN_EPI = false, bool SP2 = false>
; __device__ __forceinline__ void gemm_phase(PG8_LAS unsigned char* lds, const Gemm g, const Sched& S, const Epi& E) {
;     ...
;             PG8_LDB(B0, 1, 0); PG8_LDB(B1, 1, 1); PG8_SCHED; PG8_LDA(At, 1, 0); PG8_STAGE(PG8_SA(0, 1), a2 + hstepA, voffA);
;             PG8_WAIT_V(8); PG8_WAIT_L(0); PG8_BAR; PG8_MMA(0, 0, At, B0); PG8_MMA(0, 1, At, B1); PG8_BAR; PG8_SCHED;
	s_add_i32 s49, 0, 0x18000
	v_add_u32_e32 v149, s49, v145
	v_add_u32_e32 v154, s49, v146
	ds_read_b128 v[150:153], v149
	ds_read_b128 v[154:157], v154
	v_add_u32_e32 v149, s55, v145
	v_add_u32_e32 v162, s55, v146
	s_add_i32 s50, 0, 0x1c000
	ds_read_b128 v[158:161], v149
	ds_read_b128 v[162:165], v162
	v_add_u32_e32 v149, s50, v145
	v_add_u32_e32 v168, s50, v146
	ds_read_b128 v[172:175], v149
	ds_read_b128 v[176:179], v168
	v_add_u32_e32 v149, s56, v145
	v_add_u32_e32 v168, s56, v146
	ds_read_b128 v[180:183], v149
	ds_read_b128 v[184:187], v168
	s_add_u32 s24, s24, 0x80000
	s_addc_u32 s25, s25, 0
	s_mov_b32 m0, s34
	v_lshl_add_u64 v[234:235], s[24:25], 0, v[132:133]
	ds_read_b128 v[188:191], v148 offset:32768
	ds_read_b128 v[192:195], v148 offset:33792
	ds_read_b128 v[196:199], v148 offset:34816
	ds_read_b128 v[200:203], v148 offset:35840
	ds_read_b128 v[204:207], v148 offset:36864
	ds_read_b128 v[208:211], v148 offset:37888
	ds_read_b128 v[226:229], v148 offset:38912
	ds_read_b128 v[230:233], v148 offset:39936
	global_load_lds_dwordx4 v[234:235], off
	v_lshl_add_u64 v[234:235], s[24:25], 0, v[134:135]
	s_mov_b32 m0, s35
	s_nop 0
	global_load_lds_dwordx4 v[234:235], off
	s_waitcnt vmcnt(8)
	s_waitcnt lgkmcnt(0)
	s_barrier
	v_mfma_f32_16x16x32_bf16 v[128:131], v[150:153], v[188:191], v[128:131]
	v_mfma_f32_16x16x32_bf16 v[128:131], v[154:157], v[192:195], v[128:131]
	v_mfma_f32_16x16x32_bf16 v[120:123], v[150:153], v[196:199], v[120:123]
	v_mfma_f32_16x16x32_bf16 v[120:123], v[154:157], v[200:203], v[120:123]
	v_mfma_f32_16x16x32_bf16 v[104:107], v[150:153], v[204:207], v[104:107]
	v_mfma_f32_16x16x32_bf16 v[104:107], v[154:157], v[208:211], v[104:107]
	v_mfma_f32_16x16x32_bf16 v[88:91], v[150:153], v[226:229], v[88:91]
	v_mfma_f32_16x16x32_bf16 v[88:91], v[154:157], v[230:233], v[88:91]
	v_mfma_f32_16x16x32_bf16 v[124:127], v[158:161], v[188:191], v[124:127]
	v_mfma_f32_16x16x32_bf16 v[124:127], v[162:165], v[192:195], v[124:127]
	v_mfma_f32_16x16x32_bf16 v[112:115], v[158:161], v[196:199], v[112:115]
	v_mfma_f32_16x16x32_bf16 v[112:115], v[162:165], v[200:203], v[112:115]
	v_mfma_f32_16x16x32_bf16 v[96:99], v[158:161], v[204:207], v[96:99]
	v_mfma_f32_16x16x32_bf16 v[96:99], v[162:165], v[208:211], v[96:99]
	v_mfma_f32_16x16x32_bf16 v[80:83], v[158:161], v[226:229], v[80:83]
	v_mfma_f32_16x16x32_bf16 v[80:83], v[162:165], v[230:233], v[80:83]
	v_mfma_f32_16x16x32_bf16 v[116:119], v[172:175], v[188:191], v[116:119]
	v_mfma_f32_16x16x32_bf16 v[116:119], v[176:179], v[192:195], v[116:119]
	v_mfma_f32_16x16x32_bf16 v[100:103], v[172:175], v[196:199], v[100:103]
	v_mfma_f32_16x16x32_bf16 v[100:103], v[176:179], v[200:203], v[100:103]
	v_mfma_f32_16x16x32_bf16 v[84:87], v[172:175], v[204:207], v[84:87]
	v_mfma_f32_16x16x32_bf16 v[84:87], v[176:179], v[208:211], v[84:87]
	v_mfma_f32_16x16x32_bf16 v[72:75], v[172:175], v[226:229], v[72:75]
	v_mfma_f32_16x16x32_bf16 v[72:75], v[176:179], v[230:233], v[72:75]
	v_mfma_f32_16x16x32_bf16 v[108:111], v[180:183], v[188:191], v[108:111]
	v_mfma_f32_16x16x32_bf16 v[108:111], v[184:187], v[192:195], v[108:111]
	v_mfma_f32_16x16x32_bf16 v[92:95], v[180:183], v[196:199], v[92:95]
	v_mfma_f32_16x16x32_bf16 v[92:95], v[184:187], v[200:203], v[92:95]
	v_mfma_f32_16x16x32_bf16 v[76:79], v[180:183], v[204:207], v[76:79]
	v_mfma_f32_16x16x32_bf16 v[76:79], v[184:187], v[208:211], v[76:79]
	v_mfma_f32_16x16x32_bf16 v[68:71], v[180:183], v[226:229], v[68:71]
	v_mfma_f32_16x16x32_bf16 v[68:71], v[184:187], v[230:233], v[68:71]
	s_barrier
; #define PG8_STAGE(bufoff, gbase, voff) do { _Pragma("unroll") for (int _i = 0; _i < 2; ++_i) \
;         __builtin_amdgcn_global_load_lds((const unsigned*)((const char*)(gbase) + (voff)[_i]), (PG8_LAS unsigned*)(lds + (bufoff) + ldsw + _i * 8192), 16, 0, 0); } while (0)
; #define PG8_LDA(dst, b, h) do { _Pragma("unroll") for (int m = 0; m < 4; ++m) _Pragma("unroll") for (int k = 0; k < 2; ++k) dst[m][k] = *(const PG8_LAS bf16x8*)(lds + PG8_SA(b, h) + aoffk[k] + m * 2048); } while (0)
; #define PG8_MMA(ai, bj, At, Bt) do { __builtin_amdgcn_s_setprio(1); _Pragma("unroll") for (int m = 0; m < 4; ++m) _Pragma("unroll") for (int n = 0; n < 2; ++n) _Pragma("unroll") for (int k = 0; k < 2; ++k) \
;         acc[ai][bj][m][n] = __builtin_amdgcn_mfma_f32_16x16x32_bf16(Bt[n][k], At[m][k], acc[ai][bj][m][n], 0, 0, 0); __builtin_amdgcn_s_setprio(0); } while (0)
; #define PG8_WAIT_V(n) asm volatile("s_waitcnt vmcnt(" #n ")" ::: "memory")
; #define PG8_WAIT_L(n) asm volatile("s_waitcnt lgkmcnt(" #n ")" ::: "memory")
; #define PG8_BAR __builtin_amdgcn_s_barrier()
; #define PG8_SCHED __builtin_amdgcn_sched_barrier(0)
; template <class Epi, class Sched, bool ALIGN_EPI = false, bool SP2 = false>
; __device__ __forceinline__ void gemm_phase(PG8_LAS unsigned char* lds, const Gemm g, const Sched& S, const Epi& E) {
;     ...
;         for (int t = 0; t < nt; t += 2) {
;             const bool last = (t == nt - 2);
;             const char* a1 = cA + (size_t)(t + 1) * kstep;
;             const char* a2 = last ? nA : cA + (size_t)(t + 2) * kstep; const char* b2 = last ? nB : cB + (size_t)(t + 2) * kstep;
;             const char* a3 = a2 + kstep; const char* b3 = b2 + kstep;
;     ...
;             PG8_LDA(At, 1, 1); PG8_STAGE(PG8_SB(1, 0), b3, voffB); PG8_STAGE(PG8_SB(1, 1), b3 + hstepB, voffB); PG8_STAGE(PG8_SA(1, 0), a3, voffA);
;             PG8_WAIT_V(8); PG8_WAIT_L(0); PG8_BAR; PG8_MMA(1, 0, At, B0); PG8_MMA(1, 1, At, B1); PG8_BAR; PG8_SCHED;
	s_add_i32 s24, s49, s33
	v_lshl_add_u64 v[142:143], v[142:143], 0, s[58:59]
	s_mov_b32 m0, s24
	ds_read_b128 v[188:191], v148 offset:49152
	ds_read_b128 v[192:195], v148 offset:50176
	ds_read_b128 v[196:199], v148 offset:51200
	ds_read_b128 v[200:203], v148 offset:52224
	ds_read_b128 v[204:207], v148 offset:53248
	ds_read_b128 v[208:211], v148 offset:54272
	ds_read_b128 v[226:229], v148 offset:55296
	ds_read_b128 v[230:233], v148 offset:56320
	global_load_lds_dwordx4 v[142:143], off
	s_add_i32 m0, s24, 0x2000
	s_add_u32 s22, s22, 0x80080
	v_lshl_add_u64 v[142:143], v[166:167], 0, s[58:59]
	s_addc_u32 s23, s23, 0
	s_add_i32 s24, s50, s33
	global_load_lds_dwordx4 v[142:143], off
	v_lshl_add_u64 v[142:143], s[22:23], 0, v[2:3]
	s_mov_b32 m0, s24
	s_nop 0
	global_load_lds_dwordx4 v[142:143], off
	v_lshl_add_u64 v[142:143], s[22:23], 0, v[136:137]
	s_add_i32 m0, s24, 0x2000
	s_nop 0
	global_load_lds_dwordx4 v[142:143], off
	v_lshl_add_u64 v[142:143], v[212:213], 0, s[58:59]
	s_mov_b32 m0, s40
	s_nop 0
	global_load_lds_dwordx4 v[142:143], off
	v_lshl_add_u64 v[142:143], v[220:221], 0, s[58:59]
	s_mov_b32 m0, s41
	s_nop 0
	global_load_lds_dwordx4 v[142:143], off
	s_waitcnt vmcnt(8)
	s_waitcnt lgkmcnt(0)
	s_barrier
	v_mfma_f32_16x16x32_bf16 v[64:67], v[150:153], v[188:191], v[64:67]
	v_mfma_f32_16x16x32_bf16 v[64:67], v[154:157], v[192:195], v[64:67]
	v_mfma_f32_16x16x32_bf16 v[56:59], v[150:153], v[196:199], v[56:59]
	v_mfma_f32_16x16x32_bf16 v[56:59], v[154:157], v[200:203], v[56:59]
	v_mfma_f32_16x16x32_bf16 v[40:43], v[150:153], v[204:207], v[40:43]
	v_mfma_f32_16x16x32_bf16 v[40:43], v[154:157], v[208:211], v[40:43]
	v_mfma_f32_16x16x32_bf16 v[24:27], v[150:153], v[226:229], v[24:27]
	v_mfma_f32_16x16x32_bf16 v[24:27], v[154:157], v[230:233], v[24:27]
	v_mfma_f32_16x16x32_bf16 v[60:63], v[158:161], v[188:191], v[60:63]
	v_mfma_f32_16x16x32_bf16 v[60:63], v[162:165], v[192:195], v[60:63]
	v_mfma_f32_16x16x32_bf16 v[48:51], v[158:161], v[196:199], v[48:51]
	v_mfma_f32_16x16x32_bf16 v[48:51], v[162:165], v[200:203], v[48:51]
	v_mfma_f32_16x16x32_bf16 v[32:35], v[158:161], v[204:207], v[32:35]
	v_mfma_f32_16x16x32_bf16 v[32:35], v[162:165], v[208:211], v[32:35]
	v_mfma_f32_16x16x32_bf16 v[16:19], v[158:161], v[226:229], v[16:19]
	v_mfma_f32_16x16x32_bf16 v[16:19], v[162:165], v[230:233], v[16:19]
	v_mfma_f32_16x16x32_bf16 v[52:55], v[172:175], v[188:191], v[52:55]
	v_mfma_f32_16x16x32_bf16 v[52:55], v[176:179], v[192:195], v[52:55]
	v_mfma_f32_16x16x32_bf16 v[36:39], v[172:175], v[196:199], v[36:39]
	v_mfma_f32_16x16x32_bf16 v[36:39], v[176:179], v[200:203], v[36:39]
	v_mfma_f32_16x16x32_bf16 v[20:23], v[172:175], v[204:207], v[20:23]
	v_mfma_f32_16x16x32_bf16 v[20:23], v[176:179], v[208:211], v[20:23]
	v_mfma_f32_16x16x32_bf16 v[8:11], v[172:175], v[226:229], v[8:11]
	v_mfma_f32_16x16x32_bf16 v[8:11], v[176:179], v[230:233], v[8:11]
	v_mfma_f32_16x16x32_bf16 v[44:47], v[180:183], v[188:191], v[44:47]
	v_mfma_f32_16x16x32_bf16 v[44:47], v[184:187], v[192:195], v[44:47]
	v_mfma_f32_16x16x32_bf16 v[28:31], v[180:183], v[196:199], v[28:31]
	v_mfma_f32_16x16x32_bf16 v[28:31], v[184:187], v[200:203], v[28:31]
	v_mfma_f32_16x16x32_bf16 v[12:15], v[180:183], v[204:207], v[12:15]
	v_mfma_f32_16x16x32_bf16 v[12:15], v[184:187], v[208:211], v[12:15]
	v_mfma_f32_16x16x32_bf16 v[4:7], v[180:183], v[226:229], v[4:7]
	v_mfma_f32_16x16x32_bf16 v[4:7], v[184:187], v[230:233], v[4:7]
	s_barrier
	s_add_u32 s20, s20, 0x100
	s_addc_u32 s21, s21, 0
	s_add_u32 s13, s13, 0x100
	s_addc_u32 s15, s15, 0
	s_cmp_ge_i32 s48, s45
	s_mov_b32 s22, s48
	s_cbranch_scc0 .LBB0_1293

; #define PG8_STAGE(bufoff, gbase, voff) do { _Pragma("unroll") for (int _i = 0; _i < 2; ++_i) \
;         __builtin_amdgcn_global_load_lds((const unsigned*)((const char*)(gbase) + (voff)[_i]), (PG8_LAS unsigned*)(lds + (bufoff) + ldsw + _i * 8192), 16, 0, 0); } while (0)
; #define PG8_LDA(dst, b, h) do { _Pragma("unroll") for (int m = 0; m < 4; ++m) _Pragma("unroll") for (int k = 0; k < 2; ++k) dst[m][k] = *(const PG8_LAS bf16x8*)(lds + PG8_SA(b, h) + aoffk[k] + m * 2048); } while (0)
; #define PG8_LDB(dst, b, h) do { _Pragma("unroll") for (int n = 0; n < 2; ++n) _Pragma("unroll") for (int k = 0; k < 2; ++k) dst[n][k] = *(const PG8_LAS bf16x8*)(lds + PG8_SB(b, h) + boffk[k] + n * 2048); } while (0)
; #define PG8_MMA(ai, bj, At, Bt) do { __builtin_amdgcn_s_setprio(1); _Pragma("unroll") for (int m = 0; m < 4; ++m) _Pragma("unroll") for (int n = 0; n < 2; ++n) _Pragma("unroll") for (int k = 0; k < 2; ++k) \
;         acc[ai][bj][m][n] = __builtin_amdgcn_mfma_f32_16x16x32_bf16(Bt[n][k], At[m][k], acc[ai][bj][m][n], 0, 0, 0); __builtin_amdgcn_s_setprio(0); } while (0)
; #define PG8_WAIT_V(n) asm volatile("s_waitcnt vmcnt(" #n ")" ::: "memory")
; #define PG8_WAIT_L(n) asm volatile("s_waitcnt lgkmcnt(" #n ")" ::: "memory")
; template <class Epi, class Sched, bool ALIGN_EPI = false, bool SP2 = false>
; __device__ __forceinline__ void gemm_phase(PG8_LAS unsigned char* lds, const Gemm g, const Sched& S, const Epi& E) {
;     ...
;         for (int t = 0; t < nt; t += 2) {
;             const bool last = (t == nt - 2);
;             const char* a1 = cA + (size_t)(t + 1) * kstep;
;             const char* a2 = last ? nA : cA + (size_t)(t + 2) * kstep; const char* b2 = last ? nB : cB + (size_t)(t + 2) * kstep;
;             const char* a3 = a2 + kstep; const char* b3 = b2 + kstep;
;             if (last && has_next) S.a_ready(nxt);
;             if constexpr (SP2) {
;             PG8_LDB(B0, 0, 0); PG8_LDB(B1, 0, 1); PG8_SCHED; PG8_LDA(At, 0, 0); PG8_STAGE(PG8_SA(1, 1), a1 + hstepA, voffA);
;             PG8_WAIT_V(8); PG8_WAIT_L(0); PG8_BAR; PG8_MMA(0, 0, At, B0); PG8_MMA(0, 1, At, B1); PG8_BAR; PG8_SCHED;
;             PG8_LDA(At, 0, 1); PG8_STAGE(PG8_SB(0, 0), b2, voffB); PG8_STAGE(PG8_SB(0, 1), b2 + hstepB, voffB); PG8_STAGE(PG8_SA(0, 0), a2, voffA);
;             PG8_WAIT_V(8); PG8_WAIT_L(0); PG8_BAR; PG8_MMA(1, 0, At, B0); PG8_MMA(1, 1, At, B1); PG8_BAR; PG8_SCHED;
.Lgemm_first_4:
	s_add_u32 s20, s18, 0xfff80080
	s_addc_u32 s21, s19, -1
	s_add_i32 s47, 0, 0x10000
	s_cmp_eq_u32 s46, 28
	v_add_u32_e32 v142, s47, v147
	v_add_u32_e32 v151, s47, v148
	s_cselect_b32 s23, s9, s21
	s_cselect_b32 s22, s33, s20
	ds_read_b128 v[142:145], v142
	ds_read_b128 v[152:155], v151
	v_add_u32_e32 v151, s51, v147
	v_add_u32_e32 v160, s51, v148
	s_cselect_b32 s21, s7, s45
	s_cselect_b32 s20, s43, s44
	s_add_i32 s50, 0, 0x14000
	ds_read_b128 v[156:159], v151
	ds_read_b128 v[160:163], v160
	v_add_u32_e32 v151, s50, v147
	v_add_u32_e32 v168, s50, v148
	ds_read_b128 v[164:167], v151
	ds_read_b128 v[172:175], v168
	v_add_u32_e32 v151, s52, v147
	v_add_u32_e32 v168, s52, v148
	ds_read_b128 v[176:179], v151
	ds_read_b128 v[180:183], v168
	v_lshl_add_u64 v[212:213], s[18:19], 0, v[138:139]
	s_add_i32 m0, s36, 0xc000
	ds_read_b128 v[184:187], v150
	ds_read_b128 v[188:191], v150 offset:1024
	ds_read_b128 v[192:195], v150 offset:2048
	ds_read_b128 v[196:199], v150 offset:3072
	ds_read_b128 v[200:203], v150 offset:4096
	ds_read_b128 v[204:207], v150 offset:5120
	ds_read_b128 v[208:211], v150 offset:6144
	ds_read_b128 v[226:229], v150 offset:7168
	global_load_lds_dwordx4 v[212:213], off
	v_lshl_add_u64 v[212:213], s[18:19], 0, v[140:141]
	s_add_i32 m0, s36, 0xe000
	s_nop 0
	global_load_lds_dwordx4 v[212:213], off
	s_waitcnt vmcnt(8)
	s_waitcnt lgkmcnt(0)
	s_barrier
	v_mfma_f32_16x16x32_bf16 v[128:131], v[142:145], v[184:187], 0
	v_mfma_f32_16x16x32_bf16 v[128:131], v[152:155], v[188:191], v[128:131]
	v_mfma_f32_16x16x32_bf16 v[112:115], v[142:145], v[192:195], 0
	v_mfma_f32_16x16x32_bf16 v[112:115], v[152:155], v[196:199], v[112:115]
	v_mfma_f32_16x16x32_bf16 v[96:99], v[142:145], v[200:203], 0
	v_mfma_f32_16x16x32_bf16 v[96:99], v[152:155], v[204:207], v[96:99]
	v_mfma_f32_16x16x32_bf16 v[80:83], v[142:145], v[208:211], 0
	v_mfma_f32_16x16x32_bf16 v[80:83], v[152:155], v[226:229], v[80:83]
	v_mfma_f32_16x16x32_bf16 v[120:123], v[156:159], v[184:187], 0
	v_mfma_f32_16x16x32_bf16 v[120:123], v[160:163], v[188:191], v[120:123]
	v_mfma_f32_16x16x32_bf16 v[104:107], v[156:159], v[192:195], 0
	v_mfma_f32_16x16x32_bf16 v[104:107], v[160:163], v[196:199], v[104:107]
	v_mfma_f32_16x16x32_bf16 v[88:91], v[156:159], v[200:203], 0
	v_mfma_f32_16x16x32_bf16 v[88:91], v[160:163], v[204:207], v[88:91]
	v_mfma_f32_16x16x32_bf16 v[72:75], v[156:159], v[208:211], 0
	v_mfma_f32_16x16x32_bf16 v[72:75], v[160:163], v[226:229], v[72:75]
	v_mfma_f32_16x16x32_bf16 v[124:127], v[164:167], v[184:187], 0
	v_mfma_f32_16x16x32_bf16 v[124:127], v[172:175], v[188:191], v[124:127]
	v_mfma_f32_16x16x32_bf16 v[108:111], v[164:167], v[192:195], 0
	v_mfma_f32_16x16x32_bf16 v[108:111], v[172:175], v[196:199], v[108:111]
	v_mfma_f32_16x16x32_bf16 v[92:95], v[164:167], v[200:203], 0
	v_mfma_f32_16x16x32_bf16 v[92:95], v[172:175], v[204:207], v[92:95]
	v_mfma_f32_16x16x32_bf16 v[76:79], v[164:167], v[208:211], 0
	v_mfma_f32_16x16x32_bf16 v[76:79], v[172:175], v[226:229], v[76:79]
	v_mfma_f32_16x16x32_bf16 v[116:119], v[176:179], v[184:187], 0
	v_mfma_f32_16x16x32_bf16 v[116:119], v[180:183], v[188:191], v[116:119]
	v_mfma_f32_16x16x32_bf16 v[100:103], v[176:179], v[192:195], 0
	v_mfma_f32_16x16x32_bf16 v[100:103], v[180:183], v[196:199], v[100:103]
	v_mfma_f32_16x16x32_bf16 v[84:87], v[176:179], v[200:203], 0
	v_mfma_f32_16x16x32_bf16 v[84:87], v[180:183], v[204:207], v[84:87]
	v_mfma_f32_16x16x32_bf16 v[68:71], v[176:179], v[208:211], 0
	v_mfma_f32_16x16x32_bf16 v[68:71], v[180:183], v[226:229], v[68:71]
	s_barrier
	s_add_i32 s47, s47, s31
	v_lshl_add_u64 v[212:213], s[20:21], 0, v[2:3]
	s_mov_b32 m0, s47
	ds_read_b128 v[184:187], v150 offset:16384
	ds_read_b128 v[188:191], v150 offset:17408
	ds_read_b128 v[192:195], v150 offset:18432
	ds_read_b128 v[196:199], v150 offset:19456
	ds_read_b128 v[200:203], v150 offset:20480
	ds_read_b128 v[204:207], v150 offset:21504
	ds_read_b128 v[208:211], v150 offset:22528
	ds_read_b128 v[226:229], v150 offset:23552
	global_load_lds_dwordx4 v[212:213], off
	s_add_i32 m0, s47, 0x2000
	s_add_u32 s48, s20, 0x80000
	v_lshl_add_u64 v[220:221], s[20:21], 0, v[132:133]
	s_addc_u32 s49, s21, 0
	s_add_i32 s47, s50, s31
	global_load_lds_dwordx4 v[220:221], off
	v_lshl_add_u64 v[230:231], s[48:49], 0, v[2:3]
	s_mov_b32 m0, s47
	v_lshl_add_u64 v[232:233], s[22:23], 0, v[134:135]
	global_load_lds_dwordx4 v[230:231], off
	v_lshl_add_u64 v[230:231], s[48:49], 0, v[132:133]
	s_add_i32 m0, s47, 0x2000
	s_nop 0
	global_load_lds_dwordx4 v[230:231], off
	v_lshl_add_u64 v[230:231], s[22:23], 0, v[136:137]
	s_mov_b32 m0, s36
	s_nop 0
	global_load_lds_dwordx4 v[230:231], off
	s_mov_b32 m0, s37
	s_nop 0
	global_load_lds_dwordx4 v[232:233], off
	s_waitcnt vmcnt(8)
	s_waitcnt lgkmcnt(0)
	s_barrier
; #define PG8_STAGE(bufoff, gbase, voff) do { _Pragma("unroll") for (int _i = 0; _i < 2; ++_i) \
;         __builtin_amdgcn_global_load_lds((const unsigned*)((const char*)(gbase) + (voff)[_i]), (PG8_LAS unsigned*)(lds + (bufoff) + ldsw + _i * 8192), 16, 0, 0); } while (0)
; #define PG8_LDA(dst, b, h) do { _Pragma("unroll") for (int m = 0; m < 4; ++m) _Pragma("unroll") for (int k = 0; k < 2; ++k) dst[m][k] = *(const PG8_LAS bf16x8*)(lds + PG8_SA(b, h) + aoffk[k] + m * 2048); } while (0)
; #define PG8_LDB(dst, b, h) do { _Pragma("unroll") for (int n = 0; n < 2; ++n) _Pragma("unroll") for (int k = 0; k < 2; ++k) dst[n][k] = *(const PG8_LAS bf16x8*)(lds + PG8_SB(b, h) + boffk[k] + n * 2048); } while (0)
; #define PG8_MMA(ai, bj, At, Bt) do { __builtin_amdgcn_s_setprio(1); _Pragma("unroll") for (int m = 0; m < 4; ++m) _Pragma("unroll") for (int n = 0; n < 2; ++n) _Pragma("unroll") for (int k = 0; k < 2; ++k) \
;         acc[ai][bj][m][n] = __builtin_amdgcn_mfma_f32_16x16x32_bf16(Bt[n][k], At[m][k], acc[ai][bj][m][n], 0, 0, 0); __builtin_amdgcn_s_setprio(0); } while (0)
; #define PG8_WAIT_V(n) asm volatile("s_waitcnt vmcnt(" #n ")" ::: "memory")
; #define PG8_WAIT_L(n) asm volatile("s_waitcnt lgkmcnt(" #n ")" ::: "memory")
; #define PG8_BAR __builtin_amdgcn_s_barrier()
; #define PG8_SCHED __builtin_amdgcn_sched_barrier(0)
; template <class Epi, class Sched, bool ALIGN_EPI = false, bool SP2 = false>
; __device__ __forceinline__ void gemm_phase(PG8_LAS unsigned char* lds, const Gemm g, const Sched& S, const Epi& E) {
;     ...
;             PG8_WAIT_V(8); PG8_WAIT_L(0); PG8_BAR; PG8_MMA(1, 0, At, B0); PG8_MMA(1, 1, At, B1); PG8_BAR; PG8_SCHED;
;             PG8_LDB(B0, 1, 0); PG8_LDB(B1, 1, 1); PG8_SCHED; PG8_LDA(At, 1, 0); PG8_STAGE(PG8_SA(0, 1), a2 + hstepA, voffA);
;             PG8_WAIT_V(8); PG8_WAIT_L(0); PG8_BAR; PG8_MMA(0, 0, At, B0); PG8_MMA(0, 1, At, B1); PG8_BAR; PG8_SCHED;
	v_mfma_f32_16x16x32_bf16 v[64:67], v[142:145], v[184:187], 0
	v_mfma_f32_16x16x32_bf16 v[64:67], v[152:155], v[188:191], v[64:67]
	v_mfma_f32_16x16x32_bf16 v[48:51], v[142:145], v[192:195], 0
	v_mfma_f32_16x16x32_bf16 v[48:51], v[152:155], v[196:199], v[48:51]
	v_mfma_f32_16x16x32_bf16 v[32:35], v[142:145], v[200:203], 0
	v_mfma_f32_16x16x32_bf16 v[32:35], v[152:155], v[204:207], v[32:35]
	v_mfma_f32_16x16x32_bf16 v[16:19], v[142:145], v[208:211], 0
	v_mfma_f32_16x16x32_bf16 v[16:19], v[152:155], v[226:229], v[16:19]
	v_mfma_f32_16x16x32_bf16 v[56:59], v[156:159], v[184:187], 0
	v_mfma_f32_16x16x32_bf16 v[56:59], v[160:163], v[188:191], v[56:59]
	v_mfma_f32_16x16x32_bf16 v[40:43], v[156:159], v[192:195], 0
	v_mfma_f32_16x16x32_bf16 v[40:43], v[160:163], v[196:199], v[40:43]
	v_mfma_f32_16x16x32_bf16 v[24:27], v[156:159], v[200:203], 0
	v_mfma_f32_16x16x32_bf16 v[24:27], v[160:163], v[204:207], v[24:27]
	v_mfma_f32_16x16x32_bf16 v[8:11], v[156:159], v[208:211], 0
	v_mfma_f32_16x16x32_bf16 v[8:11], v[160:163], v[226:229], v[8:11]
	v_mfma_f32_16x16x32_bf16 v[60:63], v[164:167], v[184:187], 0
	v_mfma_f32_16x16x32_bf16 v[60:63], v[172:175], v[188:191], v[60:63]
	v_mfma_f32_16x16x32_bf16 v[44:47], v[164:167], v[192:195], 0
	v_mfma_f32_16x16x32_bf16 v[44:47], v[172:175], v[196:199], v[44:47]
	v_mfma_f32_16x16x32_bf16 v[28:31], v[164:167], v[200:203], 0
	v_mfma_f32_16x16x32_bf16 v[28:31], v[172:175], v[204:207], v[28:31]
	v_mfma_f32_16x16x32_bf16 v[12:15], v[164:167], v[208:211], 0
	v_mfma_f32_16x16x32_bf16 v[12:15], v[172:175], v[226:229], v[12:15]
	v_mfma_f32_16x16x32_bf16 v[52:55], v[176:179], v[184:187], 0
	v_mfma_f32_16x16x32_bf16 v[52:55], v[180:183], v[188:191], v[52:55]
	v_mfma_f32_16x16x32_bf16 v[36:39], v[176:179], v[192:195], 0
	v_mfma_f32_16x16x32_bf16 v[36:39], v[180:183], v[196:199], v[36:39]
	v_mfma_f32_16x16x32_bf16 v[20:23], v[176:179], v[200:203], 0
	v_mfma_f32_16x16x32_bf16 v[20:23], v[180:183], v[204:207], v[20:23]
	v_mfma_f32_16x16x32_bf16 v[4:7], v[176:179], v[208:211], 0
	v_mfma_f32_16x16x32_bf16 v[4:7], v[180:183], v[226:229], v[4:7]
	s_barrier
	s_add_i32 s47, 0, 0x18000
	v_add_u32_e32 v142, s47, v147
	v_add_u32_e32 v151, s47, v148
	ds_read_b128 v[142:145], v142
	ds_read_b128 v[152:155], v151
	v_add_u32_e32 v151, s53, v147
	v_add_u32_e32 v160, s53, v148
	s_add_i32 s48, 0, 0x1c000
	ds_read_b128 v[156:159], v151
	ds_read_b128 v[160:163], v160
	v_add_u32_e32 v151, s48, v147
	v_add_u32_e32 v168, s48, v148
	ds_read_b128 v[164:167], v151
	ds_read_b128 v[172:175], v168
	v_add_u32_e32 v151, s54, v147
	v_add_u32_e32 v168, s54, v148
	ds_read_b128 v[176:179], v151
	ds_read_b128 v[180:183], v168
	s_add_u32 s22, s22, 0x80000
	s_addc_u32 s23, s23, 0
	s_mov_b32 m0, s38
	v_lshl_add_u64 v[234:235], s[22:23], 0, v[136:137]
	ds_read_b128 v[184:187], v150 offset:32768
	ds_read_b128 v[188:191], v150 offset:33792
	ds_read_b128 v[192:195], v150 offset:34816
	ds_read_b128 v[196:199], v150 offset:35840
	ds_read_b128 v[200:203], v150 offset:36864
	ds_read_b128 v[204:207], v150 offset:37888
	ds_read_b128 v[208:211], v150 offset:38912
	ds_read_b128 v[226:229], v150 offset:39936
	global_load_lds_dwordx4 v[234:235], off
	v_lshl_add_u64 v[234:235], s[22:23], 0, v[134:135]
	s_mov_b32 m0, s39
	s_nop 0
	global_load_lds_dwordx4 v[234:235], off
	s_waitcnt vmcnt(8)
	s_waitcnt lgkmcnt(0)
	s_barrier
	v_mfma_f32_16x16x32_bf16 v[128:131], v[142:145], v[184:187], v[128:131]
	v_mfma_f32_16x16x32_bf16 v[128:131], v[152:155], v[188:191], v[128:131]
	v_mfma_f32_16x16x32_bf16 v[112:115], v[142:145], v[192:195], v[112:115]
	v_mfma_f32_16x16x32_bf16 v[112:115], v[152:155], v[196:199], v[112:115]
	v_mfma_f32_16x16x32_bf16 v[96:99], v[142:145], v[200:203], v[96:99]
	v_mfma_f32_16x16x32_bf16 v[96:99], v[152:155], v[204:207], v[96:99]
	v_mfma_f32_16x16x32_bf16 v[80:83], v[142:145], v[208:211], v[80:83]
	v_mfma_f32_16x16x32_bf16 v[80:83], v[152:155], v[226:229], v[80:83]
	v_mfma_f32_16x16x32_bf16 v[120:123], v[156:159], v[184:187], v[120:123]
	v_mfma_f32_16x16x32_bf16 v[120:123], v[160:163], v[188:191], v[120:123]
	v_mfma_f32_16x16x32_bf16 v[104:107], v[156:159], v[192:195], v[104:107]
	v_mfma_f32_16x16x32_bf16 v[104:107], v[160:163], v[196:199], v[104:107]
	v_mfma_f32_16x16x32_bf16 v[88:91], v[156:159], v[200:203], v[88:91]
	v_mfma_f32_16x16x32_bf16 v[88:91], v[160:163], v[204:207], v[88:91]
	v_mfma_f32_16x16x32_bf16 v[72:75], v[156:159], v[208:211], v[72:75]
	v_mfma_f32_16x16x32_bf16 v[72:75], v[160:163], v[226:229], v[72:75]
	v_mfma_f32_16x16x32_bf16 v[124:127], v[164:167], v[184:187], v[124:127]
	v_mfma_f32_16x16x32_bf16 v[124:127], v[172:175], v[188:191], v[124:127]
	v_mfma_f32_16x16x32_bf16 v[108:111], v[164:167], v[192:195], v[108:111]
	v_mfma_f32_16x16x32_bf16 v[108:111], v[172:175], v[196:199], v[108:111]
	v_mfma_f32_16x16x32_bf16 v[92:95], v[164:167], v[200:203], v[92:95]
	v_mfma_f32_16x16x32_bf16 v[92:95], v[172:175], v[204:207], v[92:95]
	v_mfma_f32_16x16x32_bf16 v[76:79], v[164:167], v[208:211], v[76:79]
	v_mfma_f32_16x16x32_bf16 v[76:79], v[172:175], v[226:229], v[76:79]
	v_mfma_f32_16x16x32_bf16 v[116:119], v[176:179], v[184:187], v[116:119]
	v_mfma_f32_16x16x32_bf16 v[116:119], v[180:183], v[188:191], v[116:119]
	v_mfma_f32_16x16x32_bf16 v[100:103], v[176:179], v[192:195], v[100:103]
	v_mfma_f32_16x16x32_bf16 v[100:103], v[180:183], v[196:199], v[100:103]
	v_mfma_f32_16x16x32_bf16 v[84:87], v[176:179], v[200:203], v[84:87]
	v_mfma_f32_16x16x32_bf16 v[84:87], v[180:183], v[204:207], v[84:87]
	v_mfma_f32_16x16x32_bf16 v[68:71], v[176:179], v[208:211], v[68:71]
	v_mfma_f32_16x16x32_bf16 v[68:71], v[180:183], v[226:229], v[68:71]
	s_barrier
; #define PG8_STAGE(bufoff, gbase, voff) do { _Pragma("unroll") for (int _i = 0; _i < 2; ++_i) \
;         __builtin_amdgcn_global_load_lds((const unsigned*)((const char*)(gbase) + (voff)[_i]), (PG8_LAS unsigned*)(lds + (bufoff) + ldsw + _i * 8192), 16, 0, 0); } while (0)
; #define PG8_LDA(dst, b, h) do { _Pragma("unroll") for (int m = 0; m < 4; ++m) _Pragma("unroll") for (int k = 0; k < 2; ++k) dst[m][k] = *(const PG8_LAS bf16x8*)(lds + PG8_SA(b, h) + aoffk[k] + m * 2048); } while (0)
; #define PG8_LDB(dst, b, h) do { _Pragma("unroll") for (int n = 0; n < 2; ++n) _Pragma("unroll") for (int k = 0; k < 2; ++k) dst[n][k] = *(const PG8_LAS bf16x8*)(lds + PG8_SB(b, h) + boffk[k] + n * 2048); } while (0)
; #define PG8_MMA(ai, bj, At, Bt) do { __builtin_amdgcn_s_setprio(1); _Pragma("unroll") for (int m = 0; m < 4; ++m) _Pragma("unroll") for (int n = 0; n < 2; ++n) _Pragma("unroll") for (int k = 0; k < 2; ++k) \
;         acc[ai][bj][m][n] = __builtin_amdgcn_mfma_f32_16x16x32_bf16(Bt[n][k], At[m][k], acc[ai][bj][m][n], 0, 0, 0); __builtin_amdgcn_s_setprio(0); } while (0)
; #define PG8_WAIT_V(n) asm volatile("s_waitcnt vmcnt(" #n ")" ::: "memory")
; #define PG8_WAIT_L(n) asm volatile("s_waitcnt lgkmcnt(" #n ")" ::: "memory")
; template <class Epi, class Sched, bool ALIGN_EPI = false, bool SP2 = false>
; __device__ __forceinline__ void gemm_phase(PG8_LAS unsigned char* lds, const Gemm g, const Sched& S, const Epi& E) {
;     ...
;         for (int t = 0; t < nt; t += 2) {
;             const bool last = (t == nt - 2);
;             const char* a1 = cA + (size_t)(t + 1) * kstep;
;             const char* a2 = last ? nA : cA + (size_t)(t + 2) * kstep; const char* b2 = last ? nB : cB + (size_t)(t + 2) * kstep;
;             const char* a3 = a2 + kstep; const char* b3 = b2 + kstep;
;             if (last && has_next) S.a_ready(nxt);
;             if constexpr (SP2) {
;             PG8_LDB(B0, 0, 0); PG8_LDB(B1, 0, 1); PG8_SCHED; PG8_LDA(At, 0, 0); PG8_STAGE(PG8_SA(1, 1), a1 + hstepA, voffA);
;             PG8_WAIT_V(8); PG8_WAIT_L(0); PG8_BAR; PG8_MMA(0, 0, At, B0); PG8_MMA(0, 1, At, B1); PG8_BAR; PG8_SCHED;
;     ...
;             PG8_LDA(At, 1, 1); PG8_STAGE(PG8_SB(1, 0), b3, voffB); PG8_STAGE(PG8_SB(1, 1), b3 + hstepB, voffB); PG8_STAGE(PG8_SA(1, 0), a3, voffA);
;             PG8_WAIT_V(8); PG8_WAIT_L(0); PG8_BAR; PG8_MMA(1, 0, At, B0); PG8_MMA(1, 1, At, B1); PG8_BAR; PG8_SCHED;
	s_add_i32 s22, s47, s31
	v_lshl_add_u64 v[212:213], v[212:213], 0, s[56:57]
	s_mov_b32 m0, s22
	ds_read_b128 v[184:187], v150 offset:49152
	ds_read_b128 v[188:191], v150 offset:50176
	ds_read_b128 v[192:195], v150 offset:51200
	ds_read_b128 v[196:199], v150 offset:52224
	ds_read_b128 v[200:203], v150 offset:53248
	ds_read_b128 v[204:207], v150 offset:54272
	ds_read_b128 v[208:211], v150 offset:55296
	ds_read_b128 v[226:229], v150 offset:56320
	global_load_lds_dwordx4 v[212:213], off
	s_add_i32 m0, s22, 0x2000
	s_add_u32 s20, s20, 0x80080
	v_lshl_add_u64 v[212:213], v[220:221], 0, s[56:57]
	s_addc_u32 s21, s21, 0
	s_add_i32 s22, s48, s31
	global_load_lds_dwordx4 v[212:213], off
	v_lshl_add_u64 v[212:213], s[20:21], 0, v[2:3]
	s_mov_b32 m0, s22
	s_nop 0
	global_load_lds_dwordx4 v[212:213], off
	v_lshl_add_u64 v[212:213], s[20:21], 0, v[132:133]
	s_add_i32 m0, s22, 0x2000
	s_nop 0
	global_load_lds_dwordx4 v[212:213], off
	v_lshl_add_u64 v[212:213], v[230:231], 0, s[56:57]
	s_mov_b32 m0, s40
	s_nop 0
	global_load_lds_dwordx4 v[212:213], off
	v_lshl_add_u64 v[212:213], v[232:233], 0, s[56:57]
	s_mov_b32 m0, s41
	s_nop 0
	global_load_lds_dwordx4 v[212:213], off
	s_waitcnt vmcnt(8)
	s_waitcnt lgkmcnt(0)
	s_barrier
	v_mfma_f32_16x16x32_bf16 v[64:67], v[142:145], v[184:187], v[64:67]
	v_mfma_f32_16x16x32_bf16 v[64:67], v[152:155], v[188:191], v[64:67]
	v_mfma_f32_16x16x32_bf16 v[48:51], v[142:145], v[192:195], v[48:51]
	v_mfma_f32_16x16x32_bf16 v[48:51], v[152:155], v[196:199], v[48:51]
	v_mfma_f32_16x16x32_bf16 v[32:35], v[142:145], v[200:203], v[32:35]
	v_mfma_f32_16x16x32_bf16 v[32:35], v[152:155], v[204:207], v[32:35]
	v_mfma_f32_16x16x32_bf16 v[16:19], v[142:145], v[208:211], v[16:19]
	v_mfma_f32_16x16x32_bf16 v[16:19], v[152:155], v[226:229], v[16:19]
	v_mfma_f32_16x16x32_bf16 v[56:59], v[156:159], v[184:187], v[56:59]
	v_mfma_f32_16x16x32_bf16 v[56:59], v[160:163], v[188:191], v[56:59]
	v_mfma_f32_16x16x32_bf16 v[40:43], v[156:159], v[192:195], v[40:43]
	v_mfma_f32_16x16x32_bf16 v[40:43], v[160:163], v[196:199], v[40:43]
	v_mfma_f32_16x16x32_bf16 v[24:27], v[156:159], v[200:203], v[24:27]
	v_mfma_f32_16x16x32_bf16 v[24:27], v[160:163], v[204:207], v[24:27]
	v_mfma_f32_16x16x32_bf16 v[8:11], v[156:159], v[208:211], v[8:11]
	v_mfma_f32_16x16x32_bf16 v[8:11], v[160:163], v[226:229], v[8:11]
	v_mfma_f32_16x16x32_bf16 v[60:63], v[164:167], v[184:187], v[60:63]
	v_mfma_f32_16x16x32_bf16 v[60:63], v[172:175], v[188:191], v[60:63]
	v_mfma_f32_16x16x32_bf16 v[44:47], v[164:167], v[192:195], v[44:47]
	v_mfma_f32_16x16x32_bf16 v[44:47], v[172:175], v[196:199], v[44:47]
	v_mfma_f32_16x16x32_bf16 v[28:31], v[164:167], v[200:203], v[28:31]
	v_mfma_f32_16x16x32_bf16 v[28:31], v[172:175], v[204:207], v[28:31]
	v_mfma_f32_16x16x32_bf16 v[12:15], v[164:167], v[208:211], v[12:15]
	v_mfma_f32_16x16x32_bf16 v[12:15], v[172:175], v[226:229], v[12:15]
	v_mfma_f32_16x16x32_bf16 v[52:55], v[176:179], v[184:187], v[52:55]
	v_mfma_f32_16x16x32_bf16 v[52:55], v[180:183], v[188:191], v[52:55]
	v_mfma_f32_16x16x32_bf16 v[36:39], v[176:179], v[192:195], v[36:39]
	v_mfma_f32_16x16x32_bf16 v[36:39], v[180:183], v[196:199], v[36:39]
	v_mfma_f32_16x16x32_bf16 v[20:23], v[176:179], v[200:203], v[20:23]
	v_mfma_f32_16x16x32_bf16 v[20:23], v[180:183], v[204:207], v[20:23]
	v_mfma_f32_16x16x32_bf16 v[4:7], v[176:179], v[208:211], v[4:7]
	v_mfma_f32_16x16x32_bf16 v[4:7], v[180:183], v[226:229], v[4:7]
	s_barrier
	s_add_i32 s46, s46, 2
	s_add_u32 s18, s18, 0x100
	s_addc_u32 s19, s19, 0
	s_add_u32 s44, s44, 0x100
	s_addc_u32 s45, s45, 0
	s_cmp_gt_u32 s46, 29
	s_cbranch_scc0 .LBB0_1432
	s_branch .Lgemm_after_4
.LBB0_1432:
	s_add_u32 s20, s18, 0xfff80080
	s_addc_u32 s21, s19, -1
	s_add_i32 s47, 0, 0x10000
	s_cmp_eq_u32 s46, 28
	v_add_u32_e32 v142, s47, v147
	v_add_u32_e32 v151, s47, v148
	s_cselect_b32 s23, s9, s21
	s_cselect_b32 s22, s33, s20
	ds_read_b128 v[142:145], v142
	ds_read_b128 v[152:155], v151
	v_add_u32_e32 v151, s51, v147
	v_add_u32_e32 v160, s51, v148
	s_cselect_b32 s21, s7, s45
	s_cselect_b32 s20, s43, s44
	s_add_i32 s50, 0, 0x14000
	ds_read_b128 v[156:159], v151
	ds_read_b128 v[160:163], v160
	v_add_u32_e32 v151, s50, v147
	v_add_u32_e32 v168, s50, v148
	ds_read_b128 v[164:167], v151
	ds_read_b128 v[172:175], v168
	v_add_u32_e32 v151, s52, v147
	v_add_u32_e32 v168, s52, v148
	ds_read_b128 v[176:179], v151
	ds_read_b128 v[180:183], v168
	v_lshl_add_u64 v[212:213], s[18:19], 0, v[138:139]
	s_add_i32 m0, s36, 0xc000
	ds_read_b128 v[184:187], v150
	ds_read_b128 v[188:191], v150 offset:1024
	ds_read_b128 v[192:195], v150 offset:2048
	ds_read_b128 v[196:199], v150 offset:3072
	ds_read_b128 v[200:203], v150 offset:4096
	ds_read_b128 v[204:207], v150 offset:5120
	ds_read_b128 v[208:211], v150 offset:6144
	ds_read_b128 v[226:229], v150 offset:7168
	global_load_lds_dwordx4 v[212:213], off
	v_lshl_add_u64 v[212:213], s[18:19], 0, v[140:141]
	s_add_i32 m0, s36, 0xe000
	s_nop 0
	global_load_lds_dwordx4 v[212:213], off
	s_waitcnt vmcnt(8)
	s_waitcnt lgkmcnt(0)
	s_barrier
; #define PG8_STAGE(bufoff, gbase, voff) do { _Pragma("unroll") for (int _i = 0; _i < 2; ++_i) \
;         __builtin_amdgcn_global_load_lds((const unsigned*)((const char*)(gbase) + (voff)[_i]), (PG8_LAS unsigned*)(lds + (bufoff) + ldsw + _i * 8192), 16, 0, 0); } while (0)
; #define PG8_LDA(dst, b, h) do { _Pragma("unroll") for (int m = 0; m < 4; ++m) _Pragma("unroll") for (int k = 0; k < 2; ++k) dst[m][k] = *(const PG8_LAS bf16x8*)(lds + PG8_SA(b, h) + aoffk[k] + m * 2048); } while (0)
; #define PG8_MMA(ai, bj, At, Bt) do { __builtin_amdgcn_s_setprio(1); _Pragma("unroll") for (int m = 0; m < 4; ++m) _Pragma("unroll") for (int n = 0; n < 2; ++n) _Pragma("unroll") for (int k = 0; k < 2; ++k) \
;         acc[ai][bj][m][n] = __builtin_amdgcn_mfma_f32_16x16x32_bf16(Bt[n][k], At[m][k], acc[ai][bj][m][n], 0, 0, 0); __builtin_amdgcn_s_setprio(0); } while (0)
; #define PG8_WAIT_V(n) asm volatile("s_waitcnt vmcnt(" #n ")" ::: "memory")
; #define PG8_WAIT_L(n) asm volatile("s_waitcnt lgkmcnt(" #n ")" ::: "memory")
; #define PG8_BAR __builtin_amdgcn_s_barrier()
; #define PG8_SCHED __builtin_amdgcn_sched_barrier(0)
; template <class Epi, class Sched, bool ALIGN_EPI = false, bool SP2 = false>
; __device__ __forceinline__ void gemm_phase(PG8_LAS unsigned char* lds, const Gemm g, const Sched& S, const Epi& E) {
;     ...
;             PG8_WAIT_V(8); PG8_WAIT_L(0); PG8_BAR; PG8_MMA(0, 0, At, B0); PG8_MMA(0, 1, At, B1); PG8_BAR; PG8_SCHED;
;             PG8_LDA(At, 0, 1); PG8_STAGE(PG8_SB(0, 0), b2, voffB); PG8_STAGE(PG8_SB(0, 1), b2 + hstepB, voffB); PG8_STAGE(PG8_SA(0, 0), a2, voffA);
;             PG8_WAIT_V(8); PG8_WAIT_L(0); PG8_BAR; PG8_MMA(1, 0, At, B0); PG8_MMA(1, 1, At, B1); PG8_BAR; PG8_SCHED;
	v_mfma_f32_16x16x32_bf16 v[128:131], v[142:145], v[184:187], v[128:131]
	v_mfma_f32_16x16x32_bf16 v[128:131], v[152:155], v[188:191], v[128:131]
	v_mfma_f32_16x16x32_bf16 v[112:115], v[142:145], v[192:195], v[112:115]
	v_mfma_f32_16x16x32_bf16 v[112:115], v[152:155], v[196:199], v[112:115]
	v_mfma_f32_16x16x32_bf16 v[96:99], v[142:145], v[200:203], v[96:99]
	v_mfma_f32_16x16x32_bf16 v[96:99], v[152:155], v[204:207], v[96:99]
	v_mfma_f32_16x16x32_bf16 v[80:83], v[142:145], v[208:211], v[80:83]
	v_mfma_f32_16x16x32_bf16 v[80:83], v[152:155], v[226:229], v[80:83]
	v_mfma_f32_16x16x32_bf16 v[120:123], v[156:159], v[184:187], v[120:123]
	v_mfma_f32_16x16x32_bf16 v[120:123], v[160:163], v[188:191], v[120:123]
	v_mfma_f32_16x16x32_bf16 v[104:107], v[156:159], v[192:195], v[104:107]
	v_mfma_f32_16x16x32_bf16 v[104:107], v[160:163], v[196:199], v[104:107]
	v_mfma_f32_16x16x32_bf16 v[88:91], v[156:159], v[200:203], v[88:91]
	v_mfma_f32_16x16x32_bf16 v[88:91], v[160:163], v[204:207], v[88:91]
	v_mfma_f32_16x16x32_bf16 v[72:75], v[156:159], v[208:211], v[72:75]
	v_mfma_f32_16x16x32_bf16 v[72:75], v[160:163], v[226:229], v[72:75]
	v_mfma_f32_16x16x32_bf16 v[124:127], v[164:167], v[184:187], v[124:127]
	v_mfma_f32_16x16x32_bf16 v[124:127], v[172:175], v[188:191], v[124:127]
	v_mfma_f32_16x16x32_bf16 v[108:111], v[164:167], v[192:195], v[108:111]
	v_mfma_f32_16x16x32_bf16 v[108:111], v[172:175], v[196:199], v[108:111]
	v_mfma_f32_16x16x32_bf16 v[92:95], v[164:167], v[200:203], v[92:95]
	v_mfma_f32_16x16x32_bf16 v[92:95], v[172:175], v[204:207], v[92:95]
	v_mfma_f32_16x16x32_bf16 v[76:79], v[164:167], v[208:211], v[76:79]
	v_mfma_f32_16x16x32_bf16 v[76:79], v[172:175], v[226:229], v[76:79]
	v_mfma_f32_16x16x32_bf16 v[116:119], v[176:179], v[184:187], v[116:119]
	v_mfma_f32_16x16x32_bf16 v[116:119], v[180:183], v[188:191], v[116:119]
	v_mfma_f32_16x16x32_bf16 v[100:103], v[176:179], v[192:195], v[100:103]
	v_mfma_f32_16x16x32_bf16 v[100:103], v[180:183], v[196:199], v[100:103]
	v_mfma_f32_16x16x32_bf16 v[84:87], v[176:179], v[200:203], v[84:87]
	v_mfma_f32_16x16x32_bf16 v[84:87], v[180:183], v[204:207], v[84:87]
	v_mfma_f32_16x16x32_bf16 v[68:71], v[176:179], v[208:211], v[68:71]
	v_mfma_f32_16x16x32_bf16 v[68:71], v[180:183], v[226:229], v[68:71]
	s_barrier
	s_add_i32 s47, s47, s31
	v_lshl_add_u64 v[212:213], s[20:21], 0, v[2:3]
	s_mov_b32 m0, s47
	ds_read_b128 v[184:187], v150 offset:16384
	ds_read_b128 v[188:191], v150 offset:17408
	ds_read_b128 v[192:195], v150 offset:18432
	ds_read_b128 v[196:199], v150 offset:19456
	ds_read_b128 v[200:203], v150 offset:20480
	ds_read_b128 v[204:207], v150 offset:21504
	ds_read_b128 v[208:211], v150 offset:22528
	ds_read_b128 v[226:229], v150 offset:23552
	global_load_lds_dwordx4 v[212:213], off
	s_add_i32 m0, s47, 0x2000
	s_add_u32 s48, s20, 0x80000
	v_lshl_add_u64 v[220:221], s[20:21], 0, v[132:133]
	s_addc_u32 s49, s21, 0
	s_add_i32 s47, s50, s31
	global_load_lds_dwordx4 v[220:221], off
	v_lshl_add_u64 v[230:231], s[48:49], 0, v[2:3]
	s_mov_b32 m0, s47
	v_lshl_add_u64 v[232:233], s[22:23], 0, v[134:135]
	global_load_lds_dwordx4 v[230:231], off
	v_lshl_add_u64 v[230:231], s[48:49], 0, v[132:133]
	s_add_i32 m0, s47, 0x2000
	s_nop 0
	global_load_lds_dwordx4 v[230:231], off
	v_lshl_add_u64 v[230:231], s[22:23], 0, v[136:137]
	s_mov_b32 m0, s36
	s_nop 0
	global_load_lds_dwordx4 v[230:231], off
	s_mov_b32 m0, s37
	s_nop 0
	global_load_lds_dwordx4 v[232:233], off
	s_waitcnt vmcnt(8)
	s_waitcnt lgkmcnt(0)
	s_barrier
	v_mfma_f32_16x16x32_bf16 v[64:67], v[142:145], v[184:187], v[64:67]
	v_mfma_f32_16x16x32_bf16 v[64:67], v[152:155], v[188:191], v[64:67]
	v_mfma_f32_16x16x32_bf16 v[48:51], v[142:145], v[192:195], v[48:51]
	v_mfma_f32_16x16x32_bf16 v[48:51], v[152:155], v[196:199], v[48:51]
	v_mfma_f32_16x16x32_bf16 v[32:35], v[142:145], v[200:203], v[32:35]
	v_mfma_f32_16x16x32_bf16 v[32:35], v[152:155], v[204:207], v[32:35]
	v_mfma_f32_16x16x32_bf16 v[16:19], v[142:145], v[208:211], v[16:19]
	v_mfma_f32_16x16x32_bf16 v[16:19], v[152:155], v[226:229], v[16:19]
	v_mfma_f32_16x16x32_bf16 v[56:59], v[156:159], v[184:187], v[56:59]
	v_mfma_f32_16x16x32_bf16 v[56:59], v[160:163], v[188:191], v[56:59]
	v_mfma_f32_16x16x32_bf16 v[40:43], v[156:159], v[192:195], v[40:43]
	v_mfma_f32_16x16x32_bf16 v[40:43], v[160:163], v[196:199], v[40:43]
	v_mfma_f32_16x16x32_bf16 v[24:27], v[156:159], v[200:203], v[24:27]
	v_mfma_f32_16x16x32_bf16 v[24:27], v[160:163], v[204:207], v[24:27]
	v_mfma_f32_16x16x32_bf16 v[8:11], v[156:159], v[208:211], v[8:11]
	v_mfma_f32_16x16x32_bf16 v[8:11], v[160:163], v[226:229], v[8:11]
	v_mfma_f32_16x16x32_bf16 v[60:63], v[164:167], v[184:187], v[60:63]
	v_mfma_f32_16x16x32_bf16 v[60:63], v[172:175], v[188:191], v[60:63]
	v_mfma_f32_16x16x32_bf16 v[44:47], v[164:167], v[192:195], v[44:47]
	v_mfma_f32_16x16x32_bf16 v[44:47], v[172:175], v[196:199], v[44:47]
	v_mfma_f32_16x16x32_bf16 v[28:31], v[164:167], v[200:203], v[28:31]
	v_mfma_f32_16x16x32_bf16 v[28:31], v[172:175], v[204:207], v[28:31]
	v_mfma_f32_16x16x32_bf16 v[12:15], v[164:167], v[208:211], v[12:15]
	v_mfma_f32_16x16x32_bf16 v[12:15], v[172:175], v[226:229], v[12:15]
	v_mfma_f32_16x16x32_bf16 v[52:55], v[176:179], v[184:187], v[52:55]
	v_mfma_f32_16x16x32_bf16 v[52:55], v[180:183], v[188:191], v[52:55]
	v_mfma_f32_16x16x32_bf16 v[36:39], v[176:179], v[192:195], v[36:39]
	v_mfma_f32_16x16x32_bf16 v[36:39], v[180:183], v[196:199], v[36:39]
	v_mfma_f32_16x16x32_bf16 v[20:23], v[176:179], v[200:203], v[20:23]
	v_mfma_f32_16x16x32_bf16 v[20:23], v[180:183], v[204:207], v[20:23]
	v_mfma_f32_16x16x32_bf16 v[4:7], v[176:179], v[208:211], v[4:7]
	v_mfma_f32_16x16x32_bf16 v[4:7], v[180:183], v[226:229], v[4:7]
	s_barrier
; #define PG8_STAGE(bufoff, gbase, voff) do { _Pragma("unroll") for (int _i = 0; _i < 2; ++_i) \
;         __builtin_amdgcn_global_load_lds((const unsigned*)((const char*)(gbase) + (voff)[_i]), (PG8_LAS unsigned*)(lds + (bufoff) + ldsw + _i * 8192), 16, 0, 0); } while (0)
; #define PG8_LDA(dst, b, h) do { _Pragma("unroll") for (int m = 0; m < 4; ++m) _Pragma("unroll") for (int k = 0; k < 2; ++k) dst[m][k] = *(const PG8_LAS bf16x8*)(lds + PG8_SA(b, h) + aoffk[k] + m * 2048); } while (0)
; #define PG8_LDB(dst, b, h) do { _Pragma("unroll") for (int n = 0; n < 2; ++n) _Pragma("unroll") for (int k = 0; k < 2; ++k) dst[n][k] = *(const PG8_LAS bf16x8*)(lds + PG8_SB(b, h) + boffk[k] + n * 2048); } while (0)
; #define PG8_MMA(ai, bj, At, Bt) do { __builtin_amdgcn_s_setprio(1); _Pragma("unroll") for (int m = 0; m < 4; ++m) _Pragma("unroll") for (int n = 0; n < 2; ++n) _Pragma("unroll") for (int k = 0; k < 2; ++k) \
;         acc[ai][bj][m][n] = __builtin_amdgcn_mfma_f32_16x16x32_bf16(Bt[n][k], At[m][k], acc[ai][bj][m][n], 0, 0, 0); __builtin_amdgcn_s_setprio(0); } while (0)
; #define PG8_WAIT_V(n) asm volatile("s_waitcnt vmcnt(" #n ")" ::: "memory")
; #define PG8_WAIT_L(n) asm volatile("s_waitcnt lgkmcnt(" #n ")" ::: "memory")
; #define PG8_BAR __builtin_amdgcn_s_barrier()
; #define PG8_SCHED __builtin_amdgcn_sched_barrier(0)
; template <class Epi, class Sched, bool ALIGN_EPI = false, bool SP2 = false>
; __device__ __forceinline__ void gemm_phase(PG8_LAS unsigned char* lds, const Gemm g, const Sched& S, const Epi& E) {
;     ...
;             PG8_LDB(B0, 1, 0); PG8_LDB(B1, 1, 1); PG8_SCHED; PG8_LDA(At, 1, 0); PG8_STAGE(PG8_SA(0, 1), a2 + hstepA, voffA);
;             PG8_WAIT_V(8); PG8_WAIT_L(0); PG8_BAR; PG8_MMA(0, 0, At, B0); PG8_MMA(0, 1, At, B1); PG8_BAR; PG8_SCHED;
	s_add_i32 s47, 0, 0x18000
	v_add_u32_e32 v142, s47, v147
	v_add_u32_e32 v151, s47, v148
	ds_read_b128 v[142:145], v142
	ds_read_b128 v[152:155], v151
	v_add_u32_e32 v151, s53, v147
	v_add_u32_e32 v160, s53, v148
	s_add_i32 s48, 0, 0x1c000
	ds_read_b128 v[156:159], v151
	ds_read_b128 v[160:163], v160
	v_add_u32_e32 v151, s48, v147
	v_add_u32_e32 v168, s48, v148
	ds_read_b128 v[164:167], v151
	ds_read_b128 v[172:175], v168
	v_add_u32_e32 v151, s54, v147
	v_add_u32_e32 v168, s54, v148
	ds_read_b128 v[176:179], v151
	ds_read_b128 v[180:183], v168
	s_add_u32 s22, s22, 0x80000
	s_addc_u32 s23, s23, 0
	s_mov_b32 m0, s38
	v_lshl_add_u64 v[234:235], s[22:23], 0, v[136:137]
	ds_read_b128 v[184:187], v150 offset:32768
	ds_read_b128 v[188:191], v150 offset:33792
	ds_read_b128 v[192:195], v150 offset:34816
	ds_read_b128 v[196:199], v150 offset:35840
	ds_read_b128 v[200:203], v150 offset:36864
	ds_read_b128 v[204:207], v150 offset:37888
	ds_read_b128 v[208:211], v150 offset:38912
	ds_read_b128 v[226:229], v150 offset:39936
	global_load_lds_dwordx4 v[234:235], off
	v_lshl_add_u64 v[234:235], s[22:23], 0, v[134:135]
	s_mov_b32 m0, s39
	s_nop 0
	global_load_lds_dwordx4 v[234:235], off
	s_waitcnt vmcnt(8)
	s_waitcnt lgkmcnt(0)
	s_barrier
	v_mfma_f32_16x16x32_bf16 v[128:131], v[142:145], v[184:187], v[128:131]
	v_mfma_f32_16x16x32_bf16 v[128:131], v[152:155], v[188:191], v[128:131]
	v_mfma_f32_16x16x32_bf16 v[112:115], v[142:145], v[192:195], v[112:115]
	v_mfma_f32_16x16x32_bf16 v[112:115], v[152:155], v[196:199], v[112:115]
	v_mfma_f32_16x16x32_bf16 v[96:99], v[142:145], v[200:203], v[96:99]
	v_mfma_f32_16x16x32_bf16 v[96:99], v[152:155], v[204:207], v[96:99]
	v_mfma_f32_16x16x32_bf16 v[80:83], v[142:145], v[208:211], v[80:83]
	v_mfma_f32_16x16x32_bf16 v[80:83], v[152:155], v[226:229], v[80:83]
	v_mfma_f32_16x16x32_bf16 v[120:123], v[156:159], v[184:187], v[120:123]
	v_mfma_f32_16x16x32_bf16 v[120:123], v[160:163], v[188:191], v[120:123]
	v_mfma_f32_16x16x32_bf16 v[104:107], v[156:159], v[192:195], v[104:107]
	v_mfma_f32_16x16x32_bf16 v[104:107], v[160:163], v[196:199], v[104:107]
	v_mfma_f32_16x16x32_bf16 v[88:91], v[156:159], v[200:203], v[88:91]
	v_mfma_f32_16x16x32_bf16 v[88:91], v[160:163], v[204:207], v[88:91]
	v_mfma_f32_16x16x32_bf16 v[72:75], v[156:159], v[208:211], v[72:75]
	v_mfma_f32_16x16x32_bf16 v[72:75], v[160:163], v[226:229], v[72:75]
	v_mfma_f32_16x16x32_bf16 v[124:127], v[164:167], v[184:187], v[124:127]
	v_mfma_f32_16x16x32_bf16 v[124:127], v[172:175], v[188:191], v[124:127]
	v_mfma_f32_16x16x32_bf16 v[108:111], v[164:167], v[192:195], v[108:111]
	v_mfma_f32_16x16x32_bf16 v[108:111], v[172:175], v[196:199], v[108:111]
	v_mfma_f32_16x16x32_bf16 v[92:95], v[164:167], v[200:203], v[92:95]
	v_mfma_f32_16x16x32_bf16 v[92:95], v[172:175], v[204:207], v[92:95]
	v_mfma_f32_16x16x32_bf16 v[76:79], v[164:167], v[208:211], v[76:79]
	v_mfma_f32_16x16x32_bf16 v[76:79], v[172:175], v[226:229], v[76:79]
	v_mfma_f32_16x16x32_bf16 v[116:119], v[176:179], v[184:187], v[116:119]
	v_mfma_f32_16x16x32_bf16 v[116:119], v[180:183], v[188:191], v[116:119]
	v_mfma_f32_16x16x32_bf16 v[100:103], v[176:179], v[192:195], v[100:103]
	v_mfma_f32_16x16x32_bf16 v[100:103], v[180:183], v[196:199], v[100:103]
	v_mfma_f32_16x16x32_bf16 v[84:87], v[176:179], v[200:203], v[84:87]
	v_mfma_f32_16x16x32_bf16 v[84:87], v[180:183], v[204:207], v[84:87]
	v_mfma_f32_16x16x32_bf16 v[68:71], v[176:179], v[208:211], v[68:71]
	v_mfma_f32_16x16x32_bf16 v[68:71], v[180:183], v[226:229], v[68:71]
	s_barrier
; #define PG8_STAGE(bufoff, gbase, voff) do { _Pragma("unroll") for (int _i = 0; _i < 2; ++_i) \
;         __builtin_amdgcn_global_load_lds((const unsigned*)((const char*)(gbase) + (voff)[_i]), (PG8_LAS unsigned*)(lds + (bufoff) + ldsw + _i * 8192), 16, 0, 0); } while (0)
; #define PG8_LDA(dst, b, h) do { _Pragma("unroll") for (int m = 0; m < 4; ++m) _Pragma("unroll") for (int k = 0; k < 2; ++k) dst[m][k] = *(const PG8_LAS bf16x8*)(lds + PG8_SA(b, h) + aoffk[k] + m * 2048); } while (0)
; #define PG8_MMA(ai, bj, At, Bt) do { __builtin_amdgcn_s_setprio(1); _Pragma("unroll") for (int m = 0; m < 4; ++m) _Pragma("unroll") for (int n = 0; n < 2; ++n) _Pragma("unroll") for (int k = 0; k < 2; ++k) \
;         acc[ai][bj][m][n] = __builtin_amdgcn_mfma_f32_16x16x32_bf16(Bt[n][k], At[m][k], acc[ai][bj][m][n], 0, 0, 0); __builtin_amdgcn_s_setprio(0); } while (0)
; #define PG8_WAIT_V(n) asm volatile("s_waitcnt vmcnt(" #n ")" ::: "memory")
; #define PG8_WAIT_L(n) asm volatile("s_waitcnt lgkmcnt(" #n ")" ::: "memory")
; #define PG8_BAR __builtin_amdgcn_s_barrier()
; #define PG8_SCHED __builtin_amdgcn_sched_barrier(0)
; template <class Epi, class Sched, bool ALIGN_EPI = false, bool SP2 = false>
; __device__ __forceinline__ void gemm_phase(PG8_LAS unsigned char* lds, const Gemm g, const Sched& S, const Epi& E) {
;     ...
;         for (int t = 0; t < nt; t += 2) {
;             const bool last = (t == nt - 2);
;             const char* a1 = cA + (size_t)(t + 1) * kstep;
;             const char* a2 = last ? nA : cA + (size_t)(t + 2) * kstep; const char* b2 = last ? nB : cB + (size_t)(t + 2) * kstep;
;             const char* a3 = a2 + kstep; const char* b3 = b2 + kstep;
;     ...
;             PG8_LDA(At, 1, 1); PG8_STAGE(PG8_SB(1, 0), b3, voffB); PG8_STAGE(PG8_SB(1, 1), b3 + hstepB, voffB); PG8_STAGE(PG8_SA(1, 0), a3, voffA);
;             PG8_WAIT_V(8); PG8_WAIT_L(0); PG8_BAR; PG8_MMA(1, 0, At, B0); PG8_MMA(1, 1, At, B1); PG8_BAR; PG8_SCHED;
	s_add_i32 s22, s47, s31
	v_lshl_add_u64 v[212:213], v[212:213], 0, s[56:57]
	s_mov_b32 m0, s22
	ds_read_b128 v[184:187], v150 offset:49152
	ds_read_b128 v[188:191], v150 offset:50176
	ds_read_b128 v[192:195], v150 offset:51200
	ds_read_b128 v[196:199], v150 offset:52224
	ds_read_b128 v[200:203], v150 offset:53248
	ds_read_b128 v[204:207], v150 offset:54272
	ds_read_b128 v[208:211], v150 offset:55296
	ds_read_b128 v[226:229], v150 offset:56320
	global_load_lds_dwordx4 v[212:213], off
	s_add_i32 m0, s22, 0x2000
	s_add_u32 s20, s20, 0x80080
	v_lshl_add_u64 v[212:213], v[220:221], 0, s[56:57]
	s_addc_u32 s21, s21, 0
	s_add_i32 s22, s48, s31
	global_load_lds_dwordx4 v[212:213], off
	v_lshl_add_u64 v[212:213], s[20:21], 0, v[2:3]
	s_mov_b32 m0, s22
	s_nop 0
	global_load_lds_dwordx4 v[212:213], off
	v_lshl_add_u64 v[212:213], s[20:21], 0, v[132:133]
	s_add_i32 m0, s22, 0x2000
	s_nop 0
	global_load_lds_dwordx4 v[212:213], off
	v_lshl_add_u64 v[212:213], v[230:231], 0, s[56:57]
	s_mov_b32 m0, s40
	s_nop 0
	global_load_lds_dwordx4 v[212:213], off
	v_lshl_add_u64 v[212:213], v[232:233], 0, s[56:57]
	s_mov_b32 m0, s41
	s_nop 0
	global_load_lds_dwordx4 v[212:213], off
	s_waitcnt vmcnt(8)
	s_waitcnt lgkmcnt(0)
	s_barrier
	v_mfma_f32_16x16x32_bf16 v[64:67], v[142:145], v[184:187], v[64:67]
	v_mfma_f32_16x16x32_bf16 v[64:67], v[152:155], v[188:191], v[64:67]
	v_mfma_f32_16x16x32_bf16 v[48:51], v[142:145], v[192:195], v[48:51]
	v_mfma_f32_16x16x32_bf16 v[48:51], v[152:155], v[196:199], v[48:51]
	v_mfma_f32_16x16x32_bf16 v[32:35], v[142:145], v[200:203], v[32:35]
	v_mfma_f32_16x16x32_bf16 v[32:35], v[152:155], v[204:207], v[32:35]
	v_mfma_f32_16x16x32_bf16 v[16:19], v[142:145], v[208:211], v[16:19]
	v_mfma_f32_16x16x32_bf16 v[16:19], v[152:155], v[226:229], v[16:19]
	v_mfma_f32_16x16x32_bf16 v[56:59], v[156:159], v[184:187], v[56:59]
	v_mfma_f32_16x16x32_bf16 v[56:59], v[160:163], v[188:191], v[56:59]
	v_mfma_f32_16x16x32_bf16 v[40:43], v[156:159], v[192:195], v[40:43]
	v_mfma_f32_16x16x32_bf16 v[40:43], v[160:163], v[196:199], v[40:43]
	v_mfma_f32_16x16x32_bf16 v[24:27], v[156:159], v[200:203], v[24:27]
	v_mfma_f32_16x16x32_bf16 v[24:27], v[160:163], v[204:207], v[24:27]
	v_mfma_f32_16x16x32_bf16 v[8:11], v[156:159], v[208:211], v[8:11]
	v_mfma_f32_16x16x32_bf16 v[8:11], v[160:163], v[226:229], v[8:11]
	v_mfma_f32_16x16x32_bf16 v[60:63], v[164:167], v[184:187], v[60:63]
	v_mfma_f32_16x16x32_bf16 v[60:63], v[172:175], v[188:191], v[60:63]
	v_mfma_f32_16x16x32_bf16 v[44:47], v[164:167], v[192:195], v[44:47]
	v_mfma_f32_16x16x32_bf16 v[44:47], v[172:175], v[196:199], v[44:47]
	v_mfma_f32_16x16x32_bf16 v[28:31], v[164:167], v[200:203], v[28:31]
	v_mfma_f32_16x16x32_bf16 v[28:31], v[172:175], v[204:207], v[28:31]
	v_mfma_f32_16x16x32_bf16 v[12:15], v[164:167], v[208:211], v[12:15]
	v_mfma_f32_16x16x32_bf16 v[12:15], v[172:175], v[226:229], v[12:15]
	v_mfma_f32_16x16x32_bf16 v[52:55], v[176:179], v[184:187], v[52:55]
	v_mfma_f32_16x16x32_bf16 v[52:55], v[180:183], v[188:191], v[52:55]
	v_mfma_f32_16x16x32_bf16 v[36:39], v[176:179], v[192:195], v[36:39]
	v_mfma_f32_16x16x32_bf16 v[36:39], v[180:183], v[196:199], v[36:39]
	v_mfma_f32_16x16x32_bf16 v[20:23], v[176:179], v[200:203], v[20:23]
	v_mfma_f32_16x16x32_bf16 v[20:23], v[180:183], v[204:207], v[20:23]
	v_mfma_f32_16x16x32_bf16 v[4:7], v[176:179], v[208:211], v[4:7]
	v_mfma_f32_16x16x32_bf16 v[4:7], v[180:183], v[226:229], v[4:7]
	s_barrier
	s_add_i32 s46, s46, 2
	s_add_u32 s18, s18, 0x100
	s_addc_u32 s19, s19, 0
	s_add_u32 s44, s44, 0x100
	s_addc_u32 s45, s45, 0
	s_cmp_gt_u32 s46, 29
	s_cbranch_scc0 .LBB0_1432

; #define PG8_STAGE(bufoff, gbase, voff) do { _Pragma("unroll") for (int _i = 0; _i < 2; ++_i) \
;         __builtin_amdgcn_global_load_lds((const unsigned*)((const char*)(gbase) + (voff)[_i]), (PG8_LAS unsigned*)(lds + (bufoff) + ldsw + _i * 8192), 16, 0, 0); } while (0)
; #define PG8_LDA(dst, b, h) do { _Pragma("unroll") for (int m = 0; m < 4; ++m) _Pragma("unroll") for (int k = 0; k < 2; ++k) dst[m][k] = *(const PG8_LAS bf16x8*)(lds + PG8_SA(b, h) + aoffk[k] + m * 2048); } while (0)
; #define PG8_LDB(dst, b, h) do { _Pragma("unroll") for (int n = 0; n < 2; ++n) _Pragma("unroll") for (int k = 0; k < 2; ++k) dst[n][k] = *(const PG8_LAS bf16x8*)(lds + PG8_SB(b, h) + boffk[k] + n * 2048); } while (0)
; #define PG8_MMA(ai, bj, At, Bt) do { __builtin_amdgcn_s_setprio(1); _Pragma("unroll") for (int m = 0; m < 4; ++m) _Pragma("unroll") for (int n = 0; n < 2; ++n) _Pragma("unroll") for (int k = 0; k < 2; ++k) \
;         acc[ai][bj][m][n] = __builtin_amdgcn_mfma_f32_16x16x32_bf16(Bt[n][k], At[m][k], acc[ai][bj][m][n], 0, 0, 0); __builtin_amdgcn_s_setprio(0); } while (0)
; #define PG8_WAIT_V(n) asm volatile("s_waitcnt vmcnt(" #n ")" ::: "memory")
; #define PG8_WAIT_L(n) asm volatile("s_waitcnt lgkmcnt(" #n ")" ::: "memory")
; template <class Epi, class Sched, bool ALIGN_EPI = false, bool SP2 = false>
; __device__ __forceinline__ void gemm_phase(PG8_LAS unsigned char* lds, const Gemm g, const Sched& S, const Epi& E) {
;     ...
;         for (int t = 0; t < nt; t += 2) {
;             const bool last = (t == nt - 2);
;             const char* a1 = cA + (size_t)(t + 1) * kstep;
;             const char* a2 = last ? nA : cA + (size_t)(t + 2) * kstep; const char* b2 = last ? nB : cB + (size_t)(t + 2) * kstep;
;             const char* a3 = a2 + kstep; const char* b3 = b2 + kstep;
;             if (last && has_next) S.a_ready(nxt);
;             if constexpr (SP2) {
;             PG8_LDB(B0, 0, 0); PG8_LDB(B1, 0, 1); PG8_SCHED; PG8_LDA(At, 0, 0); PG8_STAGE(PG8_SA(1, 1), a1 + hstepA, voffA);
;             PG8_WAIT_V(8); PG8_WAIT_L(0); PG8_BAR; PG8_MMA(0, 0, At, B0); PG8_MMA(0, 1, At, B1); PG8_BAR; PG8_SCHED;
;             PG8_LDA(At, 0, 1); PG8_STAGE(PG8_SB(0, 0), b2, voffB); PG8_STAGE(PG8_SB(0, 1), b2 + hstepB, voffB); PG8_STAGE(PG8_SA(0, 0), a2, voffA);
;             PG8_WAIT_V(8); PG8_WAIT_L(0); PG8_BAR; PG8_MMA(1, 0, At, B0); PG8_MMA(1, 1, At, B1); PG8_BAR; PG8_SCHED;
.Lgemm_first_5:
	s_add_i32 s50, s16, 2
	s_add_u32 s14, s12, 0x100
	s_addc_u32 s15, s13, 0
	s_add_i32 s51, 0, 0x10000
	s_cmp_eq_u32 s7, s16
	v_add_u32_e32 v142, s51, v145
	s_cselect_b32 s19, s9, s15
	s_cselect_b32 s18, s8, s14
	v_add_u32_e32 v143, s51, v146
	ds_read_b128 v[150:153], v142
	ds_read_b128 v[154:157], v143
	v_add_u32_e32 v142, s53, v145
	s_cselect_b32 s17, s11, s49
	s_cselect_b32 s16, s10, s48
	s_add_i32 s52, 0, 0x14000
	v_add_u32_e32 v143, s53, v146
	ds_read_b128 v[158:161], v142
	ds_read_b128 v[162:165], v143
	v_add_u32_e32 v142, s52, v145
	v_add_u32_e32 v143, s52, v146
	ds_read_b128 v[172:175], v142
	ds_read_b128 v[176:179], v143
	v_add_u32_e32 v142, s54, v145
	v_add_u32_e32 v143, s54, v146
	ds_read_b128 v[180:183], v142
	ds_read_b128 v[184:187], v143
	v_lshl_add_u64 v[142:143], s[12:13], 0, v[138:139]
	s_add_i32 m0, s26, 0xc000
	ds_read_b128 v[188:191], v148
	ds_read_b128 v[192:195], v148 offset:1024
	ds_read_b128 v[196:199], v148 offset:2048
	ds_read_b128 v[200:203], v148 offset:3072
	ds_read_b128 v[204:207], v148 offset:4096
	ds_read_b128 v[208:211], v148 offset:5120
	ds_read_b128 v[226:229], v148 offset:6144
	ds_read_b128 v[230:233], v148 offset:7168
	global_load_lds_dwordx4 v[142:143], off
	v_lshl_add_u64 v[142:143], s[12:13], 0, v[140:141]
	s_add_i32 m0, s26, 0xe000
	s_nop 0
	global_load_lds_dwordx4 v[142:143], off
	s_waitcnt vmcnt(8)
	s_waitcnt lgkmcnt(0)
	s_barrier
	v_mfma_f32_16x16x32_bf16 v[128:131], v[150:153], v[188:191], 0
	v_mfma_f32_16x16x32_bf16 v[128:131], v[154:157], v[192:195], v[128:131]
	v_mfma_f32_16x16x32_bf16 v[120:123], v[150:153], v[196:199], 0
	v_mfma_f32_16x16x32_bf16 v[120:123], v[154:157], v[200:203], v[120:123]
	v_mfma_f32_16x16x32_bf16 v[104:107], v[150:153], v[204:207], 0
	v_mfma_f32_16x16x32_bf16 v[104:107], v[154:157], v[208:211], v[104:107]
	v_mfma_f32_16x16x32_bf16 v[88:91], v[150:153], v[226:229], 0
	v_mfma_f32_16x16x32_bf16 v[88:91], v[154:157], v[230:233], v[88:91]
	v_mfma_f32_16x16x32_bf16 v[124:127], v[158:161], v[188:191], 0
	v_mfma_f32_16x16x32_bf16 v[124:127], v[162:165], v[192:195], v[124:127]
	v_mfma_f32_16x16x32_bf16 v[112:115], v[158:161], v[196:199], 0
	v_mfma_f32_16x16x32_bf16 v[112:115], v[162:165], v[200:203], v[112:115]
	v_mfma_f32_16x16x32_bf16 v[96:99], v[158:161], v[204:207], 0
	v_mfma_f32_16x16x32_bf16 v[96:99], v[162:165], v[208:211], v[96:99]
	v_mfma_f32_16x16x32_bf16 v[80:83], v[158:161], v[226:229], 0
	v_mfma_f32_16x16x32_bf16 v[80:83], v[162:165], v[230:233], v[80:83]
	v_mfma_f32_16x16x32_bf16 v[116:119], v[172:175], v[188:191], 0
	v_mfma_f32_16x16x32_bf16 v[116:119], v[176:179], v[192:195], v[116:119]
	v_mfma_f32_16x16x32_bf16 v[100:103], v[172:175], v[196:199], 0
	v_mfma_f32_16x16x32_bf16 v[100:103], v[176:179], v[200:203], v[100:103]
	v_mfma_f32_16x16x32_bf16 v[84:87], v[172:175], v[204:207], 0
	v_mfma_f32_16x16x32_bf16 v[84:87], v[176:179], v[208:211], v[84:87]
	v_mfma_f32_16x16x32_bf16 v[72:75], v[172:175], v[226:229], 0
	v_mfma_f32_16x16x32_bf16 v[72:75], v[176:179], v[230:233], v[72:75]
	v_mfma_f32_16x16x32_bf16 v[108:111], v[180:183], v[188:191], 0
	v_mfma_f32_16x16x32_bf16 v[108:111], v[184:187], v[192:195], v[108:111]
	v_mfma_f32_16x16x32_bf16 v[92:95], v[180:183], v[196:199], 0
	v_mfma_f32_16x16x32_bf16 v[92:95], v[184:187], v[200:203], v[92:95]
	v_mfma_f32_16x16x32_bf16 v[76:79], v[180:183], v[204:207], 0
	v_mfma_f32_16x16x32_bf16 v[76:79], v[184:187], v[208:211], v[76:79]
	v_mfma_f32_16x16x32_bf16 v[68:71], v[180:183], v[226:229], 0
	v_mfma_f32_16x16x32_bf16 v[68:71], v[184:187], v[230:233], v[68:71]
	s_barrier
	s_add_i32 s12, s51, s25
	v_lshl_add_u64 v[142:143], s[16:17], 0, v[2:3]
	s_mov_b32 m0, s12
	ds_read_b128 v[188:191], v148 offset:16384
	ds_read_b128 v[192:195], v148 offset:17408
	ds_read_b128 v[196:199], v148 offset:18432
	ds_read_b128 v[200:203], v148 offset:19456
	ds_read_b128 v[204:207], v148 offset:20480
	ds_read_b128 v[208:211], v148 offset:21504
	ds_read_b128 v[226:229], v148 offset:22528
	ds_read_b128 v[230:233], v148 offset:23552
	global_load_lds_dwordx4 v[142:143], off
	s_add_i32 m0, s12, 0x2000
	s_add_u32 s12, s16, 0x160000
	v_lshl_add_u64 v[166:167], s[16:17], 0, v[136:137]
	s_addc_u32 s13, s17, 0
	s_add_i32 s51, s52, s25
	global_load_lds_dwordx4 v[166:167], off
	v_lshl_add_u64 v[212:213], s[12:13], 0, v[2:3]
	s_mov_b32 m0, s51
	v_lshl_add_u64 v[220:221], s[18:19], 0, v[134:135]
	global_load_lds_dwordx4 v[212:213], off
	v_lshl_add_u64 v[212:213], s[12:13], 0, v[136:137]
	s_add_i32 m0, s51, 0x2000
	s_nop 0
	global_load_lds_dwordx4 v[212:213], off
	v_lshl_add_u64 v[212:213], s[18:19], 0, v[132:133]
	s_mov_b32 m0, s26
	s_nop 0
	global_load_lds_dwordx4 v[212:213], off
	s_mov_b32 m0, s27
	s_nop 0
	global_load_lds_dwordx4 v[220:221], off
	s_waitcnt vmcnt(8)
	s_waitcnt lgkmcnt(0)
	s_barrier
; #define PG8_STAGE(bufoff, gbase, voff) do { _Pragma("unroll") for (int _i = 0; _i < 2; ++_i) \
;         __builtin_amdgcn_global_load_lds((const unsigned*)((const char*)(gbase) + (voff)[_i]), (PG8_LAS unsigned*)(lds + (bufoff) + ldsw + _i * 8192), 16, 0, 0); } while (0)
; #define PG8_LDA(dst, b, h) do { _Pragma("unroll") for (int m = 0; m < 4; ++m) _Pragma("unroll") for (int k = 0; k < 2; ++k) dst[m][k] = *(const PG8_LAS bf16x8*)(lds + PG8_SA(b, h) + aoffk[k] + m * 2048); } while (0)
; #define PG8_LDB(dst, b, h) do { _Pragma("unroll") for (int n = 0; n < 2; ++n) _Pragma("unroll") for (int k = 0; k < 2; ++k) dst[n][k] = *(const PG8_LAS bf16x8*)(lds + PG8_SB(b, h) + boffk[k] + n * 2048); } while (0)
; #define PG8_MMA(ai, bj, At, Bt) do { __builtin_amdgcn_s_setprio(1); _Pragma("unroll") for (int m = 0; m < 4; ++m) _Pragma("unroll") for (int n = 0; n < 2; ++n) _Pragma("unroll") for (int k = 0; k < 2; ++k) \
;         acc[ai][bj][m][n] = __builtin_amdgcn_mfma_f32_16x16x32_bf16(Bt[n][k], At[m][k], acc[ai][bj][m][n], 0, 0, 0); __builtin_amdgcn_s_setprio(0); } while (0)
; #define PG8_WAIT_V(n) asm volatile("s_waitcnt vmcnt(" #n ")" ::: "memory")
; #define PG8_WAIT_L(n) asm volatile("s_waitcnt lgkmcnt(" #n ")" ::: "memory")
; #define PG8_BAR __builtin_amdgcn_s_barrier()
; #define PG8_SCHED __builtin_amdgcn_sched_barrier(0)
; template <class Epi, class Sched, bool ALIGN_EPI = false, bool SP2 = false>
; __device__ __forceinline__ void gemm_phase(PG8_LAS unsigned char* lds, const Gemm g, const Sched& S, const Epi& E) {
;     ...
;             PG8_WAIT_V(8); PG8_WAIT_L(0); PG8_BAR; PG8_MMA(1, 0, At, B0); PG8_MMA(1, 1, At, B1); PG8_BAR; PG8_SCHED;
;             PG8_LDB(B0, 1, 0); PG8_LDB(B1, 1, 1); PG8_SCHED; PG8_LDA(At, 1, 0); PG8_STAGE(PG8_SA(0, 1), a2 + hstepA, voffA);
;             PG8_WAIT_V(8); PG8_WAIT_L(0); PG8_BAR; PG8_MMA(0, 0, At, B0); PG8_MMA(0, 1, At, B1); PG8_BAR; PG8_SCHED;
	v_mfma_f32_16x16x32_bf16 v[64:67], v[150:153], v[188:191], 0
	v_mfma_f32_16x16x32_bf16 v[64:67], v[154:157], v[192:195], v[64:67]
	v_mfma_f32_16x16x32_bf16 v[56:59], v[150:153], v[196:199], 0
	v_mfma_f32_16x16x32_bf16 v[56:59], v[154:157], v[200:203], v[56:59]
	v_mfma_f32_16x16x32_bf16 v[40:43], v[150:153], v[204:207], 0
	v_mfma_f32_16x16x32_bf16 v[40:43], v[154:157], v[208:211], v[40:43]
	v_mfma_f32_16x16x32_bf16 v[24:27], v[150:153], v[226:229], 0
	v_mfma_f32_16x16x32_bf16 v[24:27], v[154:157], v[230:233], v[24:27]
	v_mfma_f32_16x16x32_bf16 v[60:63], v[158:161], v[188:191], 0
	v_mfma_f32_16x16x32_bf16 v[60:63], v[162:165], v[192:195], v[60:63]
	v_mfma_f32_16x16x32_bf16 v[48:51], v[158:161], v[196:199], 0
	v_mfma_f32_16x16x32_bf16 v[48:51], v[162:165], v[200:203], v[48:51]
	v_mfma_f32_16x16x32_bf16 v[32:35], v[158:161], v[204:207], 0
	v_mfma_f32_16x16x32_bf16 v[32:35], v[162:165], v[208:211], v[32:35]
	v_mfma_f32_16x16x32_bf16 v[16:19], v[158:161], v[226:229], 0
	v_mfma_f32_16x16x32_bf16 v[16:19], v[162:165], v[230:233], v[16:19]
	v_mfma_f32_16x16x32_bf16 v[52:55], v[172:175], v[188:191], 0
	v_mfma_f32_16x16x32_bf16 v[52:55], v[176:179], v[192:195], v[52:55]
	v_mfma_f32_16x16x32_bf16 v[36:39], v[172:175], v[196:199], 0
	v_mfma_f32_16x16x32_bf16 v[36:39], v[176:179], v[200:203], v[36:39]
	v_mfma_f32_16x16x32_bf16 v[20:23], v[172:175], v[204:207], 0
	v_mfma_f32_16x16x32_bf16 v[20:23], v[176:179], v[208:211], v[20:23]
	v_mfma_f32_16x16x32_bf16 v[8:11], v[172:175], v[226:229], 0
	v_mfma_f32_16x16x32_bf16 v[8:11], v[176:179], v[230:233], v[8:11]
	v_mfma_f32_16x16x32_bf16 v[44:47], v[180:183], v[188:191], 0
	v_mfma_f32_16x16x32_bf16 v[44:47], v[184:187], v[192:195], v[44:47]
	v_mfma_f32_16x16x32_bf16 v[28:31], v[180:183], v[196:199], 0
	v_mfma_f32_16x16x32_bf16 v[28:31], v[184:187], v[200:203], v[28:31]
	v_mfma_f32_16x16x32_bf16 v[12:15], v[180:183], v[204:207], 0
	v_mfma_f32_16x16x32_bf16 v[12:15], v[184:187], v[208:211], v[12:15]
	v_mfma_f32_16x16x32_bf16 v[4:7], v[180:183], v[226:229], 0
	v_mfma_f32_16x16x32_bf16 v[4:7], v[184:187], v[230:233], v[4:7]
	s_barrier
	s_add_i32 s51, 0, 0x18000
	v_add_u32_e32 v149, s51, v145
	v_add_u32_e32 v154, s51, v146
	ds_read_b128 v[150:153], v149
	ds_read_b128 v[154:157], v154
	v_add_u32_e32 v149, s55, v145
	v_add_u32_e32 v162, s55, v146
	s_add_i32 s52, 0, 0x1c000
	ds_read_b128 v[158:161], v149
	ds_read_b128 v[162:165], v162
	v_add_u32_e32 v149, s52, v145
	v_add_u32_e32 v168, s52, v146
	ds_read_b128 v[172:175], v149
	ds_read_b128 v[176:179], v168
	v_add_u32_e32 v149, s56, v145
	v_add_u32_e32 v168, s56, v146
	ds_read_b128 v[180:183], v149
	ds_read_b128 v[184:187], v168
	s_add_u32 s12, s18, 0x160000
	s_addc_u32 s13, s19, 0
	s_mov_b32 m0, s28
	v_lshl_add_u64 v[234:235], s[12:13], 0, v[132:133]
	ds_read_b128 v[188:191], v148 offset:32768
	ds_read_b128 v[192:195], v148 offset:33792
	ds_read_b128 v[196:199], v148 offset:34816
	ds_read_b128 v[200:203], v148 offset:35840
	ds_read_b128 v[204:207], v148 offset:36864
	ds_read_b128 v[208:211], v148 offset:37888
	ds_read_b128 v[226:229], v148 offset:38912
	ds_read_b128 v[230:233], v148 offset:39936
	global_load_lds_dwordx4 v[234:235], off
	v_lshl_add_u64 v[234:235], s[12:13], 0, v[134:135]
	s_mov_b32 m0, s29
	s_nop 0
	global_load_lds_dwordx4 v[234:235], off
	s_waitcnt vmcnt(8)
	s_waitcnt lgkmcnt(0)
	s_barrier
	v_mfma_f32_16x16x32_bf16 v[128:131], v[150:153], v[188:191], v[128:131]
	v_mfma_f32_16x16x32_bf16 v[128:131], v[154:157], v[192:195], v[128:131]
	v_mfma_f32_16x16x32_bf16 v[120:123], v[150:153], v[196:199], v[120:123]
	v_mfma_f32_16x16x32_bf16 v[120:123], v[154:157], v[200:203], v[120:123]
	v_mfma_f32_16x16x32_bf16 v[104:107], v[150:153], v[204:207], v[104:107]
	v_mfma_f32_16x16x32_bf16 v[104:107], v[154:157], v[208:211], v[104:107]
	v_mfma_f32_16x16x32_bf16 v[88:91], v[150:153], v[226:229], v[88:91]
	v_mfma_f32_16x16x32_bf16 v[88:91], v[154:157], v[230:233], v[88:91]
	v_mfma_f32_16x16x32_bf16 v[124:127], v[158:161], v[188:191], v[124:127]
	v_mfma_f32_16x16x32_bf16 v[124:127], v[162:165], v[192:195], v[124:127]
	v_mfma_f32_16x16x32_bf16 v[112:115], v[158:161], v[196:199], v[112:115]
	v_mfma_f32_16x16x32_bf16 v[112:115], v[162:165], v[200:203], v[112:115]
	v_mfma_f32_16x16x32_bf16 v[96:99], v[158:161], v[204:207], v[96:99]
	v_mfma_f32_16x16x32_bf16 v[96:99], v[162:165], v[208:211], v[96:99]
	v_mfma_f32_16x16x32_bf16 v[80:83], v[158:161], v[226:229], v[80:83]
	v_mfma_f32_16x16x32_bf16 v[80:83], v[162:165], v[230:233], v[80:83]
	v_mfma_f32_16x16x32_bf16 v[116:119], v[172:175], v[188:191], v[116:119]
	v_mfma_f32_16x16x32_bf16 v[116:119], v[176:179], v[192:195], v[116:119]
	v_mfma_f32_16x16x32_bf16 v[100:103], v[172:175], v[196:199], v[100:103]
	v_mfma_f32_16x16x32_bf16 v[100:103], v[176:179], v[200:203], v[100:103]
	v_mfma_f32_16x16x32_bf16 v[84:87], v[172:175], v[204:207], v[84:87]
	v_mfma_f32_16x16x32_bf16 v[84:87], v[176:179], v[208:211], v[84:87]
	v_mfma_f32_16x16x32_bf16 v[72:75], v[172:175], v[226:229], v[72:75]
	v_mfma_f32_16x16x32_bf16 v[72:75], v[176:179], v[230:233], v[72:75]
	v_mfma_f32_16x16x32_bf16 v[108:111], v[180:183], v[188:191], v[108:111]
	v_mfma_f32_16x16x32_bf16 v[108:111], v[184:187], v[192:195], v[108:111]
	v_mfma_f32_16x16x32_bf16 v[92:95], v[180:183], v[196:199], v[92:95]
	v_mfma_f32_16x16x32_bf16 v[92:95], v[184:187], v[200:203], v[92:95]
	v_mfma_f32_16x16x32_bf16 v[76:79], v[180:183], v[204:207], v[76:79]
	v_mfma_f32_16x16x32_bf16 v[76:79], v[184:187], v[208:211], v[76:79]
	v_mfma_f32_16x16x32_bf16 v[68:71], v[180:183], v[226:229], v[68:71]
	v_mfma_f32_16x16x32_bf16 v[68:71], v[184:187], v[230:233], v[68:71]
	s_barrier
; #define PG8_STAGE(bufoff, gbase, voff) do { _Pragma("unroll") for (int _i = 0; _i < 2; ++_i) \
;         __builtin_amdgcn_global_load_lds((const unsigned*)((const char*)(gbase) + (voff)[_i]), (PG8_LAS unsigned*)(lds + (bufoff) + ldsw + _i * 8192), 16, 0, 0); } while (0)
; #define PG8_LDA(dst, b, h) do { _Pragma("unroll") for (int m = 0; m < 4; ++m) _Pragma("unroll") for (int k = 0; k < 2; ++k) dst[m][k] = *(const PG8_LAS bf16x8*)(lds + PG8_SA(b, h) + aoffk[k] + m * 2048); } while (0)
; #define PG8_LDB(dst, b, h) do { _Pragma("unroll") for (int n = 0; n < 2; ++n) _Pragma("unroll") for (int k = 0; k < 2; ++k) dst[n][k] = *(const PG8_LAS bf16x8*)(lds + PG8_SB(b, h) + boffk[k] + n * 2048); } while (0)
; #define PG8_MMA(ai, bj, At, Bt) do { __builtin_amdgcn_s_setprio(1); _Pragma("unroll") for (int m = 0; m < 4; ++m) _Pragma("unroll") for (int n = 0; n < 2; ++n) _Pragma("unroll") for (int k = 0; k < 2; ++k) \
;         acc[ai][bj][m][n] = __builtin_amdgcn_mfma_f32_16x16x32_bf16(Bt[n][k], At[m][k], acc[ai][bj][m][n], 0, 0, 0); __builtin_amdgcn_s_setprio(0); } while (0)
; #define PG8_WAIT_V(n) asm volatile("s_waitcnt vmcnt(" #n ")" ::: "memory")
; #define PG8_WAIT_L(n) asm volatile("s_waitcnt lgkmcnt(" #n ")" ::: "memory")
; template <class Epi, class Sched, bool ALIGN_EPI = false, bool SP2 = false>
; __device__ __forceinline__ void gemm_phase(PG8_LAS unsigned char* lds, const Gemm g, const Sched& S, const Epi& E) {
;     ...
;         for (int t = 0; t < nt; t += 2) {
;             const bool last = (t == nt - 2);
;             const char* a1 = cA + (size_t)(t + 1) * kstep;
;             const char* a2 = last ? nA : cA + (size_t)(t + 2) * kstep; const char* b2 = last ? nB : cB + (size_t)(t + 2) * kstep;
;             const char* a3 = a2 + kstep; const char* b3 = b2 + kstep;
;             if (last && has_next) S.a_ready(nxt);
;             if constexpr (SP2) {
;             PG8_LDB(B0, 0, 0); PG8_LDB(B1, 0, 1); PG8_SCHED; PG8_LDA(At, 0, 0); PG8_STAGE(PG8_SA(1, 1), a1 + hstepA, voffA);
;             PG8_WAIT_V(8); PG8_WAIT_L(0); PG8_BAR; PG8_MMA(0, 0, At, B0); PG8_MMA(0, 1, At, B1); PG8_BAR; PG8_SCHED;
;     ...
;             PG8_LDA(At, 1, 1); PG8_STAGE(PG8_SB(1, 0), b3, voffB); PG8_STAGE(PG8_SB(1, 1), b3 + hstepB, voffB); PG8_STAGE(PG8_SA(1, 0), a3, voffA);
;             PG8_WAIT_V(8); PG8_WAIT_L(0); PG8_BAR; PG8_MMA(1, 0, At, B0); PG8_MMA(1, 1, At, B1); PG8_BAR; PG8_SCHED;
	s_add_i32 s12, s51, s25
	v_lshl_add_u64 v[142:143], v[142:143], 0, s[58:59]
	s_mov_b32 m0, s12
	ds_read_b128 v[188:191], v148 offset:49152
	ds_read_b128 v[192:195], v148 offset:50176
	ds_read_b128 v[196:199], v148 offset:51200
	ds_read_b128 v[200:203], v148 offset:52224
	ds_read_b128 v[204:207], v148 offset:53248
	ds_read_b128 v[208:211], v148 offset:54272
	ds_read_b128 v[226:229], v148 offset:55296
	ds_read_b128 v[230:233], v148 offset:56320
	global_load_lds_dwordx4 v[142:143], off
	s_add_i32 m0, s12, 0x2000
	s_add_u32 s12, s16, 0x160080
	v_lshl_add_u64 v[142:143], v[166:167], 0, s[58:59]
	s_addc_u32 s13, s17, 0
	s_add_i32 s16, s52, s25
	global_load_lds_dwordx4 v[142:143], off
	v_lshl_add_u64 v[142:143], s[12:13], 0, v[2:3]
	s_mov_b32 m0, s16
	s_nop 0
	global_load_lds_dwordx4 v[142:143], off
	v_lshl_add_u64 v[142:143], s[12:13], 0, v[136:137]
	s_add_i32 m0, s16, 0x2000
	s_nop 0
	global_load_lds_dwordx4 v[142:143], off
	v_lshl_add_u64 v[142:143], v[212:213], 0, s[58:59]
	s_mov_b32 m0, s36
	s_nop 0
	global_load_lds_dwordx4 v[142:143], off
	v_lshl_add_u64 v[142:143], v[220:221], 0, s[58:59]
	s_mov_b32 m0, s37
	s_nop 0
	global_load_lds_dwordx4 v[142:143], off
	s_waitcnt vmcnt(8)
	s_waitcnt lgkmcnt(0)
	s_barrier
	v_mfma_f32_16x16x32_bf16 v[64:67], v[150:153], v[188:191], v[64:67]
	v_mfma_f32_16x16x32_bf16 v[64:67], v[154:157], v[192:195], v[64:67]
	v_mfma_f32_16x16x32_bf16 v[56:59], v[150:153], v[196:199], v[56:59]
	v_mfma_f32_16x16x32_bf16 v[56:59], v[154:157], v[200:203], v[56:59]
	v_mfma_f32_16x16x32_bf16 v[40:43], v[150:153], v[204:207], v[40:43]
	v_mfma_f32_16x16x32_bf16 v[40:43], v[154:157], v[208:211], v[40:43]
	v_mfma_f32_16x16x32_bf16 v[24:27], v[150:153], v[226:229], v[24:27]
	v_mfma_f32_16x16x32_bf16 v[24:27], v[154:157], v[230:233], v[24:27]
	v_mfma_f32_16x16x32_bf16 v[60:63], v[158:161], v[188:191], v[60:63]
	v_mfma_f32_16x16x32_bf16 v[60:63], v[162:165], v[192:195], v[60:63]
	v_mfma_f32_16x16x32_bf16 v[48:51], v[158:161], v[196:199], v[48:51]
	v_mfma_f32_16x16x32_bf16 v[48:51], v[162:165], v[200:203], v[48:51]
	v_mfma_f32_16x16x32_bf16 v[32:35], v[158:161], v[204:207], v[32:35]
	v_mfma_f32_16x16x32_bf16 v[32:35], v[162:165], v[208:211], v[32:35]
	v_mfma_f32_16x16x32_bf16 v[16:19], v[158:161], v[226:229], v[16:19]
	v_mfma_f32_16x16x32_bf16 v[16:19], v[162:165], v[230:233], v[16:19]
	v_mfma_f32_16x16x32_bf16 v[52:55], v[172:175], v[188:191], v[52:55]
	v_mfma_f32_16x16x32_bf16 v[52:55], v[176:179], v[192:195], v[52:55]
	v_mfma_f32_16x16x32_bf16 v[36:39], v[172:175], v[196:199], v[36:39]
	v_mfma_f32_16x16x32_bf16 v[36:39], v[176:179], v[200:203], v[36:39]
	v_mfma_f32_16x16x32_bf16 v[20:23], v[172:175], v[204:207], v[20:23]
	v_mfma_f32_16x16x32_bf16 v[20:23], v[176:179], v[208:211], v[20:23]
	v_mfma_f32_16x16x32_bf16 v[8:11], v[172:175], v[226:229], v[8:11]
	v_mfma_f32_16x16x32_bf16 v[8:11], v[176:179], v[230:233], v[8:11]
	v_mfma_f32_16x16x32_bf16 v[44:47], v[180:183], v[188:191], v[44:47]
	v_mfma_f32_16x16x32_bf16 v[44:47], v[184:187], v[192:195], v[44:47]
	v_mfma_f32_16x16x32_bf16 v[28:31], v[180:183], v[196:199], v[28:31]
	v_mfma_f32_16x16x32_bf16 v[28:31], v[184:187], v[200:203], v[28:31]
	v_mfma_f32_16x16x32_bf16 v[12:15], v[180:183], v[204:207], v[12:15]
	v_mfma_f32_16x16x32_bf16 v[12:15], v[184:187], v[208:211], v[12:15]
	v_mfma_f32_16x16x32_bf16 v[4:7], v[180:183], v[226:229], v[4:7]
	v_mfma_f32_16x16x32_bf16 v[4:7], v[184:187], v[230:233], v[4:7]
	s_barrier
	s_add_u32 s48, s48, 0x100
	s_addc_u32 s49, s49, 0
	s_cmp_ge_i32 s50, s43
	s_mov_b64 s[12:13], s[14:15]
	s_mov_b32 s16, s50
	s_cbranch_scc0 .LBB0_1592
	s_branch .Lgemm_after_5
.LBB0_1592:
	s_add_i32 s50, s16, 2
	s_add_u32 s14, s12, 0x100
	s_addc_u32 s15, s13, 0
	s_add_i32 s51, 0, 0x10000
	s_cmp_eq_u32 s7, s16
	v_add_u32_e32 v142, s51, v145
	s_cselect_b32 s19, s9, s15
	s_cselect_b32 s18, s8, s14
	v_add_u32_e32 v143, s51, v146
	ds_read_b128 v[150:153], v142
	ds_read_b128 v[154:157], v143
	v_add_u32_e32 v142, s53, v145
	s_cselect_b32 s17, s11, s49
	s_cselect_b32 s16, s10, s48
	s_add_i32 s52, 0, 0x14000
	v_add_u32_e32 v143, s53, v146
	ds_read_b128 v[158:161], v142
	ds_read_b128 v[162:165], v143
	v_add_u32_e32 v142, s52, v145
	v_add_u32_e32 v143, s52, v146
	ds_read_b128 v[172:175], v142
	ds_read_b128 v[176:179], v143
	v_add_u32_e32 v142, s54, v145
	v_add_u32_e32 v143, s54, v146
	ds_read_b128 v[180:183], v142
	ds_read_b128 v[184:187], v143
	v_lshl_add_u64 v[142:143], s[12:13], 0, v[138:139]
	s_add_i32 m0, s26, 0xc000
	ds_read_b128 v[188:191], v148
	ds_read_b128 v[192:195], v148 offset:1024
	ds_read_b128 v[196:199], v148 offset:2048
	ds_read_b128 v[200:203], v148 offset:3072
	ds_read_b128 v[204:207], v148 offset:4096
	ds_read_b128 v[208:211], v148 offset:5120
	ds_read_b128 v[226:229], v148 offset:6144
	ds_read_b128 v[230:233], v148 offset:7168
	global_load_lds_dwordx4 v[142:143], off
	v_lshl_add_u64 v[142:143], s[12:13], 0, v[140:141]
	s_add_i32 m0, s26, 0xe000
	s_nop 0
	global_load_lds_dwordx4 v[142:143], off
	s_waitcnt vmcnt(8)
	s_waitcnt lgkmcnt(0)
	s_barrier
; #define PG8_STAGE(bufoff, gbase, voff) do { _Pragma("unroll") for (int _i = 0; _i < 2; ++_i) \
;         __builtin_amdgcn_global_load_lds((const unsigned*)((const char*)(gbase) + (voff)[_i]), (PG8_LAS unsigned*)(lds + (bufoff) + ldsw + _i * 8192), 16, 0, 0); } while (0)
; #define PG8_LDA(dst, b, h) do { _Pragma("unroll") for (int m = 0; m < 4; ++m) _Pragma("unroll") for (int k = 0; k < 2; ++k) dst[m][k] = *(const PG8_LAS bf16x8*)(lds + PG8_SA(b, h) + aoffk[k] + m * 2048); } while (0)
; #define PG8_MMA(ai, bj, At, Bt) do { __builtin_amdgcn_s_setprio(1); _Pragma("unroll") for (int m = 0; m < 4; ++m) _Pragma("unroll") for (int n = 0; n < 2; ++n) _Pragma("unroll") for (int k = 0; k < 2; ++k) \
;         acc[ai][bj][m][n] = __builtin_amdgcn_mfma_f32_16x16x32_bf16(Bt[n][k], At[m][k], acc[ai][bj][m][n], 0, 0, 0); __builtin_amdgcn_s_setprio(0); } while (0)
; #define PG8_WAIT_V(n) asm volatile("s_waitcnt vmcnt(" #n ")" ::: "memory")
; #define PG8_WAIT_L(n) asm volatile("s_waitcnt lgkmcnt(" #n ")" ::: "memory")
; #define PG8_BAR __builtin_amdgcn_s_barrier()
; #define PG8_SCHED __builtin_amdgcn_sched_barrier(0)
; template <class Epi, class Sched, bool ALIGN_EPI = false, bool SP2 = false>
; __device__ __forceinline__ void gemm_phase(PG8_LAS unsigned char* lds, const Gemm g, const Sched& S, const Epi& E) {
;     ...
;             PG8_WAIT_V(8); PG8_WAIT_L(0); PG8_BAR; PG8_MMA(0, 0, At, B0); PG8_MMA(0, 1, At, B1); PG8_BAR; PG8_SCHED;
;             PG8_LDA(At, 0, 1); PG8_STAGE(PG8_SB(0, 0), b2, voffB); PG8_STAGE(PG8_SB(0, 1), b2 + hstepB, voffB); PG8_STAGE(PG8_SA(0, 0), a2, voffA);
;             PG8_WAIT_V(8); PG8_WAIT_L(0); PG8_BAR; PG8_MMA(1, 0, At, B0); PG8_MMA(1, 1, At, B1); PG8_BAR; PG8_SCHED;
	v_mfma_f32_16x16x32_bf16 v[128:131], v[150:153], v[188:191], v[128:131]
	v_mfma_f32_16x16x32_bf16 v[128:131], v[154:157], v[192:195], v[128:131]
	v_mfma_f32_16x16x32_bf16 v[120:123], v[150:153], v[196:199], v[120:123]
	v_mfma_f32_16x16x32_bf16 v[120:123], v[154:157], v[200:203], v[120:123]
	v_mfma_f32_16x16x32_bf16 v[104:107], v[150:153], v[204:207], v[104:107]
	v_mfma_f32_16x16x32_bf16 v[104:107], v[154:157], v[208:211], v[104:107]
	v_mfma_f32_16x16x32_bf16 v[88:91], v[150:153], v[226:229], v[88:91]
	v_mfma_f32_16x16x32_bf16 v[88:91], v[154:157], v[230:233], v[88:91]
	v_mfma_f32_16x16x32_bf16 v[124:127], v[158:161], v[188:191], v[124:127]
	v_mfma_f32_16x16x32_bf16 v[124:127], v[162:165], v[192:195], v[124:127]
	v_mfma_f32_16x16x32_bf16 v[112:115], v[158:161], v[196:199], v[112:115]
	v_mfma_f32_16x16x32_bf16 v[112:115], v[162:165], v[200:203], v[112:115]
	v_mfma_f32_16x16x32_bf16 v[96:99], v[158:161], v[204:207], v[96:99]
	v_mfma_f32_16x16x32_bf16 v[96:99], v[162:165], v[208:211], v[96:99]
	v_mfma_f32_16x16x32_bf16 v[80:83], v[158:161], v[226:229], v[80:83]
	v_mfma_f32_16x16x32_bf16 v[80:83], v[162:165], v[230:233], v[80:83]
	v_mfma_f32_16x16x32_bf16 v[116:119], v[172:175], v[188:191], v[116:119]
	v_mfma_f32_16x16x32_bf16 v[116:119], v[176:179], v[192:195], v[116:119]
	v_mfma_f32_16x16x32_bf16 v[100:103], v[172:175], v[196:199], v[100:103]
	v_mfma_f32_16x16x32_bf16 v[100:103], v[176:179], v[200:203], v[100:103]
	v_mfma_f32_16x16x32_bf16 v[84:87], v[172:175], v[204:207], v[84:87]
	v_mfma_f32_16x16x32_bf16 v[84:87], v[176:179], v[208:211], v[84:87]
	v_mfma_f32_16x16x32_bf16 v[72:75], v[172:175], v[226:229], v[72:75]
	v_mfma_f32_16x16x32_bf16 v[72:75], v[176:179], v[230:233], v[72:75]
	v_mfma_f32_16x16x32_bf16 v[108:111], v[180:183], v[188:191], v[108:111]
	v_mfma_f32_16x16x32_bf16 v[108:111], v[184:187], v[192:195], v[108:111]
	v_mfma_f32_16x16x32_bf16 v[92:95], v[180:183], v[196:199], v[92:95]
	v_mfma_f32_16x16x32_bf16 v[92:95], v[184:187], v[200:203], v[92:95]
	v_mfma_f32_16x16x32_bf16 v[76:79], v[180:183], v[204:207], v[76:79]
	v_mfma_f32_16x16x32_bf16 v[76:79], v[184:187], v[208:211], v[76:79]
	v_mfma_f32_16x16x32_bf16 v[68:71], v[180:183], v[226:229], v[68:71]
	v_mfma_f32_16x16x32_bf16 v[68:71], v[184:187], v[230:233], v[68:71]
	s_barrier
	s_add_i32 s12, s51, s25
	v_lshl_add_u64 v[142:143], s[16:17], 0, v[2:3]
	s_mov_b32 m0, s12
	ds_read_b128 v[188:191], v148 offset:16384
	ds_read_b128 v[192:195], v148 offset:17408
	ds_read_b128 v[196:199], v148 offset:18432
	ds_read_b128 v[200:203], v148 offset:19456
	ds_read_b128 v[204:207], v148 offset:20480
	ds_read_b128 v[208:211], v148 offset:21504
	ds_read_b128 v[226:229], v148 offset:22528
	ds_read_b128 v[230:233], v148 offset:23552
	global_load_lds_dwordx4 v[142:143], off
	s_add_i32 m0, s12, 0x2000
	s_add_u32 s12, s16, 0x160000
	v_lshl_add_u64 v[166:167], s[16:17], 0, v[136:137]
	s_addc_u32 s13, s17, 0
	s_add_i32 s51, s52, s25
	global_load_lds_dwordx4 v[166:167], off
	v_lshl_add_u64 v[212:213], s[12:13], 0, v[2:3]
	s_mov_b32 m0, s51
	v_lshl_add_u64 v[220:221], s[18:19], 0, v[134:135]
	global_load_lds_dwordx4 v[212:213], off
	v_lshl_add_u64 v[212:213], s[12:13], 0, v[136:137]
	s_add_i32 m0, s51, 0x2000
	s_nop 0
	global_load_lds_dwordx4 v[212:213], off
	v_lshl_add_u64 v[212:213], s[18:19], 0, v[132:133]
	s_mov_b32 m0, s26
	s_nop 0
	global_load_lds_dwordx4 v[212:213], off
	s_mov_b32 m0, s27
	s_nop 0
	global_load_lds_dwordx4 v[220:221], off
	s_waitcnt vmcnt(8)
	s_waitcnt lgkmcnt(0)
	s_barrier
	v_mfma_f32_16x16x32_bf16 v[64:67], v[150:153], v[188:191], v[64:67]
	v_mfma_f32_16x16x32_bf16 v[64:67], v[154:157], v[192:195], v[64:67]
	v_mfma_f32_16x16x32_bf16 v[56:59], v[150:153], v[196:199], v[56:59]
	v_mfma_f32_16x16x32_bf16 v[56:59], v[154:157], v[200:203], v[56:59]
	v_mfma_f32_16x16x32_bf16 v[40:43], v[150:153], v[204:207], v[40:43]
	v_mfma_f32_16x16x32_bf16 v[40:43], v[154:157], v[208:211], v[40:43]
	v_mfma_f32_16x16x32_bf16 v[24:27], v[150:153], v[226:229], v[24:27]
	v_mfma_f32_16x16x32_bf16 v[24:27], v[154:157], v[230:233], v[24:27]
	v_mfma_f32_16x16x32_bf16 v[60:63], v[158:161], v[188:191], v[60:63]
	v_mfma_f32_16x16x32_bf16 v[60:63], v[162:165], v[192:195], v[60:63]
	v_mfma_f32_16x16x32_bf16 v[48:51], v[158:161], v[196:199], v[48:51]
	v_mfma_f32_16x16x32_bf16 v[48:51], v[162:165], v[200:203], v[48:51]
	v_mfma_f32_16x16x32_bf16 v[32:35], v[158:161], v[204:207], v[32:35]
	v_mfma_f32_16x16x32_bf16 v[32:35], v[162:165], v[208:211], v[32:35]
	v_mfma_f32_16x16x32_bf16 v[16:19], v[158:161], v[226:229], v[16:19]
	v_mfma_f32_16x16x32_bf16 v[16:19], v[162:165], v[230:233], v[16:19]
	v_mfma_f32_16x16x32_bf16 v[52:55], v[172:175], v[188:191], v[52:55]
	v_mfma_f32_16x16x32_bf16 v[52:55], v[176:179], v[192:195], v[52:55]
	v_mfma_f32_16x16x32_bf16 v[36:39], v[172:175], v[196:199], v[36:39]
	v_mfma_f32_16x16x32_bf16 v[36:39], v[176:179], v[200:203], v[36:39]
	v_mfma_f32_16x16x32_bf16 v[20:23], v[172:175], v[204:207], v[20:23]
	v_mfma_f32_16x16x32_bf16 v[20:23], v[176:179], v[208:211], v[20:23]
	v_mfma_f32_16x16x32_bf16 v[8:11], v[172:175], v[226:229], v[8:11]
	v_mfma_f32_16x16x32_bf16 v[8:11], v[176:179], v[230:233], v[8:11]
	v_mfma_f32_16x16x32_bf16 v[44:47], v[180:183], v[188:191], v[44:47]
	v_mfma_f32_16x16x32_bf16 v[44:47], v[184:187], v[192:195], v[44:47]
	v_mfma_f32_16x16x32_bf16 v[28:31], v[180:183], v[196:199], v[28:31]
	v_mfma_f32_16x16x32_bf16 v[28:31], v[184:187], v[200:203], v[28:31]
	v_mfma_f32_16x16x32_bf16 v[12:15], v[180:183], v[204:207], v[12:15]
	v_mfma_f32_16x16x32_bf16 v[12:15], v[184:187], v[208:211], v[12:15]
	v_mfma_f32_16x16x32_bf16 v[4:7], v[180:183], v[226:229], v[4:7]
	v_mfma_f32_16x16x32_bf16 v[4:7], v[184:187], v[230:233], v[4:7]
	s_barrier
; #define PG8_STAGE(bufoff, gbase, voff) do { _Pragma("unroll") for (int _i = 0; _i < 2; ++_i) \
;         __builtin_amdgcn_global_load_lds((const unsigned*)((const char*)(gbase) + (voff)[_i]), (PG8_LAS unsigned*)(lds + (bufoff) + ldsw + _i * 8192), 16, 0, 0); } while (0)
; #define PG8_LDA(dst, b, h) do { _Pragma("unroll") for (int m = 0; m < 4; ++m) _Pragma("unroll") for (int k = 0; k < 2; ++k) dst[m][k] = *(const PG8_LAS bf16x8*)(lds + PG8_SA(b, h) + aoffk[k] + m * 2048); } while (0)
; #define PG8_LDB(dst, b, h) do { _Pragma("unroll") for (int n = 0; n < 2; ++n) _Pragma("unroll") for (int k = 0; k < 2; ++k) dst[n][k] = *(const PG8_LAS bf16x8*)(lds + PG8_SB(b, h) + boffk[k] + n * 2048); } while (0)
; #define PG8_MMA(ai, bj, At, Bt) do { __builtin_amdgcn_s_setprio(1); _Pragma("unroll") for (int m = 0; m < 4; ++m) _Pragma("unroll") for (int n = 0; n < 2; ++n) _Pragma("unroll") for (int k = 0; k < 2; ++k) \
;         acc[ai][bj][m][n] = __builtin_amdgcn_mfma_f32_16x16x32_bf16(Bt[n][k], At[m][k], acc[ai][bj][m][n], 0, 0, 0); __builtin_amdgcn_s_setprio(0); } while (0)
; #define PG8_WAIT_V(n) asm volatile("s_waitcnt vmcnt(" #n ")" ::: "memory")
; #define PG8_WAIT_L(n) asm volatile("s_waitcnt lgkmcnt(" #n ")" ::: "memory")
; #define PG8_BAR __builtin_amdgcn_s_barrier()
; #define PG8_SCHED __builtin_amdgcn_sched_barrier(0)
; template <class Epi, class Sched, bool ALIGN_EPI = false, bool SP2 = false>
; __device__ __forceinline__ void gemm_phase(PG8_LAS unsigned char* lds, const Gemm g, const Sched& S, const Epi& E) {
;     ...
;             PG8_LDB(B0, 1, 0); PG8_LDB(B1, 1, 1); PG8_SCHED; PG8_LDA(At, 1, 0); PG8_STAGE(PG8_SA(0, 1), a2 + hstepA, voffA);
;             PG8_WAIT_V(8); PG8_WAIT_L(0); PG8_BAR; PG8_MMA(0, 0, At, B0); PG8_MMA(0, 1, At, B1); PG8_BAR; PG8_SCHED;
	s_add_i32 s51, 0, 0x18000
	v_add_u32_e32 v149, s51, v145
	v_add_u32_e32 v154, s51, v146
	ds_read_b128 v[150:153], v149
	ds_read_b128 v[154:157], v154
	v_add_u32_e32 v149, s55, v145
	v_add_u32_e32 v162, s55, v146
	s_add_i32 s52, 0, 0x1c000
	ds_read_b128 v[158:161], v149
	ds_read_b128 v[162:165], v162
	v_add_u32_e32 v149, s52, v145
	v_add_u32_e32 v168, s52, v146
	ds_read_b128 v[172:175], v149
	ds_read_b128 v[176:179], v168
	v_add_u32_e32 v149, s56, v145
	v_add_u32_e32 v168, s56, v146
	ds_read_b128 v[180:183], v149
	ds_read_b128 v[184:187], v168
	s_add_u32 s12, s18, 0x160000
	s_addc_u32 s13, s19, 0
	s_mov_b32 m0, s28
	v_lshl_add_u64 v[234:235], s[12:13], 0, v[132:133]
	ds_read_b128 v[188:191], v148 offset:32768
	ds_read_b128 v[192:195], v148 offset:33792
	ds_read_b128 v[196:199], v148 offset:34816
	ds_read_b128 v[200:203], v148 offset:35840
	ds_read_b128 v[204:207], v148 offset:36864
	ds_read_b128 v[208:211], v148 offset:37888
	ds_read_b128 v[226:229], v148 offset:38912
	ds_read_b128 v[230:233], v148 offset:39936
	global_load_lds_dwordx4 v[234:235], off
	v_lshl_add_u64 v[234:235], s[12:13], 0, v[134:135]
	s_mov_b32 m0, s29
	s_nop 0
	global_load_lds_dwordx4 v[234:235], off
	s_waitcnt vmcnt(8)
	s_waitcnt lgkmcnt(0)
	s_barrier
	v_mfma_f32_16x16x32_bf16 v[128:131], v[150:153], v[188:191], v[128:131]
	v_mfma_f32_16x16x32_bf16 v[128:131], v[154:157], v[192:195], v[128:131]
	v_mfma_f32_16x16x32_bf16 v[120:123], v[150:153], v[196:199], v[120:123]
	v_mfma_f32_16x16x32_bf16 v[120:123], v[154:157], v[200:203], v[120:123]
	v_mfma_f32_16x16x32_bf16 v[104:107], v[150:153], v[204:207], v[104:107]
	v_mfma_f32_16x16x32_bf16 v[104:107], v[154:157], v[208:211], v[104:107]
	v_mfma_f32_16x16x32_bf16 v[88:91], v[150:153], v[226:229], v[88:91]
	v_mfma_f32_16x16x32_bf16 v[88:91], v[154:157], v[230:233], v[88:91]
	v_mfma_f32_16x16x32_bf16 v[124:127], v[158:161], v[188:191], v[124:127]
	v_mfma_f32_16x16x32_bf16 v[124:127], v[162:165], v[192:195], v[124:127]
	v_mfma_f32_16x16x32_bf16 v[112:115], v[158:161], v[196:199], v[112:115]
	v_mfma_f32_16x16x32_bf16 v[112:115], v[162:165], v[200:203], v[112:115]
	v_mfma_f32_16x16x32_bf16 v[96:99], v[158:161], v[204:207], v[96:99]
	v_mfma_f32_16x16x32_bf16 v[96:99], v[162:165], v[208:211], v[96:99]
	v_mfma_f32_16x16x32_bf16 v[80:83], v[158:161], v[226:229], v[80:83]
	v_mfma_f32_16x16x32_bf16 v[80:83], v[162:165], v[230:233], v[80:83]
	v_mfma_f32_16x16x32_bf16 v[116:119], v[172:175], v[188:191], v[116:119]
	v_mfma_f32_16x16x32_bf16 v[116:119], v[176:179], v[192:195], v[116:119]
	v_mfma_f32_16x16x32_bf16 v[100:103], v[172:175], v[196:199], v[100:103]
	v_mfma_f32_16x16x32_bf16 v[100:103], v[176:179], v[200:203], v[100:103]
	v_mfma_f32_16x16x32_bf16 v[84:87], v[172:175], v[204:207], v[84:87]
	v_mfma_f32_16x16x32_bf16 v[84:87], v[176:179], v[208:211], v[84:87]
	v_mfma_f32_16x16x32_bf16 v[72:75], v[172:175], v[226:229], v[72:75]
	v_mfma_f32_16x16x32_bf16 v[72:75], v[176:179], v[230:233], v[72:75]
	v_mfma_f32_16x16x32_bf16 v[108:111], v[180:183], v[188:191], v[108:111]
	v_mfma_f32_16x16x32_bf16 v[108:111], v[184:187], v[192:195], v[108:111]
	v_mfma_f32_16x16x32_bf16 v[92:95], v[180:183], v[196:199], v[92:95]
	v_mfma_f32_16x16x32_bf16 v[92:95], v[184:187], v[200:203], v[92:95]
	v_mfma_f32_16x16x32_bf16 v[76:79], v[180:183], v[204:207], v[76:79]
	v_mfma_f32_16x16x32_bf16 v[76:79], v[184:187], v[208:211], v[76:79]
	v_mfma_f32_16x16x32_bf16 v[68:71], v[180:183], v[226:229], v[68:71]
	v_mfma_f32_16x16x32_bf16 v[68:71], v[184:187], v[230:233], v[68:71]
	s_barrier
; #define PG8_STAGE(bufoff, gbase, voff) do { _Pragma("unroll") for (int _i = 0; _i < 2; ++_i) \
;         __builtin_amdgcn_global_load_lds((const unsigned*)((const char*)(gbase) + (voff)[_i]), (PG8_LAS unsigned*)(lds + (bufoff) + ldsw + _i * 8192), 16, 0, 0); } while (0)
; #define PG8_LDA(dst, b, h) do { _Pragma("unroll") for (int m = 0; m < 4; ++m) _Pragma("unroll") for (int k = 0; k < 2; ++k) dst[m][k] = *(const PG8_LAS bf16x8*)(lds + PG8_SA(b, h) + aoffk[k] + m * 2048); } while (0)
; #define PG8_MMA(ai, bj, At, Bt) do { __builtin_amdgcn_s_setprio(1); _Pragma("unroll") for (int m = 0; m < 4; ++m) _Pragma("unroll") for (int n = 0; n < 2; ++n) _Pragma("unroll") for (int k = 0; k < 2; ++k) \
;         acc[ai][bj][m][n] = __builtin_amdgcn_mfma_f32_16x16x32_bf16(Bt[n][k], At[m][k], acc[ai][bj][m][n], 0, 0, 0); __builtin_amdgcn_s_setprio(0); } while (0)
; #define PG8_WAIT_V(n) asm volatile("s_waitcnt vmcnt(" #n ")" ::: "memory")
; #define PG8_WAIT_L(n) asm volatile("s_waitcnt lgkmcnt(" #n ")" ::: "memory")
; #define PG8_BAR __builtin_amdgcn_s_barrier()
; #define PG8_SCHED __builtin_amdgcn_sched_barrier(0)
; template <class Epi, class Sched, bool ALIGN_EPI = false, bool SP2 = false>
; __device__ __forceinline__ void gemm_phase(PG8_LAS unsigned char* lds, const Gemm g, const Sched& S, const Epi& E) {
;     ...
;             PG8_LDA(At, 1, 1); PG8_STAGE(PG8_SB(1, 0), b3, voffB); PG8_STAGE(PG8_SB(1, 1), b3 + hstepB, voffB); PG8_STAGE(PG8_SA(1, 0), a3, voffA);
;             PG8_WAIT_V(8); PG8_WAIT_L(0); PG8_BAR; PG8_MMA(1, 0, At, B0); PG8_MMA(1, 1, At, B1); PG8_BAR; PG8_SCHED;
	s_add_i32 s12, s51, s25
	v_lshl_add_u64 v[142:143], v[142:143], 0, s[58:59]
	s_mov_b32 m0, s12
	ds_read_b128 v[188:191], v148 offset:49152
	ds_read_b128 v[192:195], v148 offset:50176
	ds_read_b128 v[196:199], v148 offset:51200
	ds_read_b128 v[200:203], v148 offset:52224
	ds_read_b128 v[204:207], v148 offset:53248
	ds_read_b128 v[208:211], v148 offset:54272
	ds_read_b128 v[226:229], v148 offset:55296
	ds_read_b128 v[230:233], v148 offset:56320
	global_load_lds_dwordx4 v[142:143], off
	s_add_i32 m0, s12, 0x2000
	s_add_u32 s12, s16, 0x160080
	v_lshl_add_u64 v[142:143], v[166:167], 0, s[58:59]
	s_addc_u32 s13, s17, 0
	s_add_i32 s16, s52, s25
	global_load_lds_dwordx4 v[142:143], off
	v_lshl_add_u64 v[142:143], s[12:13], 0, v[2:3]
	s_mov_b32 m0, s16
	s_nop 0
	global_load_lds_dwordx4 v[142:143], off
	v_lshl_add_u64 v[142:143], s[12:13], 0, v[136:137]
	s_add_i32 m0, s16, 0x2000
	s_nop 0
	global_load_lds_dwordx4 v[142:143], off
	v_lshl_add_u64 v[142:143], v[212:213], 0, s[58:59]
	s_mov_b32 m0, s36
	s_nop 0
	global_load_lds_dwordx4 v[142:143], off
	v_lshl_add_u64 v[142:143], v[220:221], 0, s[58:59]
	s_mov_b32 m0, s37
	s_nop 0
	global_load_lds_dwordx4 v[142:143], off
	s_waitcnt vmcnt(8)
	s_waitcnt lgkmcnt(0)
	s_barrier
	v_mfma_f32_16x16x32_bf16 v[64:67], v[150:153], v[188:191], v[64:67]
	v_mfma_f32_16x16x32_bf16 v[64:67], v[154:157], v[192:195], v[64:67]
	v_mfma_f32_16x16x32_bf16 v[56:59], v[150:153], v[196:199], v[56:59]
	v_mfma_f32_16x16x32_bf16 v[56:59], v[154:157], v[200:203], v[56:59]
	v_mfma_f32_16x16x32_bf16 v[40:43], v[150:153], v[204:207], v[40:43]
	v_mfma_f32_16x16x32_bf16 v[40:43], v[154:157], v[208:211], v[40:43]
	v_mfma_f32_16x16x32_bf16 v[24:27], v[150:153], v[226:229], v[24:27]
	v_mfma_f32_16x16x32_bf16 v[24:27], v[154:157], v[230:233], v[24:27]
	v_mfma_f32_16x16x32_bf16 v[60:63], v[158:161], v[188:191], v[60:63]
	v_mfma_f32_16x16x32_bf16 v[60:63], v[162:165], v[192:195], v[60:63]
	v_mfma_f32_16x16x32_bf16 v[48:51], v[158:161], v[196:199], v[48:51]
	v_mfma_f32_16x16x32_bf16 v[48:51], v[162:165], v[200:203], v[48:51]
	v_mfma_f32_16x16x32_bf16 v[32:35], v[158:161], v[204:207], v[32:35]
	v_mfma_f32_16x16x32_bf16 v[32:35], v[162:165], v[208:211], v[32:35]
	v_mfma_f32_16x16x32_bf16 v[16:19], v[158:161], v[226:229], v[16:19]
	v_mfma_f32_16x16x32_bf16 v[16:19], v[162:165], v[230:233], v[16:19]
	v_mfma_f32_16x16x32_bf16 v[52:55], v[172:175], v[188:191], v[52:55]
	v_mfma_f32_16x16x32_bf16 v[52:55], v[176:179], v[192:195], v[52:55]
	v_mfma_f32_16x16x32_bf16 v[36:39], v[172:175], v[196:199], v[36:39]
	v_mfma_f32_16x16x32_bf16 v[36:39], v[176:179], v[200:203], v[36:39]
	v_mfma_f32_16x16x32_bf16 v[20:23], v[172:175], v[204:207], v[20:23]
	v_mfma_f32_16x16x32_bf16 v[20:23], v[176:179], v[208:211], v[20:23]
	v_mfma_f32_16x16x32_bf16 v[8:11], v[172:175], v[226:229], v[8:11]
	v_mfma_f32_16x16x32_bf16 v[8:11], v[176:179], v[230:233], v[8:11]
	v_mfma_f32_16x16x32_bf16 v[44:47], v[180:183], v[188:191], v[44:47]
	v_mfma_f32_16x16x32_bf16 v[44:47], v[184:187], v[192:195], v[44:47]
	v_mfma_f32_16x16x32_bf16 v[28:31], v[180:183], v[196:199], v[28:31]
	v_mfma_f32_16x16x32_bf16 v[28:31], v[184:187], v[200:203], v[28:31]
	v_mfma_f32_16x16x32_bf16 v[12:15], v[180:183], v[204:207], v[12:15]
	v_mfma_f32_16x16x32_bf16 v[12:15], v[184:187], v[208:211], v[12:15]
	v_mfma_f32_16x16x32_bf16 v[4:7], v[180:183], v[226:229], v[4:7]
	v_mfma_f32_16x16x32_bf16 v[4:7], v[184:187], v[230:233], v[4:7]
	s_barrier
	s_add_u32 s48, s48, 0x100
	s_addc_u32 s49, s49, 0
	s_cmp_ge_i32 s50, s43
	s_mov_b64 s[12:13], s[14:15]
	s_mov_b32 s16, s50
	s_cbranch_scc0 .LBB0_1592
